# GEMM load phases: the vmcnt and lgkmcnt waits before the MFMA-block barrier merged into one s_waitcnt
# speedup vs baseline: 1.0124x; 1.0063x over previous
; #define PG8_WAIT_V(n) asm volatile("s_waitcnt vmcnt(" #n ")" ::: "memory")
; #define PG8_BAR __builtin_amdgcn_s_barrier()
; template <class Epi, class Sched, bool ALIGN_EPI = false, bool SP2 = false>
; __device__ __forceinline__ void gemm_phase(PG8_LAS unsigned char* lds, const Gemm g, const Sched& S, const Epi& E) {
;     ...
;     const int tid = tid_, wid = __builtin_amdgcn_readfirstlane(tid >> 6), lane = tid & 63, wr = wid >> 2, wc = wid & 3, fr = lane & 15, fq = lane >> 4;
;     const int K = g.K, nt = K / BK;
;     unsigned voffA[2], voffB[2];
; #pragma unroll
;     for (int i = 0; i < 2; ++i) { int R, C; stage_rc(tid * 16 + i * 8192, R, C); const int Rb = Epi::PERM ? ((R & ~31) + perm32(R & 31)) : R;
;         voffA[i] = (unsigned)(R * K + C) * 2u; voffB[i] = (unsigned)(Rb * K + C) * 2u; }
;     const size_t kstep = (size_t)(BK * 2);
;     const size_t hstep = (size_t)HALF * K * 2;
;     const size_t tstep = 2 * hstep;
;     const unsigned ldsw = (unsigned)wid * 1024u;
;     const int aoff = lds_byte(wr * 64 + fr, fq * 8), boff = lds_byte(wc * 32 + fr, fq * 8);
;     ...
;     Unit cur, nxt; int ui = 0;
;     if (!S.next(0, cur)) return;
;     f32x4 acc[2][2][4][2];
; #pragma unroll
;     for (int a = 0; a < 2; ++a)
; #pragma unroll
;         for (int b = 0; b < 2; ++b)
; #pragma unroll
;             for (int m = 0; m < 4; ++m)
; #pragma unroll
;                 for (int n = 0; n < 2; ++n) acc[a][b][m][n] = (f32x4){0.f, 0.f, 0.f, 0.f};
;     bf16x8 At[4][2], B0[2][2], B1[2][2];
;     const char* cA = (const char*)g.A + (size_t)cur.pm * tstep; const char* cB = (const char*)g.Bt + (size_t)cur.pn * tstep;
;     S.a_ready(cur);
;     if constexpr (SP2) {
;         PG8_STAGE(PG8_SB(0, 0), cB, voffB); PG8_STAGE(PG8_SB(0, 1), cB + hstep, voffB); PG8_STAGE(PG8_SA(0, 0), cA, voffA); PG8_STAGE(PG8_SA(0, 1), cA + hstep, voffA);
;         if (wr == 1) PG8_BAR;
;         PG8_WAIT_V(2); PG8_BAR;
;         PG8_STAGE(PG8_SB(1, 0), cB + kstep, voffB); PG8_STAGE(PG8_SA(1, 0), cA + kstep, voffA); PG8_STAGE(PG8_SB(1, 1), cB + hstep + kstep, voffB);
;         PG8_WAIT_V(6); PG8_BAR;
;     } else {
;         PG8_STAGE(PG8_SB(0, 0), cB, voffB); PG8_STAGE(PG8_SA(0, 0), cA, voffA); PG8_STAGE(PG8_SB(0, 1), cB + hstep, voffB); PG8_STAGE(PG8_SA(0, 1), cA + hstep, voffA);
;         if (wr == 1) PG8_BAR;
.LBB0_162:
	s_or_b64 exec, exec, s[14:15]
	s_nop 0
	s_nop 0
	s_nop 0
	s_nop 0
	v_writelane_b32 v254, s34, 49
	s_ashr_i32 s3, s46, 31
	s_ashr_i32 s33, s2, 31
	s_mov_b64 s[24:25], s[0:1]
	s_mov_b64 s[26:27], s[0:1]
	s_mov_b64 s[14:15], s[0:1]
	s_mov_b64 s[16:17], s[0:1]
	s_mov_b64 s[18:19], s[0:1]
	s_mov_b64 s[20:21], s[0:1]
	s_mov_b64 s[22:23], s[0:1]
	v_mov_b32_e32 v14, v216
	v_writelane_b32 v254, s35, 50
	s_waitcnt lgkmcnt(0)
	s_barrier
	s_cmpk_gt_i32 s2, 0x11ff
	v_writelane_b32 v254, s60, 51
	v_readfirstlane_b32 s30, v14
	s_nop 0
	v_writelane_b32 v254, s61, 52
	s_cbranch_scc1 .LBB0_186
	v_lshlrev_b32_e32 v0, 4, v14
	v_add_u32_e32 v1, 0x2000, v0
	v_ashrrev_i32_e32 v2, 31, v1
	v_lshrrev_b32_e32 v2, 22, v2
	v_add_u32_e32 v2, v1, v2
	v_ashrrev_i32_e32 v8, 10, v2
	v_mul_i32_i24_e32 v2, 0x400, v8
	v_sub_u32_e32 v1, v1, v2
	v_lshrrev_b32_e32 v2, 4, v1
	v_bitop3_b32 v1, v2, v1, 32 bitop3:0x6c
	v_ashrrev_i32_e32 v2, 31, v1
	s_load_dwordx2 s[24:25], s[24:25], 0xc8
	s_nop 0
	s_load_dwordx2 s[26:27], s[26:27], 0xc8
	v_lshrrev_b32_e32 v2, 26, v2
	v_add_u32_e32 v2, v1, v2
	v_lshlrev_b32_e32 v3, 3, v8
	v_ashrrev_i32_e32 v9, 6, v2
	v_and_b32_e32 v3, -16, v3
	v_add_u32_e32 v3, v9, v3
	s_waitcnt lgkmcnt(0)
	s_add_u32 s13, s24, 0x7800000
	v_and_b32_e32 v4, 3, v9
	s_mov_b32 s24, 0xfffe0
	v_lshrrev_b32_e32 v5, 2, v3
	v_lshlrev_b32_e32 v6, 1, v3
	v_and_b32_e32 v2, 0xc0, v2
	v_and_or_b32 v4, v3, s24, v4
	v_and_b32_e32 v5, 4, v5
	v_and_b32_e32 v6, 24, v6
	v_sub_u32_e32 v1, v1, v2
	v_mov_b32_e32 v2, 1
	v_or3_b32 v4, v4, v5, v6
	v_lshlrev_b32_e32 v5, 5, v8
	v_ashrrev_i16_sdwa v1, v2, sext(v1) dst_sel:DWORD dst_unused:UNUSED_PAD src0_sel:DWORD src1_sel:BYTE_0
	v_and_b32_e32 v5, 32, v5
	v_bfe_i32 v10, v1, 0, 16
	v_add_lshl_u32 v1, v5, v10, 1
	v_lshl_add_u32 v144, v4, 12, v1
	v_lshl_add_u32 v146, v3, 12, v1
	v_bfe_i32 v1, v14, 27, 1
	v_lshrrev_b32_e32 v1, 22, v1
	v_add_u32_e32 v1, v0, v1
	v_and_b32_e32 v1, 0xfffffc00, v1
	v_sub_u32_e32 v0, v0, v1
	v_lshrrev_b32_e32 v1, 4, v0
	v_ashrrev_i32_e32 v3, 31, v14
	v_bitop3_b32 v0, v1, v0, 32 bitop3:0x6c
	v_lshrrev_b32_e32 v3, 26, v3
	v_ashrrev_i32_e32 v1, 31, v0
	v_add_u32_e32 v3, v14, v3
	v_lshrrev_b32_e32 v1, 26, v1
	v_ashrrev_i32_e32 v12, 6, v3
	v_add_u32_e32 v1, v0, v1
	v_lshlrev_b32_e32 v3, 3, v12
	s_addc_u32 s47, s25, 0
	v_ashrrev_i32_e32 v11, 6, v1
	v_and_b32_e32 v3, -16, v3
	s_add_u32 s48, s26, 0x200000
	v_add_u32_e32 v3, v11, v3
	v_and_b32_e32 v4, 3, v11
	s_addc_u32 s49, s27, 0
	v_and_or_b32 v4, v3, s24, v4
	s_lshr_b32 s24, s33, 29
	s_add_i32 s24, s2, s24
	s_ashr_i32 s25, s30, 6
	s_ashr_i32 s26, s24, 3
	s_and_b32 s24, s24, -8
	s_ashr_i32 s31, s30, 8
	s_lshl_b32 s50, s25, 10
	s_sub_i32 s24, s2, s24
	s_cmp_lt_i32 s24, 0
	s_movk_i32 s51, 0x241
	s_cselect_b32 s27, s51, 0x240
	s_mul_i32 s24, s24, s27
	s_add_i32 s24, s24, s26
	s_mul_hi_i32 s26, s24, 0x38e38e39
	s_lshr_b32 s27, s26, 31
	s_ashr_i32 s26, s26, 5
	s_add_i32 s26, s26, s27
	s_lshl_b32 s27, s26, 2
	s_mulk_i32 s26, 0x90
	s_sub_i32 s26, s24, s26
	s_sext_i32_i16 s24, s26
	s_bfe_u32 s24, s24, 0x2001d
	s_add_i32 s28, s26, s24
	s_sext_i32_i16 s24, s28
	s_and_b32 s28, s28, 0xfffc
	s_sub_i32 s26, s26, s28
	s_sext_i32_i16 s26, s26
	v_lshrrev_b32_e32 v5, 2, v3
	v_lshlrev_b32_e32 v6, 1, v3
	v_and_b32_e32 v1, 0xc0, v1
	s_lshr_b32 s24, s24, 2
	s_add_i32 s36, s27, s26
	v_and_b32_e32 v5, 4, v5
	v_and_b32_e32 v6, 24, v6
	v_sub_u32_e32 v0, v0, v1
	s_ashr_i32 s37, s36, 31
	s_bfe_i64 s[28:29], s[24:25], 0x100000
	v_or3_b32 v4, v4, v5, v6
	v_lshlrev_b32_e32 v5, 5, v12
	v_ashrrev_i16_sdwa v0, v2, sext(v0) dst_sel:DWORD dst_unused:UNUSED_PAD src0_sel:DWORD src1_sel:BYTE_0
	s_lshl_b64 s[26:27], s[36:37], 20
	s_lshl_b64 s[28:29], s[28:29], 20
	v_and_b32_e32 v5, 32, v5
	v_bfe_i32 v13, v0, 0, 16
	s_add_u32 s42, s48, s28
	v_add_lshl_u32 v0, v5, v13, 1
	s_addc_u32 s43, s49, s29
	s_add_i32 s52, s50, 0
	v_lshl_add_u32 v148, v4, 12, v0
	s_add_i32 m0, s52, 0x10000
	v_lshl_add_u32 v150, v3, 12, v0
	global_load_lds_dwordx4 v148, s[42:43]
	s_add_i32 m0, s52, 0x12000
	s_add_u32 s28, s42, 0x80000
	global_load_lds_dwordx4 v144, s[42:43]
	s_addc_u32 s29, s43, 0
	s_add_i32 m0, s52, 0x14000
	v_mov_b32_e32 v153, 0
	global_load_lds_dwordx4 v148, s[28:29]
	s_add_i32 m0, s52, 0x16000
	s_add_u32 s40, s13, s26
	s_addc_u32 s41, s47, s27
	s_add_i32 s53, s52, 0x2000
	global_load_lds_dwordx4 v144, s[28:29]
	s_mov_b32 m0, s52
	s_add_u32 s26, s40, 0x80000
	global_load_lds_dwordx4 v150, s[40:41]
	s_mov_b32 m0, s53
	s_addc_u32 s27, s41, 0
	s_add_i32 s54, s52, 0x4000
	global_load_lds_dwordx4 v146, s[40:41]
	s_mov_b32 m0, s54
	s_add_i32 s55, s52, 0x6000
	global_load_lds_dwordx4 v150, s[26:27]
	s_mov_b32 m0, s55
	v_mov_b32_e32 v149, v153
	global_load_lds_dwordx4 v146, s[26:27]
	s_load_dwordx2 s[28:29], s[14:15], 0xc8
	s_nop 0
	s_load_dwordx2 s[14:15], s[16:17], 0xc8
	s_load_dwordx2 s[26:27], s[18:19], 0xc8
	s_nop 0
	s_load_dwordx2 s[20:21], s[20:21], 0xc8
	s_nop 0
	s_load_dwordx2 s[16:17], s[22:23], 0x98
	v_mov_b32_e32 v145, v153
	v_mov_b32_e32 v151, v153
	v_mov_b32_e32 v147, v153
	s_cmp_eq_u32 s31, 1
	v_lshl_add_u64 v[6:7], s[42:43], 0, v[148:149]
	v_lshl_add_u64 v[2:3], s[42:43], 0, v[144:145]
	v_lshl_add_u64 v[0:1], s[40:41], 0, v[150:151]
	s_cselect_b64 s[18:19], -1, 0
	s_cmp_lg_u32 s31, 1
	v_lshl_add_u64 v[4:5], s[40:41], 0, v[146:147]
	s_cbranch_scc1 .LBB0_165
	s_barrier

; #define PG8_STAGE(bufoff, gbase, voff) do { _Pragma("unroll") for (int _i = 0; _i < 2; ++_i) \
;         __builtin_amdgcn_global_load_lds((const unsigned*)((const char*)(gbase) + (voff)[_i]), (PG8_LAS unsigned*)(lds + (bufoff) + ldsw + _i * 8192), 16, 0, 0); } while (0)
; #define PG8_LDA(dst, b, h) do { _Pragma("unroll") for (int m = 0; m < 4; ++m) _Pragma("unroll") for (int k = 0; k < 2; ++k) dst[m][k] = *(const PG8_LAS bf16x8*)(lds + PG8_SA(b, h) + aoff + m * 2048 + k * 1024); } while (0)
; #define PG8_LDB(dst, b, h) do { _Pragma("unroll") for (int n = 0; n < 2; ++n) _Pragma("unroll") for (int k = 0; k < 2; ++k) dst[n][k] = *(const PG8_LAS bf16x8*)(lds + PG8_SB(b, h) + boff + n * 2048 + k * 1024); } while (0)
; #define PG8_WAIT_V(n) asm volatile("s_waitcnt vmcnt(" #n ")" ::: "memory")
; #define PG8_WAIT_L(n) asm volatile("s_waitcnt lgkmcnt(" #n ")" ::: "memory")
; #define PG8_BAR __builtin_amdgcn_s_barrier()
; #define PG8_SCHED __builtin_amdgcn_sched_barrier(0)
; template <class Epi, class Sched, bool ALIGN_EPI = false, bool SP2 = false>
; __device__ __forceinline__ void gemm_phase(PG8_LAS unsigned char* lds, const Gemm g, const Sched& S, const Epi& E) {
;     ...
;         const bool has_next = S.next(ui + 1, nxt);
;         const char* nA = has_next ? (const char*)g.A + (size_t)nxt.pm * tstep : cA; const char* nB = has_next ? (const char*)g.Bt + (size_t)nxt.pn * tstep : cB;
;         for (int t = 0; t < nt; t += 2) {
;             const bool last = (t == nt - 2);
;             const char* a1 = cA + (size_t)(t + 1) * kstep;
;             const char* a2 = last ? nA : cA + (size_t)(t + 2) * kstep; const char* b2 = last ? nB : cB + (size_t)(t + 2) * kstep;
;             const char* a3 = a2 + kstep; const char* b3 = b2 + kstep;
;             if (last && has_next) S.a_ready(nxt);
;             if constexpr (SP2) {
;             PG8_LDB(B0, 0, 0); PG8_LDB(B1, 0, 1); PG8_SCHED; PG8_LDA(At, 0, 0); PG8_STAGE(PG8_SA(1, 1), a1 + hstep, voffA);
;             PG8_WAIT_V(8); PG8_WAIT_L(0); PG8_BAR; PG8_MMA(0, 0, At, B0); PG8_MMA(0, 1, At, B1); PG8_BAR; PG8_SCHED;
;             PG8_LDA(At, 0, 1); PG8_STAGE(PG8_SB(0, 0), b2, voffB); PG8_STAGE(PG8_SB(0, 1), b2 + hstep, voffB); PG8_STAGE(PG8_SA(0, 0), a2, voffA);
;             PG8_WAIT_V(8); PG8_WAIT_L(0); PG8_BAR; PG8_MMA(1, 0, At, B0); PG8_MMA(1, 1, At, B1); PG8_BAR; PG8_SCHED;
.LBB0_170:
	s_ashr_i32 s29, s28, 31
	s_lshl_b64 s[30:31], s[28:29], 20
	s_add_u32 s30, s13, s30
	s_addc_u32 s31, s47, s31
	s_and_b64 s[34:35], s[38:39], exec
	s_cselect_b32 s29, s31, s41
	s_cselect_b32 s37, s30, s40
	s_ashr_i32 s27, s26, 31
	s_lshl_b64 s[34:35], s[26:27], 20
	s_add_u32 s34, s48, s34
	s_addc_u32 s35, s49, s35
	s_and_b64 s[44:45], s[38:39], exec
	s_cselect_b32 s27, s35, s43
	s_cselect_b32 s65, s34, s42
	s_add_u32 s40, s40, 0x80080
	s_addc_u32 s41, s41, 0
	s_add_u32 s67, s42, 0x100
	s_addc_u32 s68, s43, 0
	s_mov_b32 s69, -2
	ds_read_b128 v[128:131], v175
	ds_read_b128 v[132:135], v175 offset:1024
	ds_read_b128 v[136:139], v175 offset:2048
	ds_read_b128 v[140:143], v175 offset:3072
	ds_read_b128 v[164:167], v176
	ds_read_b128 v[168:171], v176 offset:1024
	ds_read_b128 v[178:181], v176 offset:2048
	ds_read_b128 v[182:185], v176 offset:3072
	s_add_u32 s42, s40, 0xfff80080
	s_addc_u32 s43, s41, -1
	s_cmp_eq_u32 s69, 28
	s_cselect_b32 s45, s29, s43
	s_cselect_b32 s44, s37, s42
	s_cselect_b32 s43, s27, s68
	s_cselect_b32 s42, s65, s67
	v_lshl_add_u64 v[190:191], s[40:41], 0, v[156:157]
	s_add_i32 m0, s52, 0xc000
	ds_read_b128 v[186:189], v177
	ds_read_b128 v[194:197], v177 offset:1024
	ds_read_b128 v[198:201], v177 offset:2048
	ds_read_b128 v[202:205], v177 offset:3072
	ds_read_b128 v[206:209], v177 offset:4096
	ds_read_b128 v[210:213], v177 offset:5120
	ds_read_b128 v[218:221], v177 offset:6144
	ds_read_b128 v[222:225], v177 offset:7168
	global_load_lds_dwordx4 v[190:191], off
	v_lshl_add_u64 v[190:191], s[40:41], 0, v[158:159]
	s_add_i32 m0, s52, 0xe000
	s_nop 0
	global_load_lds_dwordx4 v[190:191], off
	s_waitcnt vmcnt(8) lgkmcnt(0)
	s_setprio 1
	s_barrier
	v_mfma_f32_16x16x32_bf16 v[124:127], v[128:131], v[186:189], 0
	v_mfma_f32_16x16x32_bf16 v[120:123], v[136:139], v[186:189], 0
	v_mfma_f32_16x16x32_bf16 v[116:119], v[128:131], v[198:201], 0
	v_mfma_f32_16x16x32_bf16 v[112:115], v[136:139], v[198:201], 0
	v_mfma_f32_16x16x32_bf16 v[100:103], v[128:131], v[206:209], 0
	v_mfma_f32_16x16x32_bf16 v[96:99], v[136:139], v[206:209], 0
	v_mfma_f32_16x16x32_bf16 v[84:87], v[128:131], v[218:221], 0
	v_mfma_f32_16x16x32_bf16 v[80:83], v[136:139], v[218:221], 0
	v_mfma_f32_16x16x32_bf16 v[124:127], v[132:135], v[194:197], v[124:127]
	v_mfma_f32_16x16x32_bf16 v[120:123], v[140:143], v[194:197], v[120:123]
	v_mfma_f32_16x16x32_bf16 v[116:119], v[132:135], v[202:205], v[116:119]
	v_mfma_f32_16x16x32_bf16 v[112:115], v[140:143], v[202:205], v[112:115]
	v_mfma_f32_16x16x32_bf16 v[100:103], v[132:135], v[210:213], v[100:103]
	v_mfma_f32_16x16x32_bf16 v[96:99], v[140:143], v[210:213], v[96:99]
	v_mfma_f32_16x16x32_bf16 v[84:87], v[132:135], v[222:225], v[84:87]
	v_mfma_f32_16x16x32_bf16 v[80:83], v[140:143], v[222:225], v[80:83]
	v_mfma_f32_16x16x32_bf16 v[108:111], v[164:167], v[186:189], 0
	v_mfma_f32_16x16x32_bf16 v[104:107], v[178:181], v[186:189], 0
	v_mfma_f32_16x16x32_bf16 v[92:95], v[164:167], v[198:201], 0
	v_mfma_f32_16x16x32_bf16 v[88:91], v[178:181], v[198:201], 0
	v_mfma_f32_16x16x32_bf16 v[76:79], v[164:167], v[206:209], 0
	v_mfma_f32_16x16x32_bf16 v[72:75], v[178:181], v[206:209], 0
	v_mfma_f32_16x16x32_bf16 v[68:71], v[164:167], v[218:221], 0
	v_mfma_f32_16x16x32_bf16 v[64:67], v[178:181], v[218:221], 0
	v_mfma_f32_16x16x32_bf16 v[108:111], v[168:171], v[194:197], v[108:111]
	v_mfma_f32_16x16x32_bf16 v[104:107], v[182:185], v[194:197], v[104:107]
	v_mfma_f32_16x16x32_bf16 v[92:95], v[168:171], v[202:205], v[92:95]
	v_mfma_f32_16x16x32_bf16 v[88:91], v[182:185], v[202:205], v[88:91]
	v_mfma_f32_16x16x32_bf16 v[76:79], v[168:171], v[210:213], v[76:79]
	v_mfma_f32_16x16x32_bf16 v[72:75], v[182:185], v[210:213], v[72:75]
	v_mfma_f32_16x16x32_bf16 v[68:71], v[168:171], v[222:225], v[68:71]
	v_mfma_f32_16x16x32_bf16 v[64:67], v[182:185], v[222:225], v[64:67]
	s_barrier
	s_setprio 0
	s_add_i32 s70, s61, s50
	v_lshl_add_u64 v[190:191], s[42:43], 0, v[148:149]
	s_mov_b32 m0, s70
	ds_read_b128 v[186:189], v177 offset:16384
	ds_read_b128 v[194:197], v177 offset:17408
	ds_read_b128 v[198:201], v177 offset:18432
	ds_read_b128 v[202:205], v177 offset:19456
	ds_read_b128 v[206:209], v177 offset:20480
	ds_read_b128 v[210:213], v177 offset:21504
	ds_read_b128 v[218:221], v177 offset:22528
	ds_read_b128 v[222:225], v177 offset:23552
	global_load_lds_dwordx4 v[190:191], off
	s_add_i32 m0, s70, 0x2000
	s_add_u32 s70, s42, 0x80000
	v_lshl_add_u64 v[214:215], s[42:43], 0, v[144:145]
	s_addc_u32 s71, s43, 0
	s_add_i32 s72, s62, s50
	global_load_lds_dwordx4 v[214:215], off
	v_lshl_add_u64 v[226:227], s[70:71], 0, v[148:149]
	s_mov_b32 m0, s72
	v_lshl_add_u64 v[228:229], s[44:45], 0, v[146:147]
	global_load_lds_dwordx4 v[226:227], off
	v_lshl_add_u64 v[226:227], s[70:71], 0, v[144:145]
	s_add_i32 m0, s72, 0x2000
	s_nop 0
	global_load_lds_dwordx4 v[226:227], off
	v_lshl_add_u64 v[226:227], s[44:45], 0, v[150:151]
	s_mov_b32 m0, s52
	s_nop 0
	global_load_lds_dwordx4 v[226:227], off
	s_mov_b32 m0, s53
	s_nop 0
	global_load_lds_dwordx4 v[228:229], off
	s_waitcnt vmcnt(8) lgkmcnt(0)
	s_setprio 1
	s_barrier
; #define PG8_STAGE(bufoff, gbase, voff) do { _Pragma("unroll") for (int _i = 0; _i < 2; ++_i) \
;         __builtin_amdgcn_global_load_lds((const unsigned*)((const char*)(gbase) + (voff)[_i]), (PG8_LAS unsigned*)(lds + (bufoff) + ldsw + _i * 8192), 16, 0, 0); } while (0)
; #define PG8_LDA(dst, b, h) do { _Pragma("unroll") for (int m = 0; m < 4; ++m) _Pragma("unroll") for (int k = 0; k < 2; ++k) dst[m][k] = *(const PG8_LAS bf16x8*)(lds + PG8_SA(b, h) + aoff + m * 2048 + k * 1024); } while (0)
; #define PG8_LDB(dst, b, h) do { _Pragma("unroll") for (int n = 0; n < 2; ++n) _Pragma("unroll") for (int k = 0; k < 2; ++k) dst[n][k] = *(const PG8_LAS bf16x8*)(lds + PG8_SB(b, h) + boff + n * 2048 + k * 1024); } while (0)
; #define PG8_MMA(ai, bj, At, Bt) do { __builtin_amdgcn_s_setprio(1); _Pragma("unroll") for (int m = 0; m < 4; ++m) _Pragma("unroll") for (int n = 0; n < 2; ++n) _Pragma("unroll") for (int k = 0; k < 2; ++k) \
;         acc[ai][bj][m][n] = __builtin_amdgcn_mfma_f32_16x16x32_bf16(Bt[n][k], At[m][k], acc[ai][bj][m][n], 0, 0, 0); __builtin_amdgcn_s_setprio(0); } while (0)
; #define PG8_WAIT_V(n) asm volatile("s_waitcnt vmcnt(" #n ")" ::: "memory")
; #define PG8_WAIT_L(n) asm volatile("s_waitcnt lgkmcnt(" #n ")" ::: "memory")
; #define PG8_BAR __builtin_amdgcn_s_barrier()
; #define PG8_SCHED __builtin_amdgcn_sched_barrier(0)
; template <class Epi, class Sched, bool ALIGN_EPI = false, bool SP2 = false>
; __device__ __forceinline__ void gemm_phase(PG8_LAS unsigned char* lds, const Gemm g, const Sched& S, const Epi& E) {
;     ...
;             PG8_WAIT_V(8); PG8_WAIT_L(0); PG8_BAR; PG8_MMA(1, 0, At, B0); PG8_MMA(1, 1, At, B1); PG8_BAR; PG8_SCHED;
;             PG8_LDB(B0, 1, 0); PG8_LDB(B1, 1, 1); PG8_SCHED; PG8_LDA(At, 1, 0); PG8_STAGE(PG8_SA(0, 1), a2 + hstep, voffA);
;             PG8_WAIT_V(8); PG8_WAIT_L(0); PG8_BAR; PG8_MMA(0, 0, At, B0); PG8_MMA(0, 1, At, B1); PG8_BAR; PG8_SCHED;
	v_mfma_f32_16x16x32_bf16 v[60:63], v[128:131], v[186:189], 0
	v_mfma_f32_16x16x32_bf16 v[56:59], v[136:139], v[186:189], 0
	v_mfma_f32_16x16x32_bf16 v[52:55], v[128:131], v[198:201], 0
	v_mfma_f32_16x16x32_bf16 v[48:51], v[136:139], v[198:201], 0
	v_mfma_f32_16x16x32_bf16 v[36:39], v[128:131], v[206:209], 0
	v_mfma_f32_16x16x32_bf16 v[32:35], v[136:139], v[206:209], 0
	v_mfma_f32_16x16x32_bf16 v[20:23], v[128:131], v[218:221], 0
	v_mfma_f32_16x16x32_bf16 v[16:19], v[136:139], v[218:221], 0
	v_mfma_f32_16x16x32_bf16 v[60:63], v[132:135], v[194:197], v[60:63]
	v_mfma_f32_16x16x32_bf16 v[56:59], v[140:143], v[194:197], v[56:59]
	v_mfma_f32_16x16x32_bf16 v[52:55], v[132:135], v[202:205], v[52:55]
	v_mfma_f32_16x16x32_bf16 v[48:51], v[140:143], v[202:205], v[48:51]
	v_mfma_f32_16x16x32_bf16 v[36:39], v[132:135], v[210:213], v[36:39]
	v_mfma_f32_16x16x32_bf16 v[32:35], v[140:143], v[210:213], v[32:35]
	v_mfma_f32_16x16x32_bf16 v[20:23], v[132:135], v[222:225], v[20:23]
	v_mfma_f32_16x16x32_bf16 v[16:19], v[140:143], v[222:225], v[16:19]
	v_mfma_f32_16x16x32_bf16 v[44:47], v[164:167], v[186:189], 0
	v_mfma_f32_16x16x32_bf16 v[40:43], v[178:181], v[186:189], 0
	v_mfma_f32_16x16x32_bf16 v[28:31], v[164:167], v[198:201], 0
	v_mfma_f32_16x16x32_bf16 v[24:27], v[178:181], v[198:201], 0
	v_mfma_f32_16x16x32_bf16 v[12:15], v[164:167], v[206:209], 0
	v_mfma_f32_16x16x32_bf16 v[8:11], v[178:181], v[206:209], 0
	v_mfma_f32_16x16x32_bf16 v[4:7], v[164:167], v[218:221], 0
	v_mfma_f32_16x16x32_bf16 v[0:3], v[178:181], v[218:221], 0
	v_mfma_f32_16x16x32_bf16 v[44:47], v[168:171], v[194:197], v[44:47]
	v_mfma_f32_16x16x32_bf16 v[40:43], v[182:185], v[194:197], v[40:43]
	v_mfma_f32_16x16x32_bf16 v[28:31], v[168:171], v[202:205], v[28:31]
	v_mfma_f32_16x16x32_bf16 v[24:27], v[182:185], v[202:205], v[24:27]
	v_mfma_f32_16x16x32_bf16 v[12:15], v[168:171], v[210:213], v[12:15]
	v_mfma_f32_16x16x32_bf16 v[8:11], v[182:185], v[210:213], v[8:11]
	v_mfma_f32_16x16x32_bf16 v[4:7], v[168:171], v[222:225], v[4:7]
	v_mfma_f32_16x16x32_bf16 v[0:3], v[182:185], v[222:225], v[0:3]
	s_barrier
	s_setprio 0
	s_add_i32 s70, 0, 0x18000
	s_add_i32 s71, 0, 0x1c000
	v_add_u32_e32 v140, s70, v173
	v_add_u32_e32 v182, s71, v173
	ds_read_b128 v[128:131], v140
	ds_read_b128 v[132:135], v140 offset:1024
	ds_read_b128 v[136:139], v140 offset:2048
	ds_read_b128 v[140:143], v140 offset:3072
	ds_read_b128 v[164:167], v182
	ds_read_b128 v[168:171], v182 offset:1024
	ds_read_b128 v[178:181], v182 offset:2048
	ds_read_b128 v[182:185], v182 offset:3072
	s_add_u32 s44, s44, 0x80000
	s_addc_u32 s45, s45, 0
	s_mov_b32 m0, s54
	v_lshl_add_u64 v[230:231], s[44:45], 0, v[150:151]
	ds_read_b128 v[186:189], v177 offset:32768
	ds_read_b128 v[194:197], v177 offset:33792
	ds_read_b128 v[198:201], v177 offset:34816
	ds_read_b128 v[202:205], v177 offset:35840
	ds_read_b128 v[206:209], v177 offset:36864
	ds_read_b128 v[210:213], v177 offset:37888
	ds_read_b128 v[218:221], v177 offset:38912
	ds_read_b128 v[222:225], v177 offset:39936
	global_load_lds_dwordx4 v[230:231], off
	v_lshl_add_u64 v[230:231], s[44:45], 0, v[146:147]
	s_mov_b32 m0, s55
	s_nop 0
	global_load_lds_dwordx4 v[230:231], off
	s_waitcnt vmcnt(8) lgkmcnt(0)
	s_setprio 1
	s_barrier
	v_mfma_f32_16x16x32_bf16 v[124:127], v[128:131], v[186:189], v[124:127]
	v_mfma_f32_16x16x32_bf16 v[120:123], v[136:139], v[186:189], v[120:123]
	v_mfma_f32_16x16x32_bf16 v[116:119], v[128:131], v[198:201], v[116:119]
	v_mfma_f32_16x16x32_bf16 v[112:115], v[136:139], v[198:201], v[112:115]
	v_mfma_f32_16x16x32_bf16 v[100:103], v[128:131], v[206:209], v[100:103]
	v_mfma_f32_16x16x32_bf16 v[96:99], v[136:139], v[206:209], v[96:99]
	v_mfma_f32_16x16x32_bf16 v[84:87], v[128:131], v[218:221], v[84:87]
	v_mfma_f32_16x16x32_bf16 v[80:83], v[136:139], v[218:221], v[80:83]
	v_mfma_f32_16x16x32_bf16 v[124:127], v[132:135], v[194:197], v[124:127]
	v_mfma_f32_16x16x32_bf16 v[120:123], v[140:143], v[194:197], v[120:123]
	v_mfma_f32_16x16x32_bf16 v[116:119], v[132:135], v[202:205], v[116:119]
	v_mfma_f32_16x16x32_bf16 v[112:115], v[140:143], v[202:205], v[112:115]
	v_mfma_f32_16x16x32_bf16 v[100:103], v[132:135], v[210:213], v[100:103]
	v_mfma_f32_16x16x32_bf16 v[96:99], v[140:143], v[210:213], v[96:99]
	v_mfma_f32_16x16x32_bf16 v[84:87], v[132:135], v[222:225], v[84:87]
	v_mfma_f32_16x16x32_bf16 v[80:83], v[140:143], v[222:225], v[80:83]
	v_mfma_f32_16x16x32_bf16 v[108:111], v[164:167], v[186:189], v[108:111]
	v_mfma_f32_16x16x32_bf16 v[104:107], v[178:181], v[186:189], v[104:107]
	v_mfma_f32_16x16x32_bf16 v[92:95], v[164:167], v[198:201], v[92:95]
	v_mfma_f32_16x16x32_bf16 v[88:91], v[178:181], v[198:201], v[88:91]
	v_mfma_f32_16x16x32_bf16 v[76:79], v[164:167], v[206:209], v[76:79]
	v_mfma_f32_16x16x32_bf16 v[72:75], v[178:181], v[206:209], v[72:75]
	v_mfma_f32_16x16x32_bf16 v[68:71], v[164:167], v[218:221], v[68:71]
	v_mfma_f32_16x16x32_bf16 v[64:67], v[178:181], v[218:221], v[64:67]
	v_mfma_f32_16x16x32_bf16 v[108:111], v[168:171], v[194:197], v[108:111]
	v_mfma_f32_16x16x32_bf16 v[104:107], v[182:185], v[194:197], v[104:107]
	v_mfma_f32_16x16x32_bf16 v[92:95], v[168:171], v[202:205], v[92:95]
	v_mfma_f32_16x16x32_bf16 v[88:91], v[182:185], v[202:205], v[88:91]
	v_mfma_f32_16x16x32_bf16 v[76:79], v[168:171], v[210:213], v[76:79]
	v_mfma_f32_16x16x32_bf16 v[72:75], v[182:185], v[210:213], v[72:75]
	v_mfma_f32_16x16x32_bf16 v[68:71], v[168:171], v[222:225], v[68:71]
	v_mfma_f32_16x16x32_bf16 v[64:67], v[182:185], v[222:225], v[64:67]
	s_barrier
; #define PG8_STAGE(bufoff, gbase, voff) do { _Pragma("unroll") for (int _i = 0; _i < 2; ++_i) \
;         __builtin_amdgcn_global_load_lds((const unsigned*)((const char*)(gbase) + (voff)[_i]), (PG8_LAS unsigned*)(lds + (bufoff) + ldsw + _i * 8192), 16, 0, 0); } while (0)
; #define PG8_LDA(dst, b, h) do { _Pragma("unroll") for (int m = 0; m < 4; ++m) _Pragma("unroll") for (int k = 0; k < 2; ++k) dst[m][k] = *(const PG8_LAS bf16x8*)(lds + PG8_SA(b, h) + aoff + m * 2048 + k * 1024); } while (0)
; #define PG8_LDB(dst, b, h) do { _Pragma("unroll") for (int n = 0; n < 2; ++n) _Pragma("unroll") for (int k = 0; k < 2; ++k) dst[n][k] = *(const PG8_LAS bf16x8*)(lds + PG8_SB(b, h) + boff + n * 2048 + k * 1024); } while (0)
; #define PG8_MMA(ai, bj, At, Bt) do { __builtin_amdgcn_s_setprio(1); _Pragma("unroll") for (int m = 0; m < 4; ++m) _Pragma("unroll") for (int n = 0; n < 2; ++n) _Pragma("unroll") for (int k = 0; k < 2; ++k) \
;         acc[ai][bj][m][n] = __builtin_amdgcn_mfma_f32_16x16x32_bf16(Bt[n][k], At[m][k], acc[ai][bj][m][n], 0, 0, 0); __builtin_amdgcn_s_setprio(0); } while (0)
; #define PG8_WAIT_V(n) asm volatile("s_waitcnt vmcnt(" #n ")" ::: "memory")
; template <class Epi, class Sched, bool ALIGN_EPI = false, bool SP2 = false>
; __device__ __forceinline__ void gemm_phase(PG8_LAS unsigned char* lds, const Gemm g, const Sched& S, const Epi& E) {
;     ...
;             PG8_LDB(B0, 0, 0); PG8_LDB(B1, 0, 1); PG8_SCHED; PG8_LDA(At, 0, 0); PG8_STAGE(PG8_SA(1, 1), a1 + hstep, voffA);
;             PG8_WAIT_V(8); PG8_WAIT_L(0); PG8_BAR; PG8_MMA(0, 0, At, B0); PG8_MMA(0, 1, At, B1); PG8_BAR; PG8_SCHED;
;             PG8_LDA(At, 0, 1); PG8_STAGE(PG8_SB(0, 0), b2, voffB); PG8_STAGE(PG8_SB(0, 1), b2 + hstep, voffB); PG8_STAGE(PG8_SA(0, 0), a2, voffA);
;             PG8_WAIT_V(8); PG8_WAIT_L(0); PG8_BAR; PG8_MMA(1, 0, At, B0); PG8_MMA(1, 1, At, B1); PG8_BAR; PG8_SCHED;
;             PG8_LDB(B0, 1, 0); PG8_LDB(B1, 1, 1); PG8_SCHED; PG8_LDA(At, 1, 0); PG8_STAGE(PG8_SA(0, 1), a2 + hstep, voffA);
;             PG8_WAIT_V(8); PG8_WAIT_L(0); PG8_BAR; PG8_MMA(0, 0, At, B0); PG8_MMA(0, 1, At, B1); PG8_BAR; PG8_SCHED;
;             PG8_LDA(At, 1, 1); PG8_STAGE(PG8_SB(1, 0), b3, voffB); PG8_STAGE(PG8_SB(1, 1), b3 + hstep, voffB); PG8_STAGE(PG8_SA(1, 0), a3, voffA);
;             PG8_WAIT_V(8); PG8_WAIT_L(0); PG8_BAR; PG8_MMA(1, 0, At, B0); PG8_MMA(1, 1, At, B1); PG8_BAR; PG8_SCHED;
	s_setprio 0
	s_add_i32 s44, s70, s50
	v_lshl_add_u64 v[190:191], v[190:191], 0, s[22:23]
	s_mov_b32 m0, s44
	ds_read_b128 v[186:189], v177 offset:49152
	ds_read_b128 v[194:197], v177 offset:50176
	ds_read_b128 v[198:201], v177 offset:51200
	ds_read_b128 v[202:205], v177 offset:52224
	ds_read_b128 v[206:209], v177 offset:53248
	ds_read_b128 v[210:213], v177 offset:54272
	ds_read_b128 v[218:221], v177 offset:55296
	ds_read_b128 v[222:225], v177 offset:56320
	global_load_lds_dwordx4 v[190:191], off
	s_add_i32 m0, s44, 0x2000
	s_add_u32 s42, s42, 0x80080
	v_lshl_add_u64 v[190:191], v[214:215], 0, s[22:23]
	s_addc_u32 s43, s43, 0
	s_add_i32 s44, s71, s50
	global_load_lds_dwordx4 v[190:191], off
	v_lshl_add_u64 v[190:191], s[42:43], 0, v[148:149]
	s_mov_b32 m0, s44
	s_nop 0
	global_load_lds_dwordx4 v[190:191], off
	v_lshl_add_u64 v[190:191], s[42:43], 0, v[144:145]
	s_add_i32 m0, s44, 0x2000
	s_nop 0
	global_load_lds_dwordx4 v[190:191], off
	v_lshl_add_u64 v[190:191], v[226:227], 0, s[22:23]
	s_mov_b32 m0, s59
	s_nop 0
	global_load_lds_dwordx4 v[190:191], off
	v_lshl_add_u64 v[190:191], v[228:229], 0, s[22:23]
	s_mov_b32 m0, s60
	s_nop 0
	global_load_lds_dwordx4 v[190:191], off
	s_waitcnt vmcnt(8) lgkmcnt(0)
	s_setprio 1
	s_barrier
	v_mfma_f32_16x16x32_bf16 v[60:63], v[128:131], v[186:189], v[60:63]
	v_mfma_f32_16x16x32_bf16 v[56:59], v[136:139], v[186:189], v[56:59]
	v_mfma_f32_16x16x32_bf16 v[52:55], v[128:131], v[198:201], v[52:55]
	v_mfma_f32_16x16x32_bf16 v[48:51], v[136:139], v[198:201], v[48:51]
	v_mfma_f32_16x16x32_bf16 v[36:39], v[128:131], v[206:209], v[36:39]
	v_mfma_f32_16x16x32_bf16 v[32:35], v[136:139], v[206:209], v[32:35]
	v_mfma_f32_16x16x32_bf16 v[20:23], v[128:131], v[218:221], v[20:23]
	v_mfma_f32_16x16x32_bf16 v[16:19], v[136:139], v[218:221], v[16:19]
	v_mfma_f32_16x16x32_bf16 v[60:63], v[132:135], v[194:197], v[60:63]
	v_mfma_f32_16x16x32_bf16 v[56:59], v[140:143], v[194:197], v[56:59]
	v_mfma_f32_16x16x32_bf16 v[52:55], v[132:135], v[202:205], v[52:55]
	v_mfma_f32_16x16x32_bf16 v[48:51], v[140:143], v[202:205], v[48:51]
	v_mfma_f32_16x16x32_bf16 v[36:39], v[132:135], v[210:213], v[36:39]
	v_mfma_f32_16x16x32_bf16 v[32:35], v[140:143], v[210:213], v[32:35]
	v_mfma_f32_16x16x32_bf16 v[20:23], v[132:135], v[222:225], v[20:23]
	v_mfma_f32_16x16x32_bf16 v[16:19], v[140:143], v[222:225], v[16:19]
	v_mfma_f32_16x16x32_bf16 v[44:47], v[164:167], v[186:189], v[44:47]
	v_mfma_f32_16x16x32_bf16 v[40:43], v[178:181], v[186:189], v[40:43]
	v_mfma_f32_16x16x32_bf16 v[28:31], v[164:167], v[198:201], v[28:31]
	v_mfma_f32_16x16x32_bf16 v[24:27], v[178:181], v[198:201], v[24:27]
	v_mfma_f32_16x16x32_bf16 v[12:15], v[164:167], v[206:209], v[12:15]
	v_mfma_f32_16x16x32_bf16 v[8:11], v[178:181], v[206:209], v[8:11]
	v_mfma_f32_16x16x32_bf16 v[4:7], v[164:167], v[218:221], v[4:7]
	v_mfma_f32_16x16x32_bf16 v[0:3], v[178:181], v[218:221], v[0:3]
	v_mfma_f32_16x16x32_bf16 v[44:47], v[168:171], v[194:197], v[44:47]
	v_mfma_f32_16x16x32_bf16 v[40:43], v[182:185], v[194:197], v[40:43]
	v_mfma_f32_16x16x32_bf16 v[28:31], v[168:171], v[202:205], v[28:31]
	v_mfma_f32_16x16x32_bf16 v[24:27], v[182:185], v[202:205], v[24:27]
	v_mfma_f32_16x16x32_bf16 v[12:15], v[168:171], v[210:213], v[12:15]
	v_mfma_f32_16x16x32_bf16 v[8:11], v[182:185], v[210:213], v[8:11]
	v_mfma_f32_16x16x32_bf16 v[4:7], v[168:171], v[222:225], v[4:7]
	v_mfma_f32_16x16x32_bf16 v[0:3], v[182:185], v[222:225], v[0:3]
	s_barrier
	s_setprio 0
	s_add_i32 s69, s69, 2
	s_add_u32 s40, s40, 0x100
	s_addc_u32 s41, s41, 0
	s_add_u32 s67, s67, 0x100
	s_addc_u32 s68, s68, 0
	s_cmp_gt_u32 s69, 29
.LBB0_171:
	ds_read_b128 v[128:131], v175
	ds_read_b128 v[132:135], v175 offset:1024
	ds_read_b128 v[136:139], v175 offset:2048
	ds_read_b128 v[140:143], v175 offset:3072
	ds_read_b128 v[164:167], v176
	ds_read_b128 v[168:171], v176 offset:1024
	ds_read_b128 v[178:181], v176 offset:2048
	ds_read_b128 v[182:185], v176 offset:3072
	s_add_u32 s42, s40, 0xfff80080
	s_addc_u32 s43, s41, -1
	s_cmp_eq_u32 s69, 28
	s_cselect_b32 s45, s29, s43
	s_cselect_b32 s44, s37, s42
	s_cselect_b32 s43, s27, s68
	s_cselect_b32 s42, s65, s67
	v_lshl_add_u64 v[190:191], s[40:41], 0, v[156:157]
	s_add_i32 m0, s52, 0xc000
	ds_read_b128 v[186:189], v177
	ds_read_b128 v[194:197], v177 offset:1024
	ds_read_b128 v[198:201], v177 offset:2048
	ds_read_b128 v[202:205], v177 offset:3072
	ds_read_b128 v[206:209], v177 offset:4096
	ds_read_b128 v[210:213], v177 offset:5120
	ds_read_b128 v[218:221], v177 offset:6144
	ds_read_b128 v[222:225], v177 offset:7168
	global_load_lds_dwordx4 v[190:191], off
	v_lshl_add_u64 v[190:191], s[40:41], 0, v[158:159]
	s_add_i32 m0, s52, 0xe000
	s_nop 0
	global_load_lds_dwordx4 v[190:191], off
	s_waitcnt vmcnt(8) lgkmcnt(0)
	s_setprio 1
	s_barrier
; #define PG8_STAGE(bufoff, gbase, voff) do { _Pragma("unroll") for (int _i = 0; _i < 2; ++_i) \
;         __builtin_amdgcn_global_load_lds((const unsigned*)((const char*)(gbase) + (voff)[_i]), (PG8_LAS unsigned*)(lds + (bufoff) + ldsw + _i * 8192), 16, 0, 0); } while (0)
; #define PG8_LDA(dst, b, h) do { _Pragma("unroll") for (int m = 0; m < 4; ++m) _Pragma("unroll") for (int k = 0; k < 2; ++k) dst[m][k] = *(const PG8_LAS bf16x8*)(lds + PG8_SA(b, h) + aoff + m * 2048 + k * 1024); } while (0)
; #define PG8_MMA(ai, bj, At, Bt) do { __builtin_amdgcn_s_setprio(1); _Pragma("unroll") for (int m = 0; m < 4; ++m) _Pragma("unroll") for (int n = 0; n < 2; ++n) _Pragma("unroll") for (int k = 0; k < 2; ++k) \
;         acc[ai][bj][m][n] = __builtin_amdgcn_mfma_f32_16x16x32_bf16(Bt[n][k], At[m][k], acc[ai][bj][m][n], 0, 0, 0); __builtin_amdgcn_s_setprio(0); } while (0)
; #define PG8_WAIT_V(n) asm volatile("s_waitcnt vmcnt(" #n ")" ::: "memory")
; #define PG8_WAIT_L(n) asm volatile("s_waitcnt lgkmcnt(" #n ")" ::: "memory")
; #define PG8_BAR __builtin_amdgcn_s_barrier()
; #define PG8_SCHED __builtin_amdgcn_sched_barrier(0)
; template <class Epi, class Sched, bool ALIGN_EPI = false, bool SP2 = false>
; __device__ __forceinline__ void gemm_phase(PG8_LAS unsigned char* lds, const Gemm g, const Sched& S, const Epi& E) {
;     ...
;             PG8_WAIT_V(8); PG8_WAIT_L(0); PG8_BAR; PG8_MMA(0, 0, At, B0); PG8_MMA(0, 1, At, B1); PG8_BAR; PG8_SCHED;
;             PG8_LDA(At, 0, 1); PG8_STAGE(PG8_SB(0, 0), b2, voffB); PG8_STAGE(PG8_SB(0, 1), b2 + hstep, voffB); PG8_STAGE(PG8_SA(0, 0), a2, voffA);
;             PG8_WAIT_V(8); PG8_WAIT_L(0); PG8_BAR; PG8_MMA(1, 0, At, B0); PG8_MMA(1, 1, At, B1); PG8_BAR; PG8_SCHED;
	v_mfma_f32_16x16x32_bf16 v[124:127], v[128:131], v[186:189], v[124:127]
	v_mfma_f32_16x16x32_bf16 v[120:123], v[136:139], v[186:189], v[120:123]
	v_mfma_f32_16x16x32_bf16 v[116:119], v[128:131], v[198:201], v[116:119]
	v_mfma_f32_16x16x32_bf16 v[112:115], v[136:139], v[198:201], v[112:115]
	v_mfma_f32_16x16x32_bf16 v[100:103], v[128:131], v[206:209], v[100:103]
	v_mfma_f32_16x16x32_bf16 v[96:99], v[136:139], v[206:209], v[96:99]
	v_mfma_f32_16x16x32_bf16 v[84:87], v[128:131], v[218:221], v[84:87]
	v_mfma_f32_16x16x32_bf16 v[80:83], v[136:139], v[218:221], v[80:83]
	v_mfma_f32_16x16x32_bf16 v[124:127], v[132:135], v[194:197], v[124:127]
	v_mfma_f32_16x16x32_bf16 v[120:123], v[140:143], v[194:197], v[120:123]
	v_mfma_f32_16x16x32_bf16 v[116:119], v[132:135], v[202:205], v[116:119]
	v_mfma_f32_16x16x32_bf16 v[112:115], v[140:143], v[202:205], v[112:115]
	v_mfma_f32_16x16x32_bf16 v[100:103], v[132:135], v[210:213], v[100:103]
	v_mfma_f32_16x16x32_bf16 v[96:99], v[140:143], v[210:213], v[96:99]
	v_mfma_f32_16x16x32_bf16 v[84:87], v[132:135], v[222:225], v[84:87]
	v_mfma_f32_16x16x32_bf16 v[80:83], v[140:143], v[222:225], v[80:83]
	v_mfma_f32_16x16x32_bf16 v[108:111], v[164:167], v[186:189], v[108:111]
	v_mfma_f32_16x16x32_bf16 v[104:107], v[178:181], v[186:189], v[104:107]
	v_mfma_f32_16x16x32_bf16 v[92:95], v[164:167], v[198:201], v[92:95]
	v_mfma_f32_16x16x32_bf16 v[88:91], v[178:181], v[198:201], v[88:91]
	v_mfma_f32_16x16x32_bf16 v[76:79], v[164:167], v[206:209], v[76:79]
	v_mfma_f32_16x16x32_bf16 v[72:75], v[178:181], v[206:209], v[72:75]
	v_mfma_f32_16x16x32_bf16 v[68:71], v[164:167], v[218:221], v[68:71]
	v_mfma_f32_16x16x32_bf16 v[64:67], v[178:181], v[218:221], v[64:67]
	v_mfma_f32_16x16x32_bf16 v[108:111], v[168:171], v[194:197], v[108:111]
	v_mfma_f32_16x16x32_bf16 v[104:107], v[182:185], v[194:197], v[104:107]
	v_mfma_f32_16x16x32_bf16 v[92:95], v[168:171], v[202:205], v[92:95]
	v_mfma_f32_16x16x32_bf16 v[88:91], v[182:185], v[202:205], v[88:91]
	v_mfma_f32_16x16x32_bf16 v[76:79], v[168:171], v[210:213], v[76:79]
	v_mfma_f32_16x16x32_bf16 v[72:75], v[182:185], v[210:213], v[72:75]
	v_mfma_f32_16x16x32_bf16 v[68:71], v[168:171], v[222:225], v[68:71]
	v_mfma_f32_16x16x32_bf16 v[64:67], v[182:185], v[222:225], v[64:67]
	s_barrier
	s_setprio 0
	s_add_i32 s70, s61, s50
	v_lshl_add_u64 v[190:191], s[42:43], 0, v[148:149]
	s_mov_b32 m0, s70
	ds_read_b128 v[186:189], v177 offset:16384
	ds_read_b128 v[194:197], v177 offset:17408
	ds_read_b128 v[198:201], v177 offset:18432
	ds_read_b128 v[202:205], v177 offset:19456
	ds_read_b128 v[206:209], v177 offset:20480
	ds_read_b128 v[210:213], v177 offset:21504
	ds_read_b128 v[218:221], v177 offset:22528
	ds_read_b128 v[222:225], v177 offset:23552
	global_load_lds_dwordx4 v[190:191], off
	s_add_i32 m0, s70, 0x2000
	s_add_u32 s70, s42, 0x80000
	v_lshl_add_u64 v[214:215], s[42:43], 0, v[144:145]
	s_addc_u32 s71, s43, 0
	s_add_i32 s72, s62, s50
	global_load_lds_dwordx4 v[214:215], off
	v_lshl_add_u64 v[226:227], s[70:71], 0, v[148:149]
	s_mov_b32 m0, s72
	v_lshl_add_u64 v[228:229], s[44:45], 0, v[146:147]
	global_load_lds_dwordx4 v[226:227], off
	v_lshl_add_u64 v[226:227], s[70:71], 0, v[144:145]
	s_add_i32 m0, s72, 0x2000
	s_nop 0
	global_load_lds_dwordx4 v[226:227], off
	v_lshl_add_u64 v[226:227], s[44:45], 0, v[150:151]
	s_mov_b32 m0, s52
	s_nop 0
	global_load_lds_dwordx4 v[226:227], off
	s_mov_b32 m0, s53
	s_nop 0
	global_load_lds_dwordx4 v[228:229], off
	s_waitcnt vmcnt(8) lgkmcnt(0)
	s_setprio 1
	s_barrier
	v_mfma_f32_16x16x32_bf16 v[60:63], v[128:131], v[186:189], v[60:63]
	v_mfma_f32_16x16x32_bf16 v[56:59], v[136:139], v[186:189], v[56:59]
	v_mfma_f32_16x16x32_bf16 v[52:55], v[128:131], v[198:201], v[52:55]
	v_mfma_f32_16x16x32_bf16 v[48:51], v[136:139], v[198:201], v[48:51]
	v_mfma_f32_16x16x32_bf16 v[36:39], v[128:131], v[206:209], v[36:39]
	v_mfma_f32_16x16x32_bf16 v[32:35], v[136:139], v[206:209], v[32:35]
	v_mfma_f32_16x16x32_bf16 v[20:23], v[128:131], v[218:221], v[20:23]
	v_mfma_f32_16x16x32_bf16 v[16:19], v[136:139], v[218:221], v[16:19]
	v_mfma_f32_16x16x32_bf16 v[60:63], v[132:135], v[194:197], v[60:63]
	v_mfma_f32_16x16x32_bf16 v[56:59], v[140:143], v[194:197], v[56:59]
	v_mfma_f32_16x16x32_bf16 v[52:55], v[132:135], v[202:205], v[52:55]
	v_mfma_f32_16x16x32_bf16 v[48:51], v[140:143], v[202:205], v[48:51]
	v_mfma_f32_16x16x32_bf16 v[36:39], v[132:135], v[210:213], v[36:39]
	v_mfma_f32_16x16x32_bf16 v[32:35], v[140:143], v[210:213], v[32:35]
	v_mfma_f32_16x16x32_bf16 v[20:23], v[132:135], v[222:225], v[20:23]
	v_mfma_f32_16x16x32_bf16 v[16:19], v[140:143], v[222:225], v[16:19]
	v_mfma_f32_16x16x32_bf16 v[44:47], v[164:167], v[186:189], v[44:47]
	v_mfma_f32_16x16x32_bf16 v[40:43], v[178:181], v[186:189], v[40:43]
	v_mfma_f32_16x16x32_bf16 v[28:31], v[164:167], v[198:201], v[28:31]
	v_mfma_f32_16x16x32_bf16 v[24:27], v[178:181], v[198:201], v[24:27]
	v_mfma_f32_16x16x32_bf16 v[12:15], v[164:167], v[206:209], v[12:15]
	v_mfma_f32_16x16x32_bf16 v[8:11], v[178:181], v[206:209], v[8:11]
	v_mfma_f32_16x16x32_bf16 v[4:7], v[164:167], v[218:221], v[4:7]
	v_mfma_f32_16x16x32_bf16 v[0:3], v[178:181], v[218:221], v[0:3]
	v_mfma_f32_16x16x32_bf16 v[44:47], v[168:171], v[194:197], v[44:47]
	v_mfma_f32_16x16x32_bf16 v[40:43], v[182:185], v[194:197], v[40:43]
	v_mfma_f32_16x16x32_bf16 v[28:31], v[168:171], v[202:205], v[28:31]
	v_mfma_f32_16x16x32_bf16 v[24:27], v[182:185], v[202:205], v[24:27]
	v_mfma_f32_16x16x32_bf16 v[12:15], v[168:171], v[210:213], v[12:15]
	v_mfma_f32_16x16x32_bf16 v[8:11], v[182:185], v[210:213], v[8:11]
	v_mfma_f32_16x16x32_bf16 v[4:7], v[168:171], v[222:225], v[4:7]
	v_mfma_f32_16x16x32_bf16 v[0:3], v[182:185], v[222:225], v[0:3]
	s_barrier
; #define PG8_STAGE(bufoff, gbase, voff) do { _Pragma("unroll") for (int _i = 0; _i < 2; ++_i) \
;         __builtin_amdgcn_global_load_lds((const unsigned*)((const char*)(gbase) + (voff)[_i]), (PG8_LAS unsigned*)(lds + (bufoff) + ldsw + _i * 8192), 16, 0, 0); } while (0)
; #define PG8_LDA(dst, b, h) do { _Pragma("unroll") for (int m = 0; m < 4; ++m) _Pragma("unroll") for (int k = 0; k < 2; ++k) dst[m][k] = *(const PG8_LAS bf16x8*)(lds + PG8_SA(b, h) + aoff + m * 2048 + k * 1024); } while (0)
; #define PG8_LDB(dst, b, h) do { _Pragma("unroll") for (int n = 0; n < 2; ++n) _Pragma("unroll") for (int k = 0; k < 2; ++k) dst[n][k] = *(const PG8_LAS bf16x8*)(lds + PG8_SB(b, h) + boff + n * 2048 + k * 1024); } while (0)
; #define PG8_MMA(ai, bj, At, Bt) do { __builtin_amdgcn_s_setprio(1); _Pragma("unroll") for (int m = 0; m < 4; ++m) _Pragma("unroll") for (int n = 0; n < 2; ++n) _Pragma("unroll") for (int k = 0; k < 2; ++k) \
;         acc[ai][bj][m][n] = __builtin_amdgcn_mfma_f32_16x16x32_bf16(Bt[n][k], At[m][k], acc[ai][bj][m][n], 0, 0, 0); __builtin_amdgcn_s_setprio(0); } while (0)
; #define PG8_WAIT_V(n) asm volatile("s_waitcnt vmcnt(" #n ")" ::: "memory")
; #define PG8_WAIT_L(n) asm volatile("s_waitcnt lgkmcnt(" #n ")" ::: "memory")
; #define PG8_BAR __builtin_amdgcn_s_barrier()
; #define PG8_SCHED __builtin_amdgcn_sched_barrier(0)
; template <class Epi, class Sched, bool ALIGN_EPI = false, bool SP2 = false>
; __device__ __forceinline__ void gemm_phase(PG8_LAS unsigned char* lds, const Gemm g, const Sched& S, const Epi& E) {
;     ...
;             PG8_LDB(B0, 1, 0); PG8_LDB(B1, 1, 1); PG8_SCHED; PG8_LDA(At, 1, 0); PG8_STAGE(PG8_SA(0, 1), a2 + hstep, voffA);
;             PG8_WAIT_V(8); PG8_WAIT_L(0); PG8_BAR; PG8_MMA(0, 0, At, B0); PG8_MMA(0, 1, At, B1); PG8_BAR; PG8_SCHED;
	s_setprio 0
	s_add_i32 s70, 0, 0x18000
	s_add_i32 s71, 0, 0x1c000
	v_add_u32_e32 v140, s70, v173
	v_add_u32_e32 v182, s71, v173
	ds_read_b128 v[128:131], v140
	ds_read_b128 v[132:135], v140 offset:1024
	ds_read_b128 v[136:139], v140 offset:2048
	ds_read_b128 v[140:143], v140 offset:3072
	ds_read_b128 v[164:167], v182
	ds_read_b128 v[168:171], v182 offset:1024
	ds_read_b128 v[178:181], v182 offset:2048
	ds_read_b128 v[182:185], v182 offset:3072
	s_add_u32 s44, s44, 0x80000
	s_addc_u32 s45, s45, 0
	s_mov_b32 m0, s54
	v_lshl_add_u64 v[230:231], s[44:45], 0, v[150:151]
	ds_read_b128 v[186:189], v177 offset:32768
	ds_read_b128 v[194:197], v177 offset:33792
	ds_read_b128 v[198:201], v177 offset:34816
	ds_read_b128 v[202:205], v177 offset:35840
	ds_read_b128 v[206:209], v177 offset:36864
	ds_read_b128 v[210:213], v177 offset:37888
	ds_read_b128 v[218:221], v177 offset:38912
	ds_read_b128 v[222:225], v177 offset:39936
	global_load_lds_dwordx4 v[230:231], off
	v_lshl_add_u64 v[230:231], s[44:45], 0, v[146:147]
	s_mov_b32 m0, s55
	s_nop 0
	global_load_lds_dwordx4 v[230:231], off
	s_waitcnt vmcnt(8) lgkmcnt(0)
	s_setprio 1
	s_barrier
	v_mfma_f32_16x16x32_bf16 v[124:127], v[128:131], v[186:189], v[124:127]
	v_mfma_f32_16x16x32_bf16 v[120:123], v[136:139], v[186:189], v[120:123]
	v_mfma_f32_16x16x32_bf16 v[116:119], v[128:131], v[198:201], v[116:119]
	v_mfma_f32_16x16x32_bf16 v[112:115], v[136:139], v[198:201], v[112:115]
	v_mfma_f32_16x16x32_bf16 v[100:103], v[128:131], v[206:209], v[100:103]
	v_mfma_f32_16x16x32_bf16 v[96:99], v[136:139], v[206:209], v[96:99]
	v_mfma_f32_16x16x32_bf16 v[84:87], v[128:131], v[218:221], v[84:87]
	v_mfma_f32_16x16x32_bf16 v[80:83], v[136:139], v[218:221], v[80:83]
	v_mfma_f32_16x16x32_bf16 v[124:127], v[132:135], v[194:197], v[124:127]
	v_mfma_f32_16x16x32_bf16 v[120:123], v[140:143], v[194:197], v[120:123]
	v_mfma_f32_16x16x32_bf16 v[116:119], v[132:135], v[202:205], v[116:119]
	v_mfma_f32_16x16x32_bf16 v[112:115], v[140:143], v[202:205], v[112:115]
	v_mfma_f32_16x16x32_bf16 v[100:103], v[132:135], v[210:213], v[100:103]
	v_mfma_f32_16x16x32_bf16 v[96:99], v[140:143], v[210:213], v[96:99]
	v_mfma_f32_16x16x32_bf16 v[84:87], v[132:135], v[222:225], v[84:87]
	v_mfma_f32_16x16x32_bf16 v[80:83], v[140:143], v[222:225], v[80:83]
	v_mfma_f32_16x16x32_bf16 v[108:111], v[164:167], v[186:189], v[108:111]
	v_mfma_f32_16x16x32_bf16 v[104:107], v[178:181], v[186:189], v[104:107]
	v_mfma_f32_16x16x32_bf16 v[92:95], v[164:167], v[198:201], v[92:95]
	v_mfma_f32_16x16x32_bf16 v[88:91], v[178:181], v[198:201], v[88:91]
	v_mfma_f32_16x16x32_bf16 v[76:79], v[164:167], v[206:209], v[76:79]
	v_mfma_f32_16x16x32_bf16 v[72:75], v[178:181], v[206:209], v[72:75]
	v_mfma_f32_16x16x32_bf16 v[68:71], v[164:167], v[218:221], v[68:71]
	v_mfma_f32_16x16x32_bf16 v[64:67], v[178:181], v[218:221], v[64:67]
	v_mfma_f32_16x16x32_bf16 v[108:111], v[168:171], v[194:197], v[108:111]
	v_mfma_f32_16x16x32_bf16 v[104:107], v[182:185], v[194:197], v[104:107]
	v_mfma_f32_16x16x32_bf16 v[92:95], v[168:171], v[202:205], v[92:95]
	v_mfma_f32_16x16x32_bf16 v[88:91], v[182:185], v[202:205], v[88:91]
	v_mfma_f32_16x16x32_bf16 v[76:79], v[168:171], v[210:213], v[76:79]
	v_mfma_f32_16x16x32_bf16 v[72:75], v[182:185], v[210:213], v[72:75]
	v_mfma_f32_16x16x32_bf16 v[68:71], v[168:171], v[222:225], v[68:71]
	v_mfma_f32_16x16x32_bf16 v[64:67], v[182:185], v[222:225], v[64:67]
	s_barrier
; #define PG8_STAGE(bufoff, gbase, voff) do { _Pragma("unroll") for (int _i = 0; _i < 2; ++_i) \
;         __builtin_amdgcn_global_load_lds((const unsigned*)((const char*)(gbase) + (voff)[_i]), (PG8_LAS unsigned*)(lds + (bufoff) + ldsw + _i * 8192), 16, 0, 0); } while (0)
; #define PG8_LDA(dst, b, h) do { _Pragma("unroll") for (int m = 0; m < 4; ++m) _Pragma("unroll") for (int k = 0; k < 2; ++k) dst[m][k] = *(const PG8_LAS bf16x8*)(lds + PG8_SA(b, h) + aoff + m * 2048 + k * 1024); } while (0)
; #define PG8_MMA(ai, bj, At, Bt) do { __builtin_amdgcn_s_setprio(1); _Pragma("unroll") for (int m = 0; m < 4; ++m) _Pragma("unroll") for (int n = 0; n < 2; ++n) _Pragma("unroll") for (int k = 0; k < 2; ++k) \
;         acc[ai][bj][m][n] = __builtin_amdgcn_mfma_f32_16x16x32_bf16(Bt[n][k], At[m][k], acc[ai][bj][m][n], 0, 0, 0); __builtin_amdgcn_s_setprio(0); } while (0)
; #define PG8_WAIT_V(n) asm volatile("s_waitcnt vmcnt(" #n ")" ::: "memory")
; #define PG8_WAIT_L(n) asm volatile("s_waitcnt lgkmcnt(" #n ")" ::: "memory")
; #define PG8_BAR __builtin_amdgcn_s_barrier()
; #define PG8_SCHED __builtin_amdgcn_sched_barrier(0)
; template <class Epi, class Sched, bool ALIGN_EPI = false, bool SP2 = false>
; __device__ __forceinline__ void gemm_phase(PG8_LAS unsigned char* lds, const Gemm g, const Sched& S, const Epi& E) {
;     ...
;             PG8_LDA(At, 1, 1); PG8_STAGE(PG8_SB(1, 0), b3, voffB); PG8_STAGE(PG8_SB(1, 1), b3 + hstep, voffB); PG8_STAGE(PG8_SA(1, 0), a3, voffA);
;             PG8_WAIT_V(8); PG8_WAIT_L(0); PG8_BAR; PG8_MMA(1, 0, At, B0); PG8_MMA(1, 1, At, B1); PG8_BAR; PG8_SCHED;
;     ...
;         if constexpr (ALIGN_EPI) { if (wr == 0) PG8_BAR; }
	s_setprio 0
	s_add_i32 s44, s70, s50
	v_lshl_add_u64 v[190:191], v[190:191], 0, s[22:23]
	s_mov_b32 m0, s44
	ds_read_b128 v[186:189], v177 offset:49152
	ds_read_b128 v[194:197], v177 offset:50176
	ds_read_b128 v[198:201], v177 offset:51200
	ds_read_b128 v[202:205], v177 offset:52224
	ds_read_b128 v[206:209], v177 offset:53248
	ds_read_b128 v[210:213], v177 offset:54272
	ds_read_b128 v[218:221], v177 offset:55296
	ds_read_b128 v[222:225], v177 offset:56320
	global_load_lds_dwordx4 v[190:191], off
	s_add_i32 m0, s44, 0x2000
	s_add_u32 s42, s42, 0x80080
	v_lshl_add_u64 v[190:191], v[214:215], 0, s[22:23]
	s_addc_u32 s43, s43, 0
	s_add_i32 s44, s71, s50
	global_load_lds_dwordx4 v[190:191], off
	v_lshl_add_u64 v[190:191], s[42:43], 0, v[148:149]
	s_mov_b32 m0, s44
	s_nop 0
	global_load_lds_dwordx4 v[190:191], off
	v_lshl_add_u64 v[190:191], s[42:43], 0, v[144:145]
	s_add_i32 m0, s44, 0x2000
	s_nop 0
	global_load_lds_dwordx4 v[190:191], off
	v_lshl_add_u64 v[190:191], v[226:227], 0, s[22:23]
	s_mov_b32 m0, s59
	s_nop 0
	global_load_lds_dwordx4 v[190:191], off
	v_lshl_add_u64 v[190:191], v[228:229], 0, s[22:23]
	s_mov_b32 m0, s60
	s_nop 0
	global_load_lds_dwordx4 v[190:191], off
	s_waitcnt vmcnt(8) lgkmcnt(0)
	s_setprio 1
	s_barrier
	v_mfma_f32_16x16x32_bf16 v[60:63], v[128:131], v[186:189], v[60:63]
	v_mfma_f32_16x16x32_bf16 v[56:59], v[136:139], v[186:189], v[56:59]
	v_mfma_f32_16x16x32_bf16 v[52:55], v[128:131], v[198:201], v[52:55]
	v_mfma_f32_16x16x32_bf16 v[48:51], v[136:139], v[198:201], v[48:51]
	v_mfma_f32_16x16x32_bf16 v[36:39], v[128:131], v[206:209], v[36:39]
	v_mfma_f32_16x16x32_bf16 v[32:35], v[136:139], v[206:209], v[32:35]
	v_mfma_f32_16x16x32_bf16 v[20:23], v[128:131], v[218:221], v[20:23]
	v_mfma_f32_16x16x32_bf16 v[16:19], v[136:139], v[218:221], v[16:19]
	v_mfma_f32_16x16x32_bf16 v[60:63], v[132:135], v[194:197], v[60:63]
	v_mfma_f32_16x16x32_bf16 v[56:59], v[140:143], v[194:197], v[56:59]
	v_mfma_f32_16x16x32_bf16 v[52:55], v[132:135], v[202:205], v[52:55]
	v_mfma_f32_16x16x32_bf16 v[48:51], v[140:143], v[202:205], v[48:51]
	v_mfma_f32_16x16x32_bf16 v[36:39], v[132:135], v[210:213], v[36:39]
	v_mfma_f32_16x16x32_bf16 v[32:35], v[140:143], v[210:213], v[32:35]
	v_mfma_f32_16x16x32_bf16 v[20:23], v[132:135], v[222:225], v[20:23]
	v_mfma_f32_16x16x32_bf16 v[16:19], v[140:143], v[222:225], v[16:19]
	v_mfma_f32_16x16x32_bf16 v[44:47], v[164:167], v[186:189], v[44:47]
	v_mfma_f32_16x16x32_bf16 v[40:43], v[178:181], v[186:189], v[40:43]
	v_mfma_f32_16x16x32_bf16 v[28:31], v[164:167], v[198:201], v[28:31]
	v_mfma_f32_16x16x32_bf16 v[24:27], v[178:181], v[198:201], v[24:27]
	v_mfma_f32_16x16x32_bf16 v[12:15], v[164:167], v[206:209], v[12:15]
	v_mfma_f32_16x16x32_bf16 v[8:11], v[178:181], v[206:209], v[8:11]
	v_mfma_f32_16x16x32_bf16 v[4:7], v[164:167], v[218:221], v[4:7]
	v_mfma_f32_16x16x32_bf16 v[0:3], v[178:181], v[218:221], v[0:3]
	v_mfma_f32_16x16x32_bf16 v[44:47], v[168:171], v[194:197], v[44:47]
	v_mfma_f32_16x16x32_bf16 v[40:43], v[182:185], v[194:197], v[40:43]
	v_mfma_f32_16x16x32_bf16 v[28:31], v[168:171], v[202:205], v[28:31]
	v_mfma_f32_16x16x32_bf16 v[24:27], v[182:185], v[202:205], v[24:27]
	v_mfma_f32_16x16x32_bf16 v[12:15], v[168:171], v[210:213], v[12:15]
	v_mfma_f32_16x16x32_bf16 v[8:11], v[182:185], v[210:213], v[8:11]
	v_mfma_f32_16x16x32_bf16 v[4:7], v[168:171], v[222:225], v[4:7]
	v_mfma_f32_16x16x32_bf16 v[0:3], v[182:185], v[222:225], v[0:3]
	s_barrier
	s_setprio 0
	s_add_i32 s69, s69, 2
	s_add_u32 s40, s40, 0x100
	s_addc_u32 s41, s41, 0
	s_add_u32 s67, s67, 0x100
	s_addc_u32 s68, s68, 0
	s_cmp_gt_u32 s69, 29
	s_cbranch_scc0 .LBB0_171
	s_and_b64 vcc, exec, s[24:25]
	s_cbranch_vccz .LBB0_174
	s_barrier

; #define PG8_STAGE(bufoff, gbase, voff) do { _Pragma("unroll") for (int _i = 0; _i < 2; ++_i) \
;         __builtin_amdgcn_global_load_lds((const unsigned*)((const char*)(gbase) + (voff)[_i]), (PG8_LAS unsigned*)(lds + (bufoff) + ldsw + _i * 8192), 16, 0, 0); } while (0)
; #define PG8_LDA(dst, b, h) do { _Pragma("unroll") for (int m = 0; m < 4; ++m) _Pragma("unroll") for (int k = 0; k < 2; ++k) dst[m][k] = *(const PG8_LAS bf16x8*)(lds + PG8_SA(b, h) + aoff + m * 2048 + k * 1024); } while (0)
; #define PG8_LDB(dst, b, h) do { _Pragma("unroll") for (int n = 0; n < 2; ++n) _Pragma("unroll") for (int k = 0; k < 2; ++k) dst[n][k] = *(const PG8_LAS bf16x8*)(lds + PG8_SB(b, h) + boff + n * 2048 + k * 1024); } while (0)
; #define PG8_MMA(ai, bj, At, Bt) do { __builtin_amdgcn_s_setprio(1); _Pragma("unroll") for (int m = 0; m < 4; ++m) _Pragma("unroll") for (int n = 0; n < 2; ++n) _Pragma("unroll") for (int k = 0; k < 2; ++k) \
;         acc[ai][bj][m][n] = __builtin_amdgcn_mfma_f32_16x16x32_bf16(Bt[n][k], At[m][k], acc[ai][bj][m][n], 0, 0, 0); __builtin_amdgcn_s_setprio(0); } while (0)
; #define PG8_BAR __builtin_amdgcn_s_barrier()
; template <class Epi, class Sched, bool ALIGN_EPI = false, bool SP2 = false>
; __device__ __forceinline__ void gemm_phase(PG8_LAS unsigned char* lds, const Gemm g, const Sched& S, const Epi& E) {
;     ...
;         const bool has_next = S.next(ui + 1, nxt);
;         const char* nA = has_next ? (const char*)g.A + (size_t)nxt.pm * tstep : cA; const char* nB = has_next ? (const char*)g.Bt + (size_t)nxt.pn * tstep : cB;
;         for (int t = 0; t < nt; t += 2) {
;             const bool last = (t == nt - 2);
;             const char* a1 = cA + (size_t)(t + 1) * kstep;
;             const char* a2 = last ? nA : cA + (size_t)(t + 2) * kstep; const char* b2 = last ? nB : cB + (size_t)(t + 2) * kstep;
;             const char* a3 = a2 + kstep; const char* b3 = b2 + kstep;
;             if (last && has_next) S.a_ready(nxt);
;             if constexpr (SP2) {
;             PG8_LDB(B0, 0, 0); PG8_LDB(B1, 0, 1); PG8_SCHED; PG8_LDA(At, 0, 0); PG8_STAGE(PG8_SA(1, 1), a1 + hstep, voffA);
;             PG8_WAIT_V(8); PG8_WAIT_L(0); PG8_BAR; PG8_MMA(0, 0, At, B0); PG8_MMA(0, 1, At, B1); PG8_BAR; PG8_SCHED;
;             PG8_LDA(At, 0, 1); PG8_STAGE(PG8_SB(0, 0), b2, voffB); PG8_STAGE(PG8_SB(0, 1), b2 + hstep, voffB); PG8_STAGE(PG8_SA(0, 0), a2, voffA);
.LBB0_552:
	s_ashr_i32 s35, s34, 31
	s_lshl_b64 s[36:37], s[34:35], 19
	s_add_u32 s36, s13, s36
	s_addc_u32 s37, s47, s37
	s_and_b64 s[40:41], s[38:39], exec
	s_cselect_b32 s35, s37, s51
	s_cselect_b32 s72, s36, s50
	s_ashr_i32 s31, s30, 31
	s_lshl_b64 s[40:41], s[30:31], 19
	s_add_u32 s40, s60, s40
	s_addc_u32 s41, s61, s41
	s_and_b64 s[54:55], s[38:39], exec
	s_cselect_b32 s31, s41, s53
	s_cselect_b32 s73, s40, s52
	s_add_u32 s50, s50, 0x40080
	s_addc_u32 s51, s51, 0
	s_add_u32 s74, s52, 0x100
	s_addc_u32 s75, s53, 0
	s_mov_b32 s76, -2
	s_waitcnt vmcnt(0)
	ds_read_b128 v[128:131], v181
	ds_read_b128 v[132:135], v181 offset:1024
	ds_read_b128 v[136:139], v181 offset:2048
	ds_read_b128 v[140:143], v181 offset:3072
	ds_read_b128 v[144:147], v182
	ds_read_b128 v[148:151], v182 offset:1024
	ds_read_b128 v[168:171], v182 offset:2048
	ds_read_b128 v[172:175], v182 offset:3072
	s_add_u32 s52, s50, 0xfffc0080
	s_addc_u32 s53, s51, -1
	s_cmp_eq_u32 s76, 12
	s_cselect_b32 s55, s35, s53
	s_cselect_b32 s54, s72, s52
	s_cselect_b32 s53, s31, s75
	s_cselect_b32 s52, s73, s74
	v_lshl_add_u64 v[176:177], s[50:51], 0, v[160:161]
	s_add_i32 m0, s63, 0xc000
	ds_read_b128 v[184:187], v183
	ds_read_b128 v[188:191], v183 offset:1024
	ds_read_b128 v[194:197], v183 offset:2048
	ds_read_b128 v[198:201], v183 offset:3072
	ds_read_b128 v[202:205], v183 offset:4096
	ds_read_b128 v[206:209], v183 offset:5120
	ds_read_b128 v[210:213], v183 offset:6144
	ds_read_b128 v[218:221], v183 offset:7168
	global_load_lds_dwordx4 v[176:177], off
	v_lshl_add_u64 v[176:177], s[50:51], 0, v[162:163]
	s_add_i32 m0, s63, 0xe000
	s_nop 0
	global_load_lds_dwordx4 v[176:177], off
	s_waitcnt vmcnt(8) lgkmcnt(0)
	s_setprio 1
	s_barrier
	v_mfma_f32_16x16x32_bf16 v[124:127], v[128:131], v[184:187], 0
	v_mfma_f32_16x16x32_bf16 v[120:123], v[136:139], v[184:187], 0
	v_mfma_f32_16x16x32_bf16 v[108:111], v[128:131], v[194:197], 0
	v_mfma_f32_16x16x32_bf16 v[104:107], v[136:139], v[194:197], 0
	v_mfma_f32_16x16x32_bf16 v[96:99], v[128:131], v[202:205], 0
	v_mfma_f32_16x16x32_bf16 v[88:91], v[136:139], v[202:205], 0
	v_mfma_f32_16x16x32_bf16 v[80:83], v[128:131], v[210:213], 0
	v_mfma_f32_16x16x32_bf16 v[72:75], v[136:139], v[210:213], 0
	v_mfma_f32_16x16x32_bf16 v[124:127], v[132:135], v[188:191], v[124:127]
	v_mfma_f32_16x16x32_bf16 v[120:123], v[140:143], v[188:191], v[120:123]
	v_mfma_f32_16x16x32_bf16 v[108:111], v[132:135], v[198:201], v[108:111]
	v_mfma_f32_16x16x32_bf16 v[104:107], v[140:143], v[198:201], v[104:107]
	v_mfma_f32_16x16x32_bf16 v[96:99], v[132:135], v[206:209], v[96:99]
	v_mfma_f32_16x16x32_bf16 v[88:91], v[140:143], v[206:209], v[88:91]
	v_mfma_f32_16x16x32_bf16 v[80:83], v[132:135], v[218:221], v[80:83]
	v_mfma_f32_16x16x32_bf16 v[72:75], v[140:143], v[218:221], v[72:75]
	v_mfma_f32_16x16x32_bf16 v[116:119], v[144:147], v[184:187], 0
	v_mfma_f32_16x16x32_bf16 v[112:115], v[168:171], v[184:187], 0
	v_mfma_f32_16x16x32_bf16 v[100:103], v[144:147], v[194:197], 0
	v_mfma_f32_16x16x32_bf16 v[92:95], v[168:171], v[194:197], 0
	v_mfma_f32_16x16x32_bf16 v[84:87], v[144:147], v[202:205], 0
	v_mfma_f32_16x16x32_bf16 v[76:79], v[168:171], v[202:205], 0
	v_mfma_f32_16x16x32_bf16 v[68:71], v[144:147], v[210:213], 0
	v_mfma_f32_16x16x32_bf16 v[64:67], v[168:171], v[210:213], 0
	v_mfma_f32_16x16x32_bf16 v[116:119], v[148:151], v[188:191], v[116:119]
	v_mfma_f32_16x16x32_bf16 v[112:115], v[172:175], v[188:191], v[112:115]
	v_mfma_f32_16x16x32_bf16 v[100:103], v[148:151], v[198:201], v[100:103]
	v_mfma_f32_16x16x32_bf16 v[92:95], v[172:175], v[198:201], v[92:95]
	v_mfma_f32_16x16x32_bf16 v[84:87], v[148:151], v[206:209], v[84:87]
	v_mfma_f32_16x16x32_bf16 v[76:79], v[172:175], v[206:209], v[76:79]
	v_mfma_f32_16x16x32_bf16 v[68:71], v[148:151], v[218:221], v[68:71]
	v_mfma_f32_16x16x32_bf16 v[64:67], v[172:175], v[218:221], v[64:67]
	s_barrier
	s_setprio 0
	s_add_i32 s77, s70, s62
	v_lshl_add_u64 v[176:177], s[52:53], 0, v[156:157]
	s_mov_b32 m0, s77
	ds_read_b128 v[184:187], v183 offset:16384
	ds_read_b128 v[188:191], v183 offset:17408
	ds_read_b128 v[194:197], v183 offset:18432
	ds_read_b128 v[198:201], v183 offset:19456
	ds_read_b128 v[202:205], v183 offset:20480
	ds_read_b128 v[206:209], v183 offset:21504
	ds_read_b128 v[210:213], v183 offset:22528
	ds_read_b128 v[218:221], v183 offset:23552
	global_load_lds_dwordx4 v[176:177], off
	s_add_i32 m0, s77, 0x2000
	s_add_u32 s78, s52, 0x40000
	v_lshl_add_u64 v[214:215], s[52:53], 0, v[152:153]
	s_addc_u32 s79, s53, 0
	s_add_i32 s77, s71, s62
	global_load_lds_dwordx4 v[214:215], off
	v_lshl_add_u64 v[222:223], s[78:79], 0, v[156:157]
	s_mov_b32 m0, s77
	v_lshl_add_u64 v[224:225], s[54:55], 0, v[154:155]
	global_load_lds_dwordx4 v[222:223], off
	v_lshl_add_u64 v[222:223], s[78:79], 0, v[152:153]
	s_add_i32 m0, s77, 0x2000
	s_nop 0
	global_load_lds_dwordx4 v[222:223], off
	v_lshl_add_u64 v[222:223], s[54:55], 0, v[158:159]
	s_mov_b32 m0, s63
	s_nop 0
	global_load_lds_dwordx4 v[222:223], off
	s_mov_b32 m0, s64
	s_nop 0
	global_load_lds_dwordx4 v[224:225], off
	s_waitcnt vmcnt(8) lgkmcnt(0)
	s_setprio 1
	s_barrier
; #define PG8_STAGE(bufoff, gbase, voff) do { _Pragma("unroll") for (int _i = 0; _i < 2; ++_i) \
;         __builtin_amdgcn_global_load_lds((const unsigned*)((const char*)(gbase) + (voff)[_i]), (PG8_LAS unsigned*)(lds + (bufoff) + ldsw + _i * 8192), 16, 0, 0); } while (0)
; #define PG8_LDA(dst, b, h) do { _Pragma("unroll") for (int m = 0; m < 4; ++m) _Pragma("unroll") for (int k = 0; k < 2; ++k) dst[m][k] = *(const PG8_LAS bf16x8*)(lds + PG8_SA(b, h) + aoff + m * 2048 + k * 1024); } while (0)
; #define PG8_LDB(dst, b, h) do { _Pragma("unroll") for (int n = 0; n < 2; ++n) _Pragma("unroll") for (int k = 0; k < 2; ++k) dst[n][k] = *(const PG8_LAS bf16x8*)(lds + PG8_SB(b, h) + boff + n * 2048 + k * 1024); } while (0)
; #define PG8_MMA(ai, bj, At, Bt) do { __builtin_amdgcn_s_setprio(1); _Pragma("unroll") for (int m = 0; m < 4; ++m) _Pragma("unroll") for (int n = 0; n < 2; ++n) _Pragma("unroll") for (int k = 0; k < 2; ++k) \
;         acc[ai][bj][m][n] = __builtin_amdgcn_mfma_f32_16x16x32_bf16(Bt[n][k], At[m][k], acc[ai][bj][m][n], 0, 0, 0); __builtin_amdgcn_s_setprio(0); } while (0)
; #define PG8_WAIT_V(n) asm volatile("s_waitcnt vmcnt(" #n ")" ::: "memory")
; #define PG8_WAIT_L(n) asm volatile("s_waitcnt lgkmcnt(" #n ")" ::: "memory")
; #define PG8_BAR __builtin_amdgcn_s_barrier()
; #define PG8_SCHED __builtin_amdgcn_sched_barrier(0)
; template <class Epi, class Sched, bool ALIGN_EPI = false, bool SP2 = false>
; __device__ __forceinline__ void gemm_phase(PG8_LAS unsigned char* lds, const Gemm g, const Sched& S, const Epi& E) {
;     ...
;             PG8_WAIT_V(8); PG8_WAIT_L(0); PG8_BAR; PG8_MMA(1, 0, At, B0); PG8_MMA(1, 1, At, B1); PG8_BAR; PG8_SCHED;
;             PG8_LDB(B0, 1, 0); PG8_LDB(B1, 1, 1); PG8_SCHED; PG8_LDA(At, 1, 0); PG8_STAGE(PG8_SA(0, 1), a2 + hstep, voffA);
;             PG8_WAIT_V(8); PG8_WAIT_L(0); PG8_BAR; PG8_MMA(0, 0, At, B0); PG8_MMA(0, 1, At, B1); PG8_BAR; PG8_SCHED;
	v_mfma_f32_16x16x32_bf16 v[60:63], v[128:131], v[184:187], 0
	v_mfma_f32_16x16x32_bf16 v[56:59], v[136:139], v[184:187], 0
	v_mfma_f32_16x16x32_bf16 v[48:51], v[128:131], v[194:197], 0
	v_mfma_f32_16x16x32_bf16 v[40:43], v[136:139], v[194:197], 0
	v_mfma_f32_16x16x32_bf16 v[32:35], v[128:131], v[202:205], 0
	v_mfma_f32_16x16x32_bf16 v[24:27], v[136:139], v[202:205], 0
	v_mfma_f32_16x16x32_bf16 v[16:19], v[128:131], v[210:213], 0
	v_mfma_f32_16x16x32_bf16 v[8:11], v[136:139], v[210:213], 0
	v_mfma_f32_16x16x32_bf16 v[60:63], v[132:135], v[188:191], v[60:63]
	v_mfma_f32_16x16x32_bf16 v[56:59], v[140:143], v[188:191], v[56:59]
	v_mfma_f32_16x16x32_bf16 v[48:51], v[132:135], v[198:201], v[48:51]
	v_mfma_f32_16x16x32_bf16 v[40:43], v[140:143], v[198:201], v[40:43]
	v_mfma_f32_16x16x32_bf16 v[32:35], v[132:135], v[206:209], v[32:35]
	v_mfma_f32_16x16x32_bf16 v[24:27], v[140:143], v[206:209], v[24:27]
	v_mfma_f32_16x16x32_bf16 v[16:19], v[132:135], v[218:221], v[16:19]
	v_mfma_f32_16x16x32_bf16 v[8:11], v[140:143], v[218:221], v[8:11]
	v_mfma_f32_16x16x32_bf16 v[52:55], v[144:147], v[184:187], 0
	v_mfma_f32_16x16x32_bf16 v[44:47], v[168:171], v[184:187], 0
	v_mfma_f32_16x16x32_bf16 v[36:39], v[144:147], v[194:197], 0
	v_mfma_f32_16x16x32_bf16 v[28:31], v[168:171], v[194:197], 0
	v_mfma_f32_16x16x32_bf16 v[20:23], v[144:147], v[202:205], 0
	v_mfma_f32_16x16x32_bf16 v[12:15], v[168:171], v[202:205], 0
	v_mfma_f32_16x16x32_bf16 v[4:7], v[144:147], v[210:213], 0
	v_mfma_f32_16x16x32_bf16 v[0:3], v[168:171], v[210:213], 0
	v_mfma_f32_16x16x32_bf16 v[52:55], v[148:151], v[188:191], v[52:55]
	v_mfma_f32_16x16x32_bf16 v[44:47], v[172:175], v[188:191], v[44:47]
	v_mfma_f32_16x16x32_bf16 v[36:39], v[148:151], v[198:201], v[36:39]
	v_mfma_f32_16x16x32_bf16 v[28:31], v[172:175], v[198:201], v[28:31]
	v_mfma_f32_16x16x32_bf16 v[20:23], v[148:151], v[206:209], v[20:23]
	v_mfma_f32_16x16x32_bf16 v[12:15], v[172:175], v[206:209], v[12:15]
	v_mfma_f32_16x16x32_bf16 v[4:7], v[148:151], v[218:221], v[4:7]
	v_mfma_f32_16x16x32_bf16 v[0:3], v[172:175], v[218:221], v[0:3]
	s_barrier
	s_setprio 0
	s_add_i32 s77, 0, 0x18000
	s_add_i32 s78, 0, 0x1c000
	v_add_u32_e32 v140, s77, v179
	v_add_u32_e32 v172, s78, v179
	ds_read_b128 v[128:131], v140
	ds_read_b128 v[132:135], v140 offset:1024
	ds_read_b128 v[136:139], v140 offset:2048
	ds_read_b128 v[140:143], v140 offset:3072
	ds_read_b128 v[144:147], v172
	ds_read_b128 v[148:151], v172 offset:1024
	ds_read_b128 v[168:171], v172 offset:2048
	ds_read_b128 v[172:175], v172 offset:3072
	s_add_u32 s54, s54, 0x40000
	s_addc_u32 s55, s55, 0
	s_mov_b32 m0, s65
	v_lshl_add_u64 v[226:227], s[54:55], 0, v[158:159]
	ds_read_b128 v[184:187], v183 offset:32768
	ds_read_b128 v[188:191], v183 offset:33792
	ds_read_b128 v[194:197], v183 offset:34816
	ds_read_b128 v[198:201], v183 offset:35840
	ds_read_b128 v[202:205], v183 offset:36864
	ds_read_b128 v[206:209], v183 offset:37888
	ds_read_b128 v[210:213], v183 offset:38912
	ds_read_b128 v[218:221], v183 offset:39936
	global_load_lds_dwordx4 v[226:227], off
	v_lshl_add_u64 v[226:227], s[54:55], 0, v[154:155]
	s_mov_b32 m0, s66
	s_nop 0
	global_load_lds_dwordx4 v[226:227], off
	s_waitcnt vmcnt(8) lgkmcnt(0)
	s_setprio 1
	s_barrier
	v_mfma_f32_16x16x32_bf16 v[124:127], v[128:131], v[184:187], v[124:127]
	v_mfma_f32_16x16x32_bf16 v[120:123], v[136:139], v[184:187], v[120:123]
	v_mfma_f32_16x16x32_bf16 v[108:111], v[128:131], v[194:197], v[108:111]
	v_mfma_f32_16x16x32_bf16 v[104:107], v[136:139], v[194:197], v[104:107]
	v_mfma_f32_16x16x32_bf16 v[96:99], v[128:131], v[202:205], v[96:99]
	v_mfma_f32_16x16x32_bf16 v[88:91], v[136:139], v[202:205], v[88:91]
	v_mfma_f32_16x16x32_bf16 v[80:83], v[128:131], v[210:213], v[80:83]
	v_mfma_f32_16x16x32_bf16 v[72:75], v[136:139], v[210:213], v[72:75]
	v_mfma_f32_16x16x32_bf16 v[124:127], v[132:135], v[188:191], v[124:127]
	v_mfma_f32_16x16x32_bf16 v[120:123], v[140:143], v[188:191], v[120:123]
	v_mfma_f32_16x16x32_bf16 v[108:111], v[132:135], v[198:201], v[108:111]
	v_mfma_f32_16x16x32_bf16 v[104:107], v[140:143], v[198:201], v[104:107]
	v_mfma_f32_16x16x32_bf16 v[96:99], v[132:135], v[206:209], v[96:99]
	v_mfma_f32_16x16x32_bf16 v[88:91], v[140:143], v[206:209], v[88:91]
	v_mfma_f32_16x16x32_bf16 v[80:83], v[132:135], v[218:221], v[80:83]
	v_mfma_f32_16x16x32_bf16 v[72:75], v[140:143], v[218:221], v[72:75]
	v_mfma_f32_16x16x32_bf16 v[116:119], v[144:147], v[184:187], v[116:119]
	v_mfma_f32_16x16x32_bf16 v[112:115], v[168:171], v[184:187], v[112:115]
	v_mfma_f32_16x16x32_bf16 v[100:103], v[144:147], v[194:197], v[100:103]
	v_mfma_f32_16x16x32_bf16 v[92:95], v[168:171], v[194:197], v[92:95]
	v_mfma_f32_16x16x32_bf16 v[84:87], v[144:147], v[202:205], v[84:87]
	v_mfma_f32_16x16x32_bf16 v[76:79], v[168:171], v[202:205], v[76:79]
	v_mfma_f32_16x16x32_bf16 v[68:71], v[144:147], v[210:213], v[68:71]
	v_mfma_f32_16x16x32_bf16 v[64:67], v[168:171], v[210:213], v[64:67]
	v_mfma_f32_16x16x32_bf16 v[116:119], v[148:151], v[188:191], v[116:119]
	v_mfma_f32_16x16x32_bf16 v[112:115], v[172:175], v[188:191], v[112:115]
	v_mfma_f32_16x16x32_bf16 v[100:103], v[148:151], v[198:201], v[100:103]
	v_mfma_f32_16x16x32_bf16 v[92:95], v[172:175], v[198:201], v[92:95]
	v_mfma_f32_16x16x32_bf16 v[84:87], v[148:151], v[206:209], v[84:87]
	v_mfma_f32_16x16x32_bf16 v[76:79], v[172:175], v[206:209], v[76:79]
	v_mfma_f32_16x16x32_bf16 v[68:71], v[148:151], v[218:221], v[68:71]
	v_mfma_f32_16x16x32_bf16 v[64:67], v[172:175], v[218:221], v[64:67]
	s_barrier
; #define PG8_STAGE(bufoff, gbase, voff) do { _Pragma("unroll") for (int _i = 0; _i < 2; ++_i) \
;         __builtin_amdgcn_global_load_lds((const unsigned*)((const char*)(gbase) + (voff)[_i]), (PG8_LAS unsigned*)(lds + (bufoff) + ldsw + _i * 8192), 16, 0, 0); } while (0)
; #define PG8_LDA(dst, b, h) do { _Pragma("unroll") for (int m = 0; m < 4; ++m) _Pragma("unroll") for (int k = 0; k < 2; ++k) dst[m][k] = *(const PG8_LAS bf16x8*)(lds + PG8_SA(b, h) + aoff + m * 2048 + k * 1024); } while (0)
; #define PG8_LDB(dst, b, h) do { _Pragma("unroll") for (int n = 0; n < 2; ++n) _Pragma("unroll") for (int k = 0; k < 2; ++k) dst[n][k] = *(const PG8_LAS bf16x8*)(lds + PG8_SB(b, h) + boff + n * 2048 + k * 1024); } while (0)
; #define PG8_MMA(ai, bj, At, Bt) do { __builtin_amdgcn_s_setprio(1); _Pragma("unroll") for (int m = 0; m < 4; ++m) _Pragma("unroll") for (int n = 0; n < 2; ++n) _Pragma("unroll") for (int k = 0; k < 2; ++k) \
;         acc[ai][bj][m][n] = __builtin_amdgcn_mfma_f32_16x16x32_bf16(Bt[n][k], At[m][k], acc[ai][bj][m][n], 0, 0, 0); __builtin_amdgcn_s_setprio(0); } while (0)
; #define PG8_WAIT_V(n) asm volatile("s_waitcnt vmcnt(" #n ")" ::: "memory")
; template <class Epi, class Sched, bool ALIGN_EPI = false, bool SP2 = false>
; __device__ __forceinline__ void gemm_phase(PG8_LAS unsigned char* lds, const Gemm g, const Sched& S, const Epi& E) {
;     ...
;             PG8_LDB(B0, 0, 0); PG8_LDB(B1, 0, 1); PG8_SCHED; PG8_LDA(At, 0, 0); PG8_STAGE(PG8_SA(1, 1), a1 + hstep, voffA);
;             PG8_WAIT_V(8); PG8_WAIT_L(0); PG8_BAR; PG8_MMA(0, 0, At, B0); PG8_MMA(0, 1, At, B1); PG8_BAR; PG8_SCHED;
;             PG8_LDA(At, 0, 1); PG8_STAGE(PG8_SB(0, 0), b2, voffB); PG8_STAGE(PG8_SB(0, 1), b2 + hstep, voffB); PG8_STAGE(PG8_SA(0, 0), a2, voffA);
;             PG8_WAIT_V(8); PG8_WAIT_L(0); PG8_BAR; PG8_MMA(1, 0, At, B0); PG8_MMA(1, 1, At, B1); PG8_BAR; PG8_SCHED;
;             PG8_LDB(B0, 1, 0); PG8_LDB(B1, 1, 1); PG8_SCHED; PG8_LDA(At, 1, 0); PG8_STAGE(PG8_SA(0, 1), a2 + hstep, voffA);
;             PG8_WAIT_V(8); PG8_WAIT_L(0); PG8_BAR; PG8_MMA(0, 0, At, B0); PG8_MMA(0, 1, At, B1); PG8_BAR; PG8_SCHED;
;             PG8_LDA(At, 1, 1); PG8_STAGE(PG8_SB(1, 0), b3, voffB); PG8_STAGE(PG8_SB(1, 1), b3 + hstep, voffB); PG8_STAGE(PG8_SA(1, 0), a3, voffA);
;             PG8_WAIT_V(8); PG8_WAIT_L(0); PG8_BAR; PG8_MMA(1, 0, At, B0); PG8_MMA(1, 1, At, B1); PG8_BAR; PG8_SCHED;
	s_setprio 0
	s_add_i32 s54, s77, s62
	v_lshl_add_u64 v[176:177], v[176:177], 0, s[26:27]
	s_mov_b32 m0, s54
	ds_read_b128 v[184:187], v183 offset:49152
	ds_read_b128 v[188:191], v183 offset:50176
	ds_read_b128 v[194:197], v183 offset:51200
	ds_read_b128 v[198:201], v183 offset:52224
	ds_read_b128 v[202:205], v183 offset:53248
	ds_read_b128 v[206:209], v183 offset:54272
	ds_read_b128 v[210:213], v183 offset:55296
	ds_read_b128 v[218:221], v183 offset:56320
	global_load_lds_dwordx4 v[176:177], off
	s_add_i32 m0, s54, 0x2000
	s_add_u32 s52, s52, 0x40080
	v_lshl_add_u64 v[176:177], v[214:215], 0, s[26:27]
	s_addc_u32 s53, s53, 0
	s_add_i32 s54, s78, s62
	global_load_lds_dwordx4 v[176:177], off
	v_lshl_add_u64 v[176:177], s[52:53], 0, v[156:157]
	s_mov_b32 m0, s54
	s_nop 0
	global_load_lds_dwordx4 v[176:177], off
	v_lshl_add_u64 v[176:177], s[52:53], 0, v[152:153]
	s_add_i32 m0, s54, 0x2000
	s_nop 0
	global_load_lds_dwordx4 v[176:177], off
	v_lshl_add_u64 v[176:177], v[222:223], 0, s[26:27]
	s_mov_b32 m0, s68
	s_nop 0
	global_load_lds_dwordx4 v[176:177], off
	v_lshl_add_u64 v[176:177], v[224:225], 0, s[26:27]
	s_mov_b32 m0, s69
	s_nop 0
	global_load_lds_dwordx4 v[176:177], off
	s_waitcnt vmcnt(8) lgkmcnt(0)
	s_setprio 1
	s_barrier
	v_mfma_f32_16x16x32_bf16 v[60:63], v[128:131], v[184:187], v[60:63]
	v_mfma_f32_16x16x32_bf16 v[56:59], v[136:139], v[184:187], v[56:59]
	v_mfma_f32_16x16x32_bf16 v[48:51], v[128:131], v[194:197], v[48:51]
	v_mfma_f32_16x16x32_bf16 v[40:43], v[136:139], v[194:197], v[40:43]
	v_mfma_f32_16x16x32_bf16 v[32:35], v[128:131], v[202:205], v[32:35]
	v_mfma_f32_16x16x32_bf16 v[24:27], v[136:139], v[202:205], v[24:27]
	v_mfma_f32_16x16x32_bf16 v[16:19], v[128:131], v[210:213], v[16:19]
	v_mfma_f32_16x16x32_bf16 v[8:11], v[136:139], v[210:213], v[8:11]
	v_mfma_f32_16x16x32_bf16 v[60:63], v[132:135], v[188:191], v[60:63]
	v_mfma_f32_16x16x32_bf16 v[56:59], v[140:143], v[188:191], v[56:59]
	v_mfma_f32_16x16x32_bf16 v[48:51], v[132:135], v[198:201], v[48:51]
	v_mfma_f32_16x16x32_bf16 v[40:43], v[140:143], v[198:201], v[40:43]
	v_mfma_f32_16x16x32_bf16 v[32:35], v[132:135], v[206:209], v[32:35]
	v_mfma_f32_16x16x32_bf16 v[24:27], v[140:143], v[206:209], v[24:27]
	v_mfma_f32_16x16x32_bf16 v[16:19], v[132:135], v[218:221], v[16:19]
	v_mfma_f32_16x16x32_bf16 v[8:11], v[140:143], v[218:221], v[8:11]
	v_mfma_f32_16x16x32_bf16 v[52:55], v[144:147], v[184:187], v[52:55]
	v_mfma_f32_16x16x32_bf16 v[44:47], v[168:171], v[184:187], v[44:47]
	v_mfma_f32_16x16x32_bf16 v[36:39], v[144:147], v[194:197], v[36:39]
	v_mfma_f32_16x16x32_bf16 v[28:31], v[168:171], v[194:197], v[28:31]
	v_mfma_f32_16x16x32_bf16 v[20:23], v[144:147], v[202:205], v[20:23]
	v_mfma_f32_16x16x32_bf16 v[12:15], v[168:171], v[202:205], v[12:15]
	v_mfma_f32_16x16x32_bf16 v[4:7], v[144:147], v[210:213], v[4:7]
	v_mfma_f32_16x16x32_bf16 v[0:3], v[168:171], v[210:213], v[0:3]
	v_mfma_f32_16x16x32_bf16 v[52:55], v[148:151], v[188:191], v[52:55]
	v_mfma_f32_16x16x32_bf16 v[44:47], v[172:175], v[188:191], v[44:47]
	v_mfma_f32_16x16x32_bf16 v[36:39], v[148:151], v[198:201], v[36:39]
	v_mfma_f32_16x16x32_bf16 v[28:31], v[172:175], v[198:201], v[28:31]
	v_mfma_f32_16x16x32_bf16 v[20:23], v[148:151], v[206:209], v[20:23]
	v_mfma_f32_16x16x32_bf16 v[12:15], v[172:175], v[206:209], v[12:15]
	v_mfma_f32_16x16x32_bf16 v[4:7], v[148:151], v[218:221], v[4:7]
	v_mfma_f32_16x16x32_bf16 v[0:3], v[172:175], v[218:221], v[0:3]
	s_barrier
	s_setprio 0
	s_add_i32 s76, s76, 2
	s_add_u32 s50, s50, 0x100
	s_addc_u32 s51, s51, 0
	s_add_u32 s74, s74, 0x100
	s_addc_u32 s75, s75, 0
	s_cmp_gt_u32 s76, 13
.LBB0_553:
	ds_read_b128 v[128:131], v181
	ds_read_b128 v[132:135], v181 offset:1024
	ds_read_b128 v[136:139], v181 offset:2048
	ds_read_b128 v[140:143], v181 offset:3072
	ds_read_b128 v[144:147], v182
	ds_read_b128 v[148:151], v182 offset:1024
	ds_read_b128 v[168:171], v182 offset:2048
	ds_read_b128 v[172:175], v182 offset:3072
	s_add_u32 s52, s50, 0xfffc0080
	s_addc_u32 s53, s51, -1
	s_cmp_eq_u32 s76, 12
	s_cselect_b32 s55, s35, s53
	s_cselect_b32 s54, s72, s52
	s_cselect_b32 s53, s31, s75
	s_cselect_b32 s52, s73, s74
	v_lshl_add_u64 v[176:177], s[50:51], 0, v[160:161]
	s_add_i32 m0, s63, 0xc000
	ds_read_b128 v[184:187], v183
	ds_read_b128 v[188:191], v183 offset:1024
	ds_read_b128 v[194:197], v183 offset:2048
	ds_read_b128 v[198:201], v183 offset:3072
	ds_read_b128 v[202:205], v183 offset:4096
	ds_read_b128 v[206:209], v183 offset:5120
	ds_read_b128 v[210:213], v183 offset:6144
	ds_read_b128 v[218:221], v183 offset:7168
	global_load_lds_dwordx4 v[176:177], off
	v_lshl_add_u64 v[176:177], s[50:51], 0, v[162:163]
	s_add_i32 m0, s63, 0xe000
	s_nop 0
	global_load_lds_dwordx4 v[176:177], off
	s_waitcnt vmcnt(8) lgkmcnt(0)
	s_setprio 1
	s_barrier
; #define PG8_STAGE(bufoff, gbase, voff) do { _Pragma("unroll") for (int _i = 0; _i < 2; ++_i) \
;         __builtin_amdgcn_global_load_lds((const unsigned*)((const char*)(gbase) + (voff)[_i]), (PG8_LAS unsigned*)(lds + (bufoff) + ldsw + _i * 8192), 16, 0, 0); } while (0)
; #define PG8_LDA(dst, b, h) do { _Pragma("unroll") for (int m = 0; m < 4; ++m) _Pragma("unroll") for (int k = 0; k < 2; ++k) dst[m][k] = *(const PG8_LAS bf16x8*)(lds + PG8_SA(b, h) + aoff + m * 2048 + k * 1024); } while (0)
; #define PG8_MMA(ai, bj, At, Bt) do { __builtin_amdgcn_s_setprio(1); _Pragma("unroll") for (int m = 0; m < 4; ++m) _Pragma("unroll") for (int n = 0; n < 2; ++n) _Pragma("unroll") for (int k = 0; k < 2; ++k) \
;         acc[ai][bj][m][n] = __builtin_amdgcn_mfma_f32_16x16x32_bf16(Bt[n][k], At[m][k], acc[ai][bj][m][n], 0, 0, 0); __builtin_amdgcn_s_setprio(0); } while (0)
; #define PG8_WAIT_V(n) asm volatile("s_waitcnt vmcnt(" #n ")" ::: "memory")
; #define PG8_WAIT_L(n) asm volatile("s_waitcnt lgkmcnt(" #n ")" ::: "memory")
; #define PG8_BAR __builtin_amdgcn_s_barrier()
; #define PG8_SCHED __builtin_amdgcn_sched_barrier(0)
; template <class Epi, class Sched, bool ALIGN_EPI = false, bool SP2 = false>
; __device__ __forceinline__ void gemm_phase(PG8_LAS unsigned char* lds, const Gemm g, const Sched& S, const Epi& E) {
;     ...
;             PG8_WAIT_V(8); PG8_WAIT_L(0); PG8_BAR; PG8_MMA(0, 0, At, B0); PG8_MMA(0, 1, At, B1); PG8_BAR; PG8_SCHED;
;             PG8_LDA(At, 0, 1); PG8_STAGE(PG8_SB(0, 0), b2, voffB); PG8_STAGE(PG8_SB(0, 1), b2 + hstep, voffB); PG8_STAGE(PG8_SA(0, 0), a2, voffA);
;             PG8_WAIT_V(8); PG8_WAIT_L(0); PG8_BAR; PG8_MMA(1, 0, At, B0); PG8_MMA(1, 1, At, B1); PG8_BAR; PG8_SCHED;
	v_mfma_f32_16x16x32_bf16 v[124:127], v[128:131], v[184:187], v[124:127]
	v_mfma_f32_16x16x32_bf16 v[120:123], v[136:139], v[184:187], v[120:123]
	v_mfma_f32_16x16x32_bf16 v[108:111], v[128:131], v[194:197], v[108:111]
	v_mfma_f32_16x16x32_bf16 v[104:107], v[136:139], v[194:197], v[104:107]
	v_mfma_f32_16x16x32_bf16 v[96:99], v[128:131], v[202:205], v[96:99]
	v_mfma_f32_16x16x32_bf16 v[88:91], v[136:139], v[202:205], v[88:91]
	v_mfma_f32_16x16x32_bf16 v[80:83], v[128:131], v[210:213], v[80:83]
	v_mfma_f32_16x16x32_bf16 v[72:75], v[136:139], v[210:213], v[72:75]
	v_mfma_f32_16x16x32_bf16 v[124:127], v[132:135], v[188:191], v[124:127]
	v_mfma_f32_16x16x32_bf16 v[120:123], v[140:143], v[188:191], v[120:123]
	v_mfma_f32_16x16x32_bf16 v[108:111], v[132:135], v[198:201], v[108:111]
	v_mfma_f32_16x16x32_bf16 v[104:107], v[140:143], v[198:201], v[104:107]
	v_mfma_f32_16x16x32_bf16 v[96:99], v[132:135], v[206:209], v[96:99]
	v_mfma_f32_16x16x32_bf16 v[88:91], v[140:143], v[206:209], v[88:91]
	v_mfma_f32_16x16x32_bf16 v[80:83], v[132:135], v[218:221], v[80:83]
	v_mfma_f32_16x16x32_bf16 v[72:75], v[140:143], v[218:221], v[72:75]
	v_mfma_f32_16x16x32_bf16 v[116:119], v[144:147], v[184:187], v[116:119]
	v_mfma_f32_16x16x32_bf16 v[112:115], v[168:171], v[184:187], v[112:115]
	v_mfma_f32_16x16x32_bf16 v[100:103], v[144:147], v[194:197], v[100:103]
	v_mfma_f32_16x16x32_bf16 v[92:95], v[168:171], v[194:197], v[92:95]
	v_mfma_f32_16x16x32_bf16 v[84:87], v[144:147], v[202:205], v[84:87]
	v_mfma_f32_16x16x32_bf16 v[76:79], v[168:171], v[202:205], v[76:79]
	v_mfma_f32_16x16x32_bf16 v[68:71], v[144:147], v[210:213], v[68:71]
	v_mfma_f32_16x16x32_bf16 v[64:67], v[168:171], v[210:213], v[64:67]
	v_mfma_f32_16x16x32_bf16 v[116:119], v[148:151], v[188:191], v[116:119]
	v_mfma_f32_16x16x32_bf16 v[112:115], v[172:175], v[188:191], v[112:115]
	v_mfma_f32_16x16x32_bf16 v[100:103], v[148:151], v[198:201], v[100:103]
	v_mfma_f32_16x16x32_bf16 v[92:95], v[172:175], v[198:201], v[92:95]
	v_mfma_f32_16x16x32_bf16 v[84:87], v[148:151], v[206:209], v[84:87]
	v_mfma_f32_16x16x32_bf16 v[76:79], v[172:175], v[206:209], v[76:79]
	v_mfma_f32_16x16x32_bf16 v[68:71], v[148:151], v[218:221], v[68:71]
	v_mfma_f32_16x16x32_bf16 v[64:67], v[172:175], v[218:221], v[64:67]
	s_barrier
	s_setprio 0
	s_add_i32 s77, s70, s62
	v_lshl_add_u64 v[176:177], s[52:53], 0, v[156:157]
	s_mov_b32 m0, s77
	ds_read_b128 v[184:187], v183 offset:16384
	ds_read_b128 v[188:191], v183 offset:17408
	ds_read_b128 v[194:197], v183 offset:18432
	ds_read_b128 v[198:201], v183 offset:19456
	ds_read_b128 v[202:205], v183 offset:20480
	ds_read_b128 v[206:209], v183 offset:21504
	ds_read_b128 v[210:213], v183 offset:22528
	ds_read_b128 v[218:221], v183 offset:23552
	global_load_lds_dwordx4 v[176:177], off
	s_add_i32 m0, s77, 0x2000
	s_add_u32 s78, s52, 0x40000
	v_lshl_add_u64 v[214:215], s[52:53], 0, v[152:153]
	s_addc_u32 s79, s53, 0
	s_add_i32 s77, s71, s62
	global_load_lds_dwordx4 v[214:215], off
	v_lshl_add_u64 v[222:223], s[78:79], 0, v[156:157]
	s_mov_b32 m0, s77
	v_lshl_add_u64 v[224:225], s[54:55], 0, v[154:155]
	global_load_lds_dwordx4 v[222:223], off
	v_lshl_add_u64 v[222:223], s[78:79], 0, v[152:153]
	s_add_i32 m0, s77, 0x2000
	s_nop 0
	global_load_lds_dwordx4 v[222:223], off
	v_lshl_add_u64 v[222:223], s[54:55], 0, v[158:159]
	s_mov_b32 m0, s63
	s_nop 0
	global_load_lds_dwordx4 v[222:223], off
	s_mov_b32 m0, s64
	s_nop 0
	global_load_lds_dwordx4 v[224:225], off
	s_waitcnt vmcnt(8) lgkmcnt(0)
	s_setprio 1
	s_barrier
	v_mfma_f32_16x16x32_bf16 v[60:63], v[128:131], v[184:187], v[60:63]
	v_mfma_f32_16x16x32_bf16 v[56:59], v[136:139], v[184:187], v[56:59]
	v_mfma_f32_16x16x32_bf16 v[48:51], v[128:131], v[194:197], v[48:51]
	v_mfma_f32_16x16x32_bf16 v[40:43], v[136:139], v[194:197], v[40:43]
	v_mfma_f32_16x16x32_bf16 v[32:35], v[128:131], v[202:205], v[32:35]
	v_mfma_f32_16x16x32_bf16 v[24:27], v[136:139], v[202:205], v[24:27]
	v_mfma_f32_16x16x32_bf16 v[16:19], v[128:131], v[210:213], v[16:19]
	v_mfma_f32_16x16x32_bf16 v[8:11], v[136:139], v[210:213], v[8:11]
	v_mfma_f32_16x16x32_bf16 v[60:63], v[132:135], v[188:191], v[60:63]
	v_mfma_f32_16x16x32_bf16 v[56:59], v[140:143], v[188:191], v[56:59]
	v_mfma_f32_16x16x32_bf16 v[48:51], v[132:135], v[198:201], v[48:51]
	v_mfma_f32_16x16x32_bf16 v[40:43], v[140:143], v[198:201], v[40:43]
	v_mfma_f32_16x16x32_bf16 v[32:35], v[132:135], v[206:209], v[32:35]
	v_mfma_f32_16x16x32_bf16 v[24:27], v[140:143], v[206:209], v[24:27]
	v_mfma_f32_16x16x32_bf16 v[16:19], v[132:135], v[218:221], v[16:19]
	v_mfma_f32_16x16x32_bf16 v[8:11], v[140:143], v[218:221], v[8:11]
	v_mfma_f32_16x16x32_bf16 v[52:55], v[144:147], v[184:187], v[52:55]
	v_mfma_f32_16x16x32_bf16 v[44:47], v[168:171], v[184:187], v[44:47]
	v_mfma_f32_16x16x32_bf16 v[36:39], v[144:147], v[194:197], v[36:39]
	v_mfma_f32_16x16x32_bf16 v[28:31], v[168:171], v[194:197], v[28:31]
	v_mfma_f32_16x16x32_bf16 v[20:23], v[144:147], v[202:205], v[20:23]
	v_mfma_f32_16x16x32_bf16 v[12:15], v[168:171], v[202:205], v[12:15]
	v_mfma_f32_16x16x32_bf16 v[4:7], v[144:147], v[210:213], v[4:7]
	v_mfma_f32_16x16x32_bf16 v[0:3], v[168:171], v[210:213], v[0:3]
	v_mfma_f32_16x16x32_bf16 v[52:55], v[148:151], v[188:191], v[52:55]
	v_mfma_f32_16x16x32_bf16 v[44:47], v[172:175], v[188:191], v[44:47]
	v_mfma_f32_16x16x32_bf16 v[36:39], v[148:151], v[198:201], v[36:39]
	v_mfma_f32_16x16x32_bf16 v[28:31], v[172:175], v[198:201], v[28:31]
	v_mfma_f32_16x16x32_bf16 v[20:23], v[148:151], v[206:209], v[20:23]
	v_mfma_f32_16x16x32_bf16 v[12:15], v[172:175], v[206:209], v[12:15]
	v_mfma_f32_16x16x32_bf16 v[4:7], v[148:151], v[218:221], v[4:7]
	v_mfma_f32_16x16x32_bf16 v[0:3], v[172:175], v[218:221], v[0:3]
	s_barrier
; #define PG8_STAGE(bufoff, gbase, voff) do { _Pragma("unroll") for (int _i = 0; _i < 2; ++_i) \
;         __builtin_amdgcn_global_load_lds((const unsigned*)((const char*)(gbase) + (voff)[_i]), (PG8_LAS unsigned*)(lds + (bufoff) + ldsw + _i * 8192), 16, 0, 0); } while (0)
; #define PG8_LDA(dst, b, h) do { _Pragma("unroll") for (int m = 0; m < 4; ++m) _Pragma("unroll") for (int k = 0; k < 2; ++k) dst[m][k] = *(const PG8_LAS bf16x8*)(lds + PG8_SA(b, h) + aoff + m * 2048 + k * 1024); } while (0)
; #define PG8_LDB(dst, b, h) do { _Pragma("unroll") for (int n = 0; n < 2; ++n) _Pragma("unroll") for (int k = 0; k < 2; ++k) dst[n][k] = *(const PG8_LAS bf16x8*)(lds + PG8_SB(b, h) + boff + n * 2048 + k * 1024); } while (0)
; #define PG8_MMA(ai, bj, At, Bt) do { __builtin_amdgcn_s_setprio(1); _Pragma("unroll") for (int m = 0; m < 4; ++m) _Pragma("unroll") for (int n = 0; n < 2; ++n) _Pragma("unroll") for (int k = 0; k < 2; ++k) \
;         acc[ai][bj][m][n] = __builtin_amdgcn_mfma_f32_16x16x32_bf16(Bt[n][k], At[m][k], acc[ai][bj][m][n], 0, 0, 0); __builtin_amdgcn_s_setprio(0); } while (0)
; #define PG8_WAIT_V(n) asm volatile("s_waitcnt vmcnt(" #n ")" ::: "memory")
; #define PG8_WAIT_L(n) asm volatile("s_waitcnt lgkmcnt(" #n ")" ::: "memory")
; #define PG8_BAR __builtin_amdgcn_s_barrier()
; #define PG8_SCHED __builtin_amdgcn_sched_barrier(0)
; template <class Epi, class Sched, bool ALIGN_EPI = false, bool SP2 = false>
; __device__ __forceinline__ void gemm_phase(PG8_LAS unsigned char* lds, const Gemm g, const Sched& S, const Epi& E) {
;     ...
;             PG8_LDB(B0, 1, 0); PG8_LDB(B1, 1, 1); PG8_SCHED; PG8_LDA(At, 1, 0); PG8_STAGE(PG8_SA(0, 1), a2 + hstep, voffA);
;             PG8_WAIT_V(8); PG8_WAIT_L(0); PG8_BAR; PG8_MMA(0, 0, At, B0); PG8_MMA(0, 1, At, B1); PG8_BAR; PG8_SCHED;
	s_setprio 0
	s_add_i32 s77, 0, 0x18000
	s_add_i32 s78, 0, 0x1c000
	v_add_u32_e32 v140, s77, v179
	v_add_u32_e32 v172, s78, v179
	ds_read_b128 v[128:131], v140
	ds_read_b128 v[132:135], v140 offset:1024
	ds_read_b128 v[136:139], v140 offset:2048
	ds_read_b128 v[140:143], v140 offset:3072
	ds_read_b128 v[144:147], v172
	ds_read_b128 v[148:151], v172 offset:1024
	ds_read_b128 v[168:171], v172 offset:2048
	ds_read_b128 v[172:175], v172 offset:3072
	s_add_u32 s54, s54, 0x40000
	s_addc_u32 s55, s55, 0
	s_mov_b32 m0, s65
	v_lshl_add_u64 v[226:227], s[54:55], 0, v[158:159]
	ds_read_b128 v[184:187], v183 offset:32768
	ds_read_b128 v[188:191], v183 offset:33792
	ds_read_b128 v[194:197], v183 offset:34816
	ds_read_b128 v[198:201], v183 offset:35840
	ds_read_b128 v[202:205], v183 offset:36864
	ds_read_b128 v[206:209], v183 offset:37888
	ds_read_b128 v[210:213], v183 offset:38912
	ds_read_b128 v[218:221], v183 offset:39936
	global_load_lds_dwordx4 v[226:227], off
	v_lshl_add_u64 v[226:227], s[54:55], 0, v[154:155]
	s_mov_b32 m0, s66
	s_nop 0
	global_load_lds_dwordx4 v[226:227], off
	s_waitcnt vmcnt(8) lgkmcnt(0)
	s_setprio 1
	s_barrier
	v_mfma_f32_16x16x32_bf16 v[124:127], v[128:131], v[184:187], v[124:127]
	v_mfma_f32_16x16x32_bf16 v[120:123], v[136:139], v[184:187], v[120:123]
	v_mfma_f32_16x16x32_bf16 v[108:111], v[128:131], v[194:197], v[108:111]
	v_mfma_f32_16x16x32_bf16 v[104:107], v[136:139], v[194:197], v[104:107]
	v_mfma_f32_16x16x32_bf16 v[96:99], v[128:131], v[202:205], v[96:99]
	v_mfma_f32_16x16x32_bf16 v[88:91], v[136:139], v[202:205], v[88:91]
	v_mfma_f32_16x16x32_bf16 v[80:83], v[128:131], v[210:213], v[80:83]
	v_mfma_f32_16x16x32_bf16 v[72:75], v[136:139], v[210:213], v[72:75]
	v_mfma_f32_16x16x32_bf16 v[124:127], v[132:135], v[188:191], v[124:127]
	v_mfma_f32_16x16x32_bf16 v[120:123], v[140:143], v[188:191], v[120:123]
	v_mfma_f32_16x16x32_bf16 v[108:111], v[132:135], v[198:201], v[108:111]
	v_mfma_f32_16x16x32_bf16 v[104:107], v[140:143], v[198:201], v[104:107]
	v_mfma_f32_16x16x32_bf16 v[96:99], v[132:135], v[206:209], v[96:99]
	v_mfma_f32_16x16x32_bf16 v[88:91], v[140:143], v[206:209], v[88:91]
	v_mfma_f32_16x16x32_bf16 v[80:83], v[132:135], v[218:221], v[80:83]
	v_mfma_f32_16x16x32_bf16 v[72:75], v[140:143], v[218:221], v[72:75]
	v_mfma_f32_16x16x32_bf16 v[116:119], v[144:147], v[184:187], v[116:119]
	v_mfma_f32_16x16x32_bf16 v[112:115], v[168:171], v[184:187], v[112:115]
	v_mfma_f32_16x16x32_bf16 v[100:103], v[144:147], v[194:197], v[100:103]
	v_mfma_f32_16x16x32_bf16 v[92:95], v[168:171], v[194:197], v[92:95]
	v_mfma_f32_16x16x32_bf16 v[84:87], v[144:147], v[202:205], v[84:87]
	v_mfma_f32_16x16x32_bf16 v[76:79], v[168:171], v[202:205], v[76:79]
	v_mfma_f32_16x16x32_bf16 v[68:71], v[144:147], v[210:213], v[68:71]
	v_mfma_f32_16x16x32_bf16 v[64:67], v[168:171], v[210:213], v[64:67]
	v_mfma_f32_16x16x32_bf16 v[116:119], v[148:151], v[188:191], v[116:119]
	v_mfma_f32_16x16x32_bf16 v[112:115], v[172:175], v[188:191], v[112:115]
	v_mfma_f32_16x16x32_bf16 v[100:103], v[148:151], v[198:201], v[100:103]
	v_mfma_f32_16x16x32_bf16 v[92:95], v[172:175], v[198:201], v[92:95]
	v_mfma_f32_16x16x32_bf16 v[84:87], v[148:151], v[206:209], v[84:87]
	v_mfma_f32_16x16x32_bf16 v[76:79], v[172:175], v[206:209], v[76:79]
	v_mfma_f32_16x16x32_bf16 v[68:71], v[148:151], v[218:221], v[68:71]
	v_mfma_f32_16x16x32_bf16 v[64:67], v[172:175], v[218:221], v[64:67]
	s_barrier
; #define PG8_STAGE(bufoff, gbase, voff) do { _Pragma("unroll") for (int _i = 0; _i < 2; ++_i) \
;         __builtin_amdgcn_global_load_lds((const unsigned*)((const char*)(gbase) + (voff)[_i]), (PG8_LAS unsigned*)(lds + (bufoff) + ldsw + _i * 8192), 16, 0, 0); } while (0)
; #define PG8_LDA(dst, b, h) do { _Pragma("unroll") for (int m = 0; m < 4; ++m) _Pragma("unroll") for (int k = 0; k < 2; ++k) dst[m][k] = *(const PG8_LAS bf16x8*)(lds + PG8_SA(b, h) + aoff + m * 2048 + k * 1024); } while (0)
; #define PG8_MMA(ai, bj, At, Bt) do { __builtin_amdgcn_s_setprio(1); _Pragma("unroll") for (int m = 0; m < 4; ++m) _Pragma("unroll") for (int n = 0; n < 2; ++n) _Pragma("unroll") for (int k = 0; k < 2; ++k) \
;         acc[ai][bj][m][n] = __builtin_amdgcn_mfma_f32_16x16x32_bf16(Bt[n][k], At[m][k], acc[ai][bj][m][n], 0, 0, 0); __builtin_amdgcn_s_setprio(0); } while (0)
; #define PG8_WAIT_V(n) asm volatile("s_waitcnt vmcnt(" #n ")" ::: "memory")
; #define PG8_WAIT_L(n) asm volatile("s_waitcnt lgkmcnt(" #n ")" ::: "memory")
; #define PG8_BAR __builtin_amdgcn_s_barrier()
; #define PG8_SCHED __builtin_amdgcn_sched_barrier(0)
; template <class Epi, class Sched, bool ALIGN_EPI = false, bool SP2 = false>
; __device__ __forceinline__ void gemm_phase(PG8_LAS unsigned char* lds, const Gemm g, const Sched& S, const Epi& E) {
;     ...
;             PG8_LDA(At, 1, 1); PG8_STAGE(PG8_SB(1, 0), b3, voffB); PG8_STAGE(PG8_SB(1, 1), b3 + hstep, voffB); PG8_STAGE(PG8_SA(1, 0), a3, voffA);
;             PG8_WAIT_V(8); PG8_WAIT_L(0); PG8_BAR; PG8_MMA(1, 0, At, B0); PG8_MMA(1, 1, At, B1); PG8_BAR; PG8_SCHED;
;     ...
;         if constexpr (ALIGN_EPI) { if (wr == 0) PG8_BAR; }
	s_setprio 0
	s_add_i32 s54, s77, s62
	v_lshl_add_u64 v[176:177], v[176:177], 0, s[26:27]
	s_mov_b32 m0, s54
	ds_read_b128 v[184:187], v183 offset:49152
	ds_read_b128 v[188:191], v183 offset:50176
	ds_read_b128 v[194:197], v183 offset:51200
	ds_read_b128 v[198:201], v183 offset:52224
	ds_read_b128 v[202:205], v183 offset:53248
	ds_read_b128 v[206:209], v183 offset:54272
	ds_read_b128 v[210:213], v183 offset:55296
	ds_read_b128 v[218:221], v183 offset:56320
	global_load_lds_dwordx4 v[176:177], off
	s_add_i32 m0, s54, 0x2000
	s_add_u32 s52, s52, 0x40080
	v_lshl_add_u64 v[176:177], v[214:215], 0, s[26:27]
	s_addc_u32 s53, s53, 0
	s_add_i32 s54, s78, s62
	global_load_lds_dwordx4 v[176:177], off
	v_lshl_add_u64 v[176:177], s[52:53], 0, v[156:157]
	s_mov_b32 m0, s54
	s_nop 0
	global_load_lds_dwordx4 v[176:177], off
	v_lshl_add_u64 v[176:177], s[52:53], 0, v[152:153]
	s_add_i32 m0, s54, 0x2000
	s_nop 0
	global_load_lds_dwordx4 v[176:177], off
	v_lshl_add_u64 v[176:177], v[222:223], 0, s[26:27]
	s_mov_b32 m0, s68
	s_nop 0
	global_load_lds_dwordx4 v[176:177], off
	v_lshl_add_u64 v[176:177], v[224:225], 0, s[26:27]
	s_mov_b32 m0, s69
	s_nop 0
	global_load_lds_dwordx4 v[176:177], off
	s_waitcnt vmcnt(8) lgkmcnt(0)
	s_setprio 1
	s_barrier
	v_mfma_f32_16x16x32_bf16 v[60:63], v[128:131], v[184:187], v[60:63]
	v_mfma_f32_16x16x32_bf16 v[56:59], v[136:139], v[184:187], v[56:59]
	v_mfma_f32_16x16x32_bf16 v[48:51], v[128:131], v[194:197], v[48:51]
	v_mfma_f32_16x16x32_bf16 v[40:43], v[136:139], v[194:197], v[40:43]
	v_mfma_f32_16x16x32_bf16 v[32:35], v[128:131], v[202:205], v[32:35]
	v_mfma_f32_16x16x32_bf16 v[24:27], v[136:139], v[202:205], v[24:27]
	v_mfma_f32_16x16x32_bf16 v[16:19], v[128:131], v[210:213], v[16:19]
	v_mfma_f32_16x16x32_bf16 v[8:11], v[136:139], v[210:213], v[8:11]
	v_mfma_f32_16x16x32_bf16 v[60:63], v[132:135], v[188:191], v[60:63]
	v_mfma_f32_16x16x32_bf16 v[56:59], v[140:143], v[188:191], v[56:59]
	v_mfma_f32_16x16x32_bf16 v[48:51], v[132:135], v[198:201], v[48:51]
	v_mfma_f32_16x16x32_bf16 v[40:43], v[140:143], v[198:201], v[40:43]
	v_mfma_f32_16x16x32_bf16 v[32:35], v[132:135], v[206:209], v[32:35]
	v_mfma_f32_16x16x32_bf16 v[24:27], v[140:143], v[206:209], v[24:27]
	v_mfma_f32_16x16x32_bf16 v[16:19], v[132:135], v[218:221], v[16:19]
	v_mfma_f32_16x16x32_bf16 v[8:11], v[140:143], v[218:221], v[8:11]
	v_mfma_f32_16x16x32_bf16 v[52:55], v[144:147], v[184:187], v[52:55]
	v_mfma_f32_16x16x32_bf16 v[44:47], v[168:171], v[184:187], v[44:47]
	v_mfma_f32_16x16x32_bf16 v[36:39], v[144:147], v[194:197], v[36:39]
	v_mfma_f32_16x16x32_bf16 v[28:31], v[168:171], v[194:197], v[28:31]
	v_mfma_f32_16x16x32_bf16 v[20:23], v[144:147], v[202:205], v[20:23]
	v_mfma_f32_16x16x32_bf16 v[12:15], v[168:171], v[202:205], v[12:15]
	v_mfma_f32_16x16x32_bf16 v[4:7], v[144:147], v[210:213], v[4:7]
	v_mfma_f32_16x16x32_bf16 v[0:3], v[168:171], v[210:213], v[0:3]
	v_mfma_f32_16x16x32_bf16 v[52:55], v[148:151], v[188:191], v[52:55]
	v_mfma_f32_16x16x32_bf16 v[44:47], v[172:175], v[188:191], v[44:47]
	v_mfma_f32_16x16x32_bf16 v[36:39], v[148:151], v[198:201], v[36:39]
	v_mfma_f32_16x16x32_bf16 v[28:31], v[172:175], v[198:201], v[28:31]
	v_mfma_f32_16x16x32_bf16 v[20:23], v[148:151], v[206:209], v[20:23]
	v_mfma_f32_16x16x32_bf16 v[12:15], v[172:175], v[206:209], v[12:15]
	v_mfma_f32_16x16x32_bf16 v[4:7], v[148:151], v[218:221], v[4:7]
	v_mfma_f32_16x16x32_bf16 v[0:3], v[172:175], v[218:221], v[0:3]
	s_barrier
	s_setprio 0
	s_add_i32 s76, s76, 2
	s_add_u32 s50, s50, 0x100
	s_addc_u32 s51, s51, 0
	s_add_u32 s74, s74, 0x100
	s_addc_u32 s75, s75, 0
	s_cmp_gt_u32 s76, 13
	s_cbranch_scc0 .LBB0_553
	s_and_b64 vcc, exec, s[28:29]
	s_cbranch_vccz .LBB0_556
	s_barrier

; #define PG8_STAGE(bufoff, gbase, voff) do { _Pragma("unroll") for (int _i = 0; _i < 2; ++_i) \
;         __builtin_amdgcn_global_load_lds((const unsigned*)((const char*)(gbase) + (voff)[_i]), (PG8_LAS unsigned*)(lds + (bufoff) + ldsw + _i * 8192), 16, 0, 0); } while (0)
; #define PG8_LDA(dst, b, h) do { _Pragma("unroll") for (int m = 0; m < 4; ++m) _Pragma("unroll") for (int k = 0; k < 2; ++k) dst[m][k] = *(const PG8_LAS bf16x8*)(lds + PG8_SA(b, h) + aoff + m * 2048 + k * 1024); } while (0)
; #define PG8_LDB(dst, b, h) do { _Pragma("unroll") for (int n = 0; n < 2; ++n) _Pragma("unroll") for (int k = 0; k < 2; ++k) dst[n][k] = *(const PG8_LAS bf16x8*)(lds + PG8_SB(b, h) + boff + n * 2048 + k * 1024); } while (0)
; #define PG8_MMA(ai, bj, At, Bt) do { __builtin_amdgcn_s_setprio(1); _Pragma("unroll") for (int m = 0; m < 4; ++m) _Pragma("unroll") for (int n = 0; n < 2; ++n) _Pragma("unroll") for (int k = 0; k < 2; ++k) \
;         acc[ai][bj][m][n] = __builtin_amdgcn_mfma_f32_16x16x32_bf16(Bt[n][k], At[m][k], acc[ai][bj][m][n], 0, 0, 0); __builtin_amdgcn_s_setprio(0); } while (0)
; #define PG8_BAR __builtin_amdgcn_s_barrier()
; template <class Epi, class Sched, bool ALIGN_EPI = false, bool SP2 = false>
; __device__ __forceinline__ void gemm_phase(PG8_LAS unsigned char* lds, const Gemm g, const Sched& S, const Epi& E) {
;     ...
;         const bool has_next = S.next(ui + 1, nxt);
;         const char* nA = has_next ? (const char*)g.A + (size_t)nxt.pm * tstep : cA; const char* nB = has_next ? (const char*)g.Bt + (size_t)nxt.pn * tstep : cB;
;         for (int t = 0; t < nt; t += 2) {
;             const bool last = (t == nt - 2);
;             const char* a1 = cA + (size_t)(t + 1) * kstep;
;             const char* a2 = last ? nA : cA + (size_t)(t + 2) * kstep; const char* b2 = last ? nB : cB + (size_t)(t + 2) * kstep;
;             const char* a3 = a2 + kstep; const char* b3 = b2 + kstep;
;             if (last && has_next) S.a_ready(nxt);
;             if constexpr (SP2) {
;             PG8_LDB(B0, 0, 0); PG8_LDB(B1, 0, 1); PG8_SCHED; PG8_LDA(At, 0, 0); PG8_STAGE(PG8_SA(1, 1), a1 + hstep, voffA);
;             PG8_WAIT_V(8); PG8_WAIT_L(0); PG8_BAR; PG8_MMA(0, 0, At, B0); PG8_MMA(0, 1, At, B1); PG8_BAR; PG8_SCHED;
;             PG8_LDA(At, 0, 1); PG8_STAGE(PG8_SB(0, 0), b2, voffB); PG8_STAGE(PG8_SB(0, 1), b2 + hstep, voffB); PG8_STAGE(PG8_SA(0, 0), a2, voffA);
.LBB0_572:
	s_ashr_i32 s27, s26, 31
	s_lshl_b64 s[28:29], s[26:27], 19
	s_add_u32 s28, s47, s28
	s_addc_u32 s29, s52, s29
	s_and_b64 s[30:31], s[40:41], exec
	s_cselect_b32 s27, s29, s37
	s_cselect_b32 s68, s28, s36
	s_ashr_i32 s25, s24, 31
	s_lshl_b64 s[30:31], s[24:25], 19
	s_add_u32 s30, s53, s30
	s_addc_u32 s31, s54, s31
	s_and_b64 s[50:51], s[40:41], exec
	s_cselect_b32 s25, s31, s45
	s_cselect_b32 s69, s30, s44
	s_add_u32 s36, s36, 0x40080
	s_addc_u32 s37, s37, 0
	s_add_u32 s70, s44, 0x100
	s_addc_u32 s71, s45, 0
	s_mov_b32 s72, -2
	ds_read_b128 v[128:131], v220
	ds_read_b128 v[132:135], v220 offset:1024
	ds_read_b128 v[136:139], v220 offset:2048
	ds_read_b128 v[140:143], v220 offset:3072
	ds_read_b128 v[144:147], v221
	ds_read_b128 v[148:151], v221 offset:1024
	ds_read_b128 v[152:155], v221 offset:2048
	ds_read_b128 v[156:159], v221 offset:3072
	s_add_u32 s44, s36, 0xfffc0080
	s_addc_u32 s45, s37, -1
	s_cmp_eq_u32 s72, 12
	s_cselect_b32 s51, s27, s45
	s_cselect_b32 s50, s68, s44
	s_cselect_b32 s45, s25, s71
	s_cselect_b32 s44, s69, s70
	v_lshl_add_u64 v[210:211], s[36:37], 0, v[194:195]
	s_add_i32 m0, s55, 0xc000
	ds_read_b128 v[160:163], v222
	ds_read_b128 v[164:167], v222 offset:1024
	ds_read_b128 v[168:171], v222 offset:2048
	ds_read_b128 v[172:175], v222 offset:3072
	ds_read_b128 v[176:179], v222 offset:4096
	ds_read_b128 v[180:183], v222 offset:5120
	ds_read_b128 v[202:205], v222 offset:6144
	ds_read_b128 v[206:209], v222 offset:7168
	global_load_lds_dwordx4 v[210:211], off
	v_lshl_add_u64 v[210:211], s[36:37], 0, v[196:197]
	s_add_i32 m0, s55, 0xe000
	s_nop 0
	global_load_lds_dwordx4 v[210:211], off
	s_waitcnt vmcnt(8) lgkmcnt(0)
	s_setprio 1
	s_barrier
	v_mfma_f32_16x16x32_bf16 v[124:127], v[128:131], v[160:163], 0
	v_mfma_f32_16x16x32_bf16 v[120:123], v[136:139], v[160:163], 0
	v_mfma_f32_16x16x32_bf16 v[108:111], v[128:131], v[168:171], 0
	v_mfma_f32_16x16x32_bf16 v[104:107], v[136:139], v[168:171], 0
	v_mfma_f32_16x16x32_bf16 v[92:95], v[128:131], v[176:179], 0
	v_mfma_f32_16x16x32_bf16 v[88:91], v[136:139], v[176:179], 0
	v_mfma_f32_16x16x32_bf16 v[76:79], v[128:131], v[202:205], 0
	v_mfma_f32_16x16x32_bf16 v[72:75], v[136:139], v[202:205], 0
	v_mfma_f32_16x16x32_bf16 v[124:127], v[132:135], v[164:167], v[124:127]
	v_mfma_f32_16x16x32_bf16 v[120:123], v[140:143], v[164:167], v[120:123]
	v_mfma_f32_16x16x32_bf16 v[108:111], v[132:135], v[172:175], v[108:111]
	v_mfma_f32_16x16x32_bf16 v[104:107], v[140:143], v[172:175], v[104:107]
	v_mfma_f32_16x16x32_bf16 v[92:95], v[132:135], v[180:183], v[92:95]
	v_mfma_f32_16x16x32_bf16 v[88:91], v[140:143], v[180:183], v[88:91]
	v_mfma_f32_16x16x32_bf16 v[76:79], v[132:135], v[206:209], v[76:79]
	v_mfma_f32_16x16x32_bf16 v[72:75], v[140:143], v[206:209], v[72:75]
	v_mfma_f32_16x16x32_bf16 v[116:119], v[144:147], v[160:163], 0
	v_mfma_f32_16x16x32_bf16 v[112:115], v[152:155], v[160:163], 0
	v_mfma_f32_16x16x32_bf16 v[100:103], v[144:147], v[168:171], 0
	v_mfma_f32_16x16x32_bf16 v[96:99], v[152:155], v[168:171], 0
	v_mfma_f32_16x16x32_bf16 v[84:87], v[144:147], v[176:179], 0
	v_mfma_f32_16x16x32_bf16 v[80:83], v[152:155], v[176:179], 0
	v_mfma_f32_16x16x32_bf16 v[68:71], v[144:147], v[202:205], 0
	v_mfma_f32_16x16x32_bf16 v[64:67], v[152:155], v[202:205], 0
	v_mfma_f32_16x16x32_bf16 v[116:119], v[148:151], v[164:167], v[116:119]
	v_mfma_f32_16x16x32_bf16 v[112:115], v[156:159], v[164:167], v[112:115]
	v_mfma_f32_16x16x32_bf16 v[100:103], v[148:151], v[172:175], v[100:103]
	v_mfma_f32_16x16x32_bf16 v[96:99], v[156:159], v[172:175], v[96:99]
	v_mfma_f32_16x16x32_bf16 v[84:87], v[148:151], v[180:183], v[84:87]
	v_mfma_f32_16x16x32_bf16 v[80:83], v[156:159], v[180:183], v[80:83]
	v_mfma_f32_16x16x32_bf16 v[68:71], v[148:151], v[206:209], v[68:71]
	v_mfma_f32_16x16x32_bf16 v[64:67], v[156:159], v[206:209], v[64:67]
	s_barrier
	s_setprio 0
	s_add_i32 s73, s66, s13
	v_lshl_add_u64 v[210:211], s[44:45], 0, v[188:189]
	s_mov_b32 m0, s73
	ds_read_b128 v[160:163], v222 offset:16384
	ds_read_b128 v[164:167], v222 offset:17408
	ds_read_b128 v[168:171], v222 offset:18432
	ds_read_b128 v[172:175], v222 offset:19456
	ds_read_b128 v[176:179], v222 offset:20480
	ds_read_b128 v[180:183], v222 offset:21504
	ds_read_b128 v[202:205], v222 offset:22528
	ds_read_b128 v[206:209], v222 offset:23552
	global_load_lds_dwordx4 v[210:211], off
	s_add_i32 m0, s73, 0x2000
	s_add_u32 s74, s44, 0x40000
	v_lshl_add_u64 v[212:213], s[44:45], 0, v[184:185]
	s_addc_u32 s75, s45, 0
	s_add_i32 s73, s67, s13
	global_load_lds_dwordx4 v[212:213], off
	v_lshl_add_u64 v[214:215], s[74:75], 0, v[188:189]
	s_mov_b32 m0, s73
	v_lshl_add_u64 v[224:225], s[50:51], 0, v[186:187]
	global_load_lds_dwordx4 v[214:215], off
	v_lshl_add_u64 v[214:215], s[74:75], 0, v[184:185]
	s_add_i32 m0, s73, 0x2000
	s_nop 0
	global_load_lds_dwordx4 v[214:215], off
	v_lshl_add_u64 v[214:215], s[50:51], 0, v[190:191]
	s_mov_b32 m0, s55
	s_nop 0
	global_load_lds_dwordx4 v[214:215], off
	s_mov_b32 m0, s60
	s_nop 0
	global_load_lds_dwordx4 v[224:225], off
	s_waitcnt vmcnt(8) lgkmcnt(0)
	s_setprio 1
	s_barrier
; #define PG8_STAGE(bufoff, gbase, voff) do { _Pragma("unroll") for (int _i = 0; _i < 2; ++_i) \
;         __builtin_amdgcn_global_load_lds((const unsigned*)((const char*)(gbase) + (voff)[_i]), (PG8_LAS unsigned*)(lds + (bufoff) + ldsw + _i * 8192), 16, 0, 0); } while (0)
; #define PG8_LDA(dst, b, h) do { _Pragma("unroll") for (int m = 0; m < 4; ++m) _Pragma("unroll") for (int k = 0; k < 2; ++k) dst[m][k] = *(const PG8_LAS bf16x8*)(lds + PG8_SA(b, h) + aoff + m * 2048 + k * 1024); } while (0)
; #define PG8_LDB(dst, b, h) do { _Pragma("unroll") for (int n = 0; n < 2; ++n) _Pragma("unroll") for (int k = 0; k < 2; ++k) dst[n][k] = *(const PG8_LAS bf16x8*)(lds + PG8_SB(b, h) + boff + n * 2048 + k * 1024); } while (0)
; #define PG8_MMA(ai, bj, At, Bt) do { __builtin_amdgcn_s_setprio(1); _Pragma("unroll") for (int m = 0; m < 4; ++m) _Pragma("unroll") for (int n = 0; n < 2; ++n) _Pragma("unroll") for (int k = 0; k < 2; ++k) \
;         acc[ai][bj][m][n] = __builtin_amdgcn_mfma_f32_16x16x32_bf16(Bt[n][k], At[m][k], acc[ai][bj][m][n], 0, 0, 0); __builtin_amdgcn_s_setprio(0); } while (0)
; #define PG8_WAIT_V(n) asm volatile("s_waitcnt vmcnt(" #n ")" ::: "memory")
; #define PG8_WAIT_L(n) asm volatile("s_waitcnt lgkmcnt(" #n ")" ::: "memory")
; #define PG8_BAR __builtin_amdgcn_s_barrier()
; #define PG8_SCHED __builtin_amdgcn_sched_barrier(0)
; template <class Epi, class Sched, bool ALIGN_EPI = false, bool SP2 = false>
; __device__ __forceinline__ void gemm_phase(PG8_LAS unsigned char* lds, const Gemm g, const Sched& S, const Epi& E) {
;     ...
;             PG8_WAIT_V(8); PG8_WAIT_L(0); PG8_BAR; PG8_MMA(1, 0, At, B0); PG8_MMA(1, 1, At, B1); PG8_BAR; PG8_SCHED;
;             PG8_LDB(B0, 1, 0); PG8_LDB(B1, 1, 1); PG8_SCHED; PG8_LDA(At, 1, 0); PG8_STAGE(PG8_SA(0, 1), a2 + hstep, voffA);
;             PG8_WAIT_V(8); PG8_WAIT_L(0); PG8_BAR; PG8_MMA(0, 0, At, B0); PG8_MMA(0, 1, At, B1); PG8_BAR; PG8_SCHED;
	v_mfma_f32_16x16x32_bf16 v[60:63], v[128:131], v[160:163], 0
	v_mfma_f32_16x16x32_bf16 v[56:59], v[136:139], v[160:163], 0
	v_mfma_f32_16x16x32_bf16 v[44:47], v[128:131], v[168:171], 0
	v_mfma_f32_16x16x32_bf16 v[40:43], v[136:139], v[168:171], 0
	v_mfma_f32_16x16x32_bf16 v[28:31], v[128:131], v[176:179], 0
	v_mfma_f32_16x16x32_bf16 v[24:27], v[136:139], v[176:179], 0
	v_mfma_f32_16x16x32_bf16 v[12:15], v[128:131], v[202:205], 0
	v_mfma_f32_16x16x32_bf16 v[8:11], v[136:139], v[202:205], 0
	v_mfma_f32_16x16x32_bf16 v[60:63], v[132:135], v[164:167], v[60:63]
	v_mfma_f32_16x16x32_bf16 v[56:59], v[140:143], v[164:167], v[56:59]
	v_mfma_f32_16x16x32_bf16 v[44:47], v[132:135], v[172:175], v[44:47]
	v_mfma_f32_16x16x32_bf16 v[40:43], v[140:143], v[172:175], v[40:43]
	v_mfma_f32_16x16x32_bf16 v[28:31], v[132:135], v[180:183], v[28:31]
	v_mfma_f32_16x16x32_bf16 v[24:27], v[140:143], v[180:183], v[24:27]
	v_mfma_f32_16x16x32_bf16 v[12:15], v[132:135], v[206:209], v[12:15]
	v_mfma_f32_16x16x32_bf16 v[8:11], v[140:143], v[206:209], v[8:11]
	v_mfma_f32_16x16x32_bf16 v[52:55], v[144:147], v[160:163], 0
	v_mfma_f32_16x16x32_bf16 v[48:51], v[152:155], v[160:163], 0
	v_mfma_f32_16x16x32_bf16 v[36:39], v[144:147], v[168:171], 0
	v_mfma_f32_16x16x32_bf16 v[32:35], v[152:155], v[168:171], 0
	v_mfma_f32_16x16x32_bf16 v[20:23], v[144:147], v[176:179], 0
	v_mfma_f32_16x16x32_bf16 v[16:19], v[152:155], v[176:179], 0
	v_mfma_f32_16x16x32_bf16 v[4:7], v[144:147], v[202:205], 0
	v_mfma_f32_16x16x32_bf16 v[0:3], v[152:155], v[202:205], 0
	v_mfma_f32_16x16x32_bf16 v[52:55], v[148:151], v[164:167], v[52:55]
	v_mfma_f32_16x16x32_bf16 v[48:51], v[156:159], v[164:167], v[48:51]
	v_mfma_f32_16x16x32_bf16 v[36:39], v[148:151], v[172:175], v[36:39]
	v_mfma_f32_16x16x32_bf16 v[32:35], v[156:159], v[172:175], v[32:35]
	v_mfma_f32_16x16x32_bf16 v[20:23], v[148:151], v[180:183], v[20:23]
	v_mfma_f32_16x16x32_bf16 v[16:19], v[156:159], v[180:183], v[16:19]
	v_mfma_f32_16x16x32_bf16 v[4:7], v[148:151], v[206:209], v[4:7]
	v_mfma_f32_16x16x32_bf16 v[0:3], v[156:159], v[206:209], v[0:3]
	s_barrier
	s_setprio 0
	s_add_i32 s73, 0, 0x18000
	s_add_i32 s74, 0, 0x1c000
	v_add_u32_e32 v140, s73, v218
	v_add_u32_e32 v156, s74, v218
	ds_read_b128 v[128:131], v140
	ds_read_b128 v[132:135], v140 offset:1024
	ds_read_b128 v[136:139], v140 offset:2048
	ds_read_b128 v[140:143], v140 offset:3072
	ds_read_b128 v[144:147], v156
	ds_read_b128 v[148:151], v156 offset:1024
	ds_read_b128 v[152:155], v156 offset:2048
	ds_read_b128 v[156:159], v156 offset:3072
	s_add_u32 s50, s50, 0x40000
	s_addc_u32 s51, s51, 0
	s_mov_b32 m0, s61
	v_lshl_add_u64 v[226:227], s[50:51], 0, v[190:191]
	ds_read_b128 v[160:163], v222 offset:32768
	ds_read_b128 v[164:167], v222 offset:33792
	ds_read_b128 v[168:171], v222 offset:34816
	ds_read_b128 v[172:175], v222 offset:35840
	ds_read_b128 v[176:179], v222 offset:36864
	ds_read_b128 v[180:183], v222 offset:37888
	ds_read_b128 v[202:205], v222 offset:38912
	ds_read_b128 v[206:209], v222 offset:39936
	global_load_lds_dwordx4 v[226:227], off
	v_lshl_add_u64 v[226:227], s[50:51], 0, v[186:187]
	s_mov_b32 m0, s62
	s_nop 0
	global_load_lds_dwordx4 v[226:227], off
	s_waitcnt vmcnt(8) lgkmcnt(0)
	s_setprio 1
	s_barrier
	v_mfma_f32_16x16x32_bf16 v[124:127], v[128:131], v[160:163], v[124:127]
	v_mfma_f32_16x16x32_bf16 v[120:123], v[136:139], v[160:163], v[120:123]
	v_mfma_f32_16x16x32_bf16 v[108:111], v[128:131], v[168:171], v[108:111]
	v_mfma_f32_16x16x32_bf16 v[104:107], v[136:139], v[168:171], v[104:107]
	v_mfma_f32_16x16x32_bf16 v[92:95], v[128:131], v[176:179], v[92:95]
	v_mfma_f32_16x16x32_bf16 v[88:91], v[136:139], v[176:179], v[88:91]
	v_mfma_f32_16x16x32_bf16 v[76:79], v[128:131], v[202:205], v[76:79]
	v_mfma_f32_16x16x32_bf16 v[72:75], v[136:139], v[202:205], v[72:75]
	v_mfma_f32_16x16x32_bf16 v[124:127], v[132:135], v[164:167], v[124:127]
	v_mfma_f32_16x16x32_bf16 v[120:123], v[140:143], v[164:167], v[120:123]
	v_mfma_f32_16x16x32_bf16 v[108:111], v[132:135], v[172:175], v[108:111]
	v_mfma_f32_16x16x32_bf16 v[104:107], v[140:143], v[172:175], v[104:107]
	v_mfma_f32_16x16x32_bf16 v[92:95], v[132:135], v[180:183], v[92:95]
	v_mfma_f32_16x16x32_bf16 v[88:91], v[140:143], v[180:183], v[88:91]
	v_mfma_f32_16x16x32_bf16 v[76:79], v[132:135], v[206:209], v[76:79]
	v_mfma_f32_16x16x32_bf16 v[72:75], v[140:143], v[206:209], v[72:75]
	v_mfma_f32_16x16x32_bf16 v[116:119], v[144:147], v[160:163], v[116:119]
	v_mfma_f32_16x16x32_bf16 v[112:115], v[152:155], v[160:163], v[112:115]
	v_mfma_f32_16x16x32_bf16 v[100:103], v[144:147], v[168:171], v[100:103]
	v_mfma_f32_16x16x32_bf16 v[96:99], v[152:155], v[168:171], v[96:99]
	v_mfma_f32_16x16x32_bf16 v[84:87], v[144:147], v[176:179], v[84:87]
	v_mfma_f32_16x16x32_bf16 v[80:83], v[152:155], v[176:179], v[80:83]
	v_mfma_f32_16x16x32_bf16 v[68:71], v[144:147], v[202:205], v[68:71]
	v_mfma_f32_16x16x32_bf16 v[64:67], v[152:155], v[202:205], v[64:67]
	v_mfma_f32_16x16x32_bf16 v[116:119], v[148:151], v[164:167], v[116:119]
	v_mfma_f32_16x16x32_bf16 v[112:115], v[156:159], v[164:167], v[112:115]
	v_mfma_f32_16x16x32_bf16 v[100:103], v[148:151], v[172:175], v[100:103]
	v_mfma_f32_16x16x32_bf16 v[96:99], v[156:159], v[172:175], v[96:99]
	v_mfma_f32_16x16x32_bf16 v[84:87], v[148:151], v[180:183], v[84:87]
	v_mfma_f32_16x16x32_bf16 v[80:83], v[156:159], v[180:183], v[80:83]
	v_mfma_f32_16x16x32_bf16 v[68:71], v[148:151], v[206:209], v[68:71]
	v_mfma_f32_16x16x32_bf16 v[64:67], v[156:159], v[206:209], v[64:67]
	s_barrier
; #define PG8_STAGE(bufoff, gbase, voff) do { _Pragma("unroll") for (int _i = 0; _i < 2; ++_i) \
;         __builtin_amdgcn_global_load_lds((const unsigned*)((const char*)(gbase) + (voff)[_i]), (PG8_LAS unsigned*)(lds + (bufoff) + ldsw + _i * 8192), 16, 0, 0); } while (0)
; #define PG8_LDA(dst, b, h) do { _Pragma("unroll") for (int m = 0; m < 4; ++m) _Pragma("unroll") for (int k = 0; k < 2; ++k) dst[m][k] = *(const PG8_LAS bf16x8*)(lds + PG8_SA(b, h) + aoff + m * 2048 + k * 1024); } while (0)
; #define PG8_LDB(dst, b, h) do { _Pragma("unroll") for (int n = 0; n < 2; ++n) _Pragma("unroll") for (int k = 0; k < 2; ++k) dst[n][k] = *(const PG8_LAS bf16x8*)(lds + PG8_SB(b, h) + boff + n * 2048 + k * 1024); } while (0)
; #define PG8_MMA(ai, bj, At, Bt) do { __builtin_amdgcn_s_setprio(1); _Pragma("unroll") for (int m = 0; m < 4; ++m) _Pragma("unroll") for (int n = 0; n < 2; ++n) _Pragma("unroll") for (int k = 0; k < 2; ++k) \
;         acc[ai][bj][m][n] = __builtin_amdgcn_mfma_f32_16x16x32_bf16(Bt[n][k], At[m][k], acc[ai][bj][m][n], 0, 0, 0); __builtin_amdgcn_s_setprio(0); } while (0)
; #define PG8_WAIT_V(n) asm volatile("s_waitcnt vmcnt(" #n ")" ::: "memory")
; template <class Epi, class Sched, bool ALIGN_EPI = false, bool SP2 = false>
; __device__ __forceinline__ void gemm_phase(PG8_LAS unsigned char* lds, const Gemm g, const Sched& S, const Epi& E) {
;     ...
;             PG8_LDB(B0, 0, 0); PG8_LDB(B1, 0, 1); PG8_SCHED; PG8_LDA(At, 0, 0); PG8_STAGE(PG8_SA(1, 1), a1 + hstep, voffA);
;             PG8_WAIT_V(8); PG8_WAIT_L(0); PG8_BAR; PG8_MMA(0, 0, At, B0); PG8_MMA(0, 1, At, B1); PG8_BAR; PG8_SCHED;
;             PG8_LDA(At, 0, 1); PG8_STAGE(PG8_SB(0, 0), b2, voffB); PG8_STAGE(PG8_SB(0, 1), b2 + hstep, voffB); PG8_STAGE(PG8_SA(0, 0), a2, voffA);
;             PG8_WAIT_V(8); PG8_WAIT_L(0); PG8_BAR; PG8_MMA(1, 0, At, B0); PG8_MMA(1, 1, At, B1); PG8_BAR; PG8_SCHED;
;             PG8_LDB(B0, 1, 0); PG8_LDB(B1, 1, 1); PG8_SCHED; PG8_LDA(At, 1, 0); PG8_STAGE(PG8_SA(0, 1), a2 + hstep, voffA);
;             PG8_WAIT_V(8); PG8_WAIT_L(0); PG8_BAR; PG8_MMA(0, 0, At, B0); PG8_MMA(0, 1, At, B1); PG8_BAR; PG8_SCHED;
;             PG8_LDA(At, 1, 1); PG8_STAGE(PG8_SB(1, 0), b3, voffB); PG8_STAGE(PG8_SB(1, 1), b3 + hstep, voffB); PG8_STAGE(PG8_SA(1, 0), a3, voffA);
;             PG8_WAIT_V(8); PG8_WAIT_L(0); PG8_BAR; PG8_MMA(1, 0, At, B0); PG8_MMA(1, 1, At, B1); PG8_BAR; PG8_SCHED;
	s_setprio 0
	s_add_i32 s50, s73, s13
	v_lshl_add_u64 v[210:211], v[210:211], 0, s[20:21]
	s_mov_b32 m0, s50
	ds_read_b128 v[160:163], v222 offset:49152
	ds_read_b128 v[164:167], v222 offset:50176
	ds_read_b128 v[168:171], v222 offset:51200
	ds_read_b128 v[172:175], v222 offset:52224
	ds_read_b128 v[176:179], v222 offset:53248
	ds_read_b128 v[180:183], v222 offset:54272
	ds_read_b128 v[202:205], v222 offset:55296
	ds_read_b128 v[206:209], v222 offset:56320
	global_load_lds_dwordx4 v[210:211], off
	s_add_i32 m0, s50, 0x2000
	s_add_u32 s44, s44, 0x40080
	v_lshl_add_u64 v[210:211], v[212:213], 0, s[20:21]
	s_addc_u32 s45, s45, 0
	s_add_i32 s50, s74, s13
	global_load_lds_dwordx4 v[210:211], off
	v_lshl_add_u64 v[210:211], s[44:45], 0, v[188:189]
	s_mov_b32 m0, s50
	s_nop 0
	global_load_lds_dwordx4 v[210:211], off
	v_lshl_add_u64 v[210:211], s[44:45], 0, v[184:185]
	s_add_i32 m0, s50, 0x2000
	s_nop 0
	global_load_lds_dwordx4 v[210:211], off
	v_lshl_add_u64 v[210:211], v[214:215], 0, s[20:21]
	s_mov_b32 m0, s64
	s_nop 0
	global_load_lds_dwordx4 v[210:211], off
	v_lshl_add_u64 v[210:211], v[224:225], 0, s[20:21]
	s_mov_b32 m0, s65
	s_nop 0
	global_load_lds_dwordx4 v[210:211], off
	s_waitcnt vmcnt(8) lgkmcnt(0)
	s_setprio 1
	s_barrier
	v_mfma_f32_16x16x32_bf16 v[60:63], v[128:131], v[160:163], v[60:63]
	v_mfma_f32_16x16x32_bf16 v[56:59], v[136:139], v[160:163], v[56:59]
	v_mfma_f32_16x16x32_bf16 v[44:47], v[128:131], v[168:171], v[44:47]
	v_mfma_f32_16x16x32_bf16 v[40:43], v[136:139], v[168:171], v[40:43]
	v_mfma_f32_16x16x32_bf16 v[28:31], v[128:131], v[176:179], v[28:31]
	v_mfma_f32_16x16x32_bf16 v[24:27], v[136:139], v[176:179], v[24:27]
	v_mfma_f32_16x16x32_bf16 v[12:15], v[128:131], v[202:205], v[12:15]
	v_mfma_f32_16x16x32_bf16 v[8:11], v[136:139], v[202:205], v[8:11]
	v_mfma_f32_16x16x32_bf16 v[60:63], v[132:135], v[164:167], v[60:63]
	v_mfma_f32_16x16x32_bf16 v[56:59], v[140:143], v[164:167], v[56:59]
	v_mfma_f32_16x16x32_bf16 v[44:47], v[132:135], v[172:175], v[44:47]
	v_mfma_f32_16x16x32_bf16 v[40:43], v[140:143], v[172:175], v[40:43]
	v_mfma_f32_16x16x32_bf16 v[28:31], v[132:135], v[180:183], v[28:31]
	v_mfma_f32_16x16x32_bf16 v[24:27], v[140:143], v[180:183], v[24:27]
	v_mfma_f32_16x16x32_bf16 v[12:15], v[132:135], v[206:209], v[12:15]
	v_mfma_f32_16x16x32_bf16 v[8:11], v[140:143], v[206:209], v[8:11]
	v_mfma_f32_16x16x32_bf16 v[52:55], v[144:147], v[160:163], v[52:55]
	v_mfma_f32_16x16x32_bf16 v[48:51], v[152:155], v[160:163], v[48:51]
	v_mfma_f32_16x16x32_bf16 v[36:39], v[144:147], v[168:171], v[36:39]
	v_mfma_f32_16x16x32_bf16 v[32:35], v[152:155], v[168:171], v[32:35]
	v_mfma_f32_16x16x32_bf16 v[20:23], v[144:147], v[176:179], v[20:23]
	v_mfma_f32_16x16x32_bf16 v[16:19], v[152:155], v[176:179], v[16:19]
	v_mfma_f32_16x16x32_bf16 v[4:7], v[144:147], v[202:205], v[4:7]
	v_mfma_f32_16x16x32_bf16 v[0:3], v[152:155], v[202:205], v[0:3]
	v_mfma_f32_16x16x32_bf16 v[52:55], v[148:151], v[164:167], v[52:55]
	v_mfma_f32_16x16x32_bf16 v[48:51], v[156:159], v[164:167], v[48:51]
	v_mfma_f32_16x16x32_bf16 v[36:39], v[148:151], v[172:175], v[36:39]
	v_mfma_f32_16x16x32_bf16 v[32:35], v[156:159], v[172:175], v[32:35]
	v_mfma_f32_16x16x32_bf16 v[20:23], v[148:151], v[180:183], v[20:23]
	v_mfma_f32_16x16x32_bf16 v[16:19], v[156:159], v[180:183], v[16:19]
	v_mfma_f32_16x16x32_bf16 v[4:7], v[148:151], v[206:209], v[4:7]
	v_mfma_f32_16x16x32_bf16 v[0:3], v[156:159], v[206:209], v[0:3]
	s_barrier
	s_setprio 0
	s_add_i32 s72, s72, 2
	s_add_u32 s36, s36, 0x100
	s_addc_u32 s37, s37, 0
	s_add_u32 s70, s70, 0x100
	s_addc_u32 s71, s71, 0
	s_cmp_gt_u32 s72, 13
.LBB0_573:
	ds_read_b128 v[128:131], v220
	ds_read_b128 v[132:135], v220 offset:1024
	ds_read_b128 v[136:139], v220 offset:2048
	ds_read_b128 v[140:143], v220 offset:3072
	ds_read_b128 v[144:147], v221
	ds_read_b128 v[148:151], v221 offset:1024
	ds_read_b128 v[152:155], v221 offset:2048
	ds_read_b128 v[156:159], v221 offset:3072
	s_add_u32 s44, s36, 0xfffc0080
	s_addc_u32 s45, s37, -1
	s_cmp_eq_u32 s72, 12
	s_cselect_b32 s51, s27, s45
	s_cselect_b32 s50, s68, s44
	s_cselect_b32 s45, s25, s71
	s_cselect_b32 s44, s69, s70
	v_lshl_add_u64 v[210:211], s[36:37], 0, v[194:195]
	s_add_i32 m0, s55, 0xc000
	ds_read_b128 v[160:163], v222
	ds_read_b128 v[164:167], v222 offset:1024
	ds_read_b128 v[168:171], v222 offset:2048
	ds_read_b128 v[172:175], v222 offset:3072
	ds_read_b128 v[176:179], v222 offset:4096
	ds_read_b128 v[180:183], v222 offset:5120
	ds_read_b128 v[202:205], v222 offset:6144
	ds_read_b128 v[206:209], v222 offset:7168
	global_load_lds_dwordx4 v[210:211], off
	v_lshl_add_u64 v[210:211], s[36:37], 0, v[196:197]
	s_add_i32 m0, s55, 0xe000
	s_nop 0
	global_load_lds_dwordx4 v[210:211], off
	s_waitcnt vmcnt(8) lgkmcnt(0)
	s_setprio 1
	s_barrier
; #define PG8_STAGE(bufoff, gbase, voff) do { _Pragma("unroll") for (int _i = 0; _i < 2; ++_i) \
;         __builtin_amdgcn_global_load_lds((const unsigned*)((const char*)(gbase) + (voff)[_i]), (PG8_LAS unsigned*)(lds + (bufoff) + ldsw + _i * 8192), 16, 0, 0); } while (0)
; #define PG8_LDA(dst, b, h) do { _Pragma("unroll") for (int m = 0; m < 4; ++m) _Pragma("unroll") for (int k = 0; k < 2; ++k) dst[m][k] = *(const PG8_LAS bf16x8*)(lds + PG8_SA(b, h) + aoff + m * 2048 + k * 1024); } while (0)
; #define PG8_MMA(ai, bj, At, Bt) do { __builtin_amdgcn_s_setprio(1); _Pragma("unroll") for (int m = 0; m < 4; ++m) _Pragma("unroll") for (int n = 0; n < 2; ++n) _Pragma("unroll") for (int k = 0; k < 2; ++k) \
;         acc[ai][bj][m][n] = __builtin_amdgcn_mfma_f32_16x16x32_bf16(Bt[n][k], At[m][k], acc[ai][bj][m][n], 0, 0, 0); __builtin_amdgcn_s_setprio(0); } while (0)
; #define PG8_WAIT_V(n) asm volatile("s_waitcnt vmcnt(" #n ")" ::: "memory")
; #define PG8_WAIT_L(n) asm volatile("s_waitcnt lgkmcnt(" #n ")" ::: "memory")
; #define PG8_BAR __builtin_amdgcn_s_barrier()
; #define PG8_SCHED __builtin_amdgcn_sched_barrier(0)
; template <class Epi, class Sched, bool ALIGN_EPI = false, bool SP2 = false>
; __device__ __forceinline__ void gemm_phase(PG8_LAS unsigned char* lds, const Gemm g, const Sched& S, const Epi& E) {
;     ...
;             PG8_WAIT_V(8); PG8_WAIT_L(0); PG8_BAR; PG8_MMA(0, 0, At, B0); PG8_MMA(0, 1, At, B1); PG8_BAR; PG8_SCHED;
;             PG8_LDA(At, 0, 1); PG8_STAGE(PG8_SB(0, 0), b2, voffB); PG8_STAGE(PG8_SB(0, 1), b2 + hstep, voffB); PG8_STAGE(PG8_SA(0, 0), a2, voffA);
;             PG8_WAIT_V(8); PG8_WAIT_L(0); PG8_BAR; PG8_MMA(1, 0, At, B0); PG8_MMA(1, 1, At, B1); PG8_BAR; PG8_SCHED;
	v_mfma_f32_16x16x32_bf16 v[124:127], v[128:131], v[160:163], v[124:127]
	v_mfma_f32_16x16x32_bf16 v[120:123], v[136:139], v[160:163], v[120:123]
	v_mfma_f32_16x16x32_bf16 v[108:111], v[128:131], v[168:171], v[108:111]
	v_mfma_f32_16x16x32_bf16 v[104:107], v[136:139], v[168:171], v[104:107]
	v_mfma_f32_16x16x32_bf16 v[92:95], v[128:131], v[176:179], v[92:95]
	v_mfma_f32_16x16x32_bf16 v[88:91], v[136:139], v[176:179], v[88:91]
	v_mfma_f32_16x16x32_bf16 v[76:79], v[128:131], v[202:205], v[76:79]
	v_mfma_f32_16x16x32_bf16 v[72:75], v[136:139], v[202:205], v[72:75]
	v_mfma_f32_16x16x32_bf16 v[124:127], v[132:135], v[164:167], v[124:127]
	v_mfma_f32_16x16x32_bf16 v[120:123], v[140:143], v[164:167], v[120:123]
	v_mfma_f32_16x16x32_bf16 v[108:111], v[132:135], v[172:175], v[108:111]
	v_mfma_f32_16x16x32_bf16 v[104:107], v[140:143], v[172:175], v[104:107]
	v_mfma_f32_16x16x32_bf16 v[92:95], v[132:135], v[180:183], v[92:95]
	v_mfma_f32_16x16x32_bf16 v[88:91], v[140:143], v[180:183], v[88:91]
	v_mfma_f32_16x16x32_bf16 v[76:79], v[132:135], v[206:209], v[76:79]
	v_mfma_f32_16x16x32_bf16 v[72:75], v[140:143], v[206:209], v[72:75]
	v_mfma_f32_16x16x32_bf16 v[116:119], v[144:147], v[160:163], v[116:119]
	v_mfma_f32_16x16x32_bf16 v[112:115], v[152:155], v[160:163], v[112:115]
	v_mfma_f32_16x16x32_bf16 v[100:103], v[144:147], v[168:171], v[100:103]
	v_mfma_f32_16x16x32_bf16 v[96:99], v[152:155], v[168:171], v[96:99]
	v_mfma_f32_16x16x32_bf16 v[84:87], v[144:147], v[176:179], v[84:87]
	v_mfma_f32_16x16x32_bf16 v[80:83], v[152:155], v[176:179], v[80:83]
	v_mfma_f32_16x16x32_bf16 v[68:71], v[144:147], v[202:205], v[68:71]
	v_mfma_f32_16x16x32_bf16 v[64:67], v[152:155], v[202:205], v[64:67]
	v_mfma_f32_16x16x32_bf16 v[116:119], v[148:151], v[164:167], v[116:119]
	v_mfma_f32_16x16x32_bf16 v[112:115], v[156:159], v[164:167], v[112:115]
	v_mfma_f32_16x16x32_bf16 v[100:103], v[148:151], v[172:175], v[100:103]
	v_mfma_f32_16x16x32_bf16 v[96:99], v[156:159], v[172:175], v[96:99]
	v_mfma_f32_16x16x32_bf16 v[84:87], v[148:151], v[180:183], v[84:87]
	v_mfma_f32_16x16x32_bf16 v[80:83], v[156:159], v[180:183], v[80:83]
	v_mfma_f32_16x16x32_bf16 v[68:71], v[148:151], v[206:209], v[68:71]
	v_mfma_f32_16x16x32_bf16 v[64:67], v[156:159], v[206:209], v[64:67]
	s_barrier
	s_setprio 0
	s_add_i32 s73, s66, s13
	v_lshl_add_u64 v[210:211], s[44:45], 0, v[188:189]
	s_mov_b32 m0, s73
	ds_read_b128 v[160:163], v222 offset:16384
	ds_read_b128 v[164:167], v222 offset:17408
	ds_read_b128 v[168:171], v222 offset:18432
	ds_read_b128 v[172:175], v222 offset:19456
	ds_read_b128 v[176:179], v222 offset:20480
	ds_read_b128 v[180:183], v222 offset:21504
	ds_read_b128 v[202:205], v222 offset:22528
	ds_read_b128 v[206:209], v222 offset:23552
	global_load_lds_dwordx4 v[210:211], off
	s_add_i32 m0, s73, 0x2000
	s_add_u32 s74, s44, 0x40000
	v_lshl_add_u64 v[212:213], s[44:45], 0, v[184:185]
	s_addc_u32 s75, s45, 0
	s_add_i32 s73, s67, s13
	global_load_lds_dwordx4 v[212:213], off
	v_lshl_add_u64 v[214:215], s[74:75], 0, v[188:189]
	s_mov_b32 m0, s73
	v_lshl_add_u64 v[224:225], s[50:51], 0, v[186:187]
	global_load_lds_dwordx4 v[214:215], off
	v_lshl_add_u64 v[214:215], s[74:75], 0, v[184:185]
	s_add_i32 m0, s73, 0x2000
	s_nop 0
	global_load_lds_dwordx4 v[214:215], off
	v_lshl_add_u64 v[214:215], s[50:51], 0, v[190:191]
	s_mov_b32 m0, s55
	s_nop 0
	global_load_lds_dwordx4 v[214:215], off
	s_mov_b32 m0, s60
	s_nop 0
	global_load_lds_dwordx4 v[224:225], off
	s_waitcnt vmcnt(8) lgkmcnt(0)
	s_setprio 1
	s_barrier
	v_mfma_f32_16x16x32_bf16 v[60:63], v[128:131], v[160:163], v[60:63]
	v_mfma_f32_16x16x32_bf16 v[56:59], v[136:139], v[160:163], v[56:59]
	v_mfma_f32_16x16x32_bf16 v[44:47], v[128:131], v[168:171], v[44:47]
	v_mfma_f32_16x16x32_bf16 v[40:43], v[136:139], v[168:171], v[40:43]
	v_mfma_f32_16x16x32_bf16 v[28:31], v[128:131], v[176:179], v[28:31]
	v_mfma_f32_16x16x32_bf16 v[24:27], v[136:139], v[176:179], v[24:27]
	v_mfma_f32_16x16x32_bf16 v[12:15], v[128:131], v[202:205], v[12:15]
	v_mfma_f32_16x16x32_bf16 v[8:11], v[136:139], v[202:205], v[8:11]
	v_mfma_f32_16x16x32_bf16 v[60:63], v[132:135], v[164:167], v[60:63]
	v_mfma_f32_16x16x32_bf16 v[56:59], v[140:143], v[164:167], v[56:59]
	v_mfma_f32_16x16x32_bf16 v[44:47], v[132:135], v[172:175], v[44:47]
	v_mfma_f32_16x16x32_bf16 v[40:43], v[140:143], v[172:175], v[40:43]
	v_mfma_f32_16x16x32_bf16 v[28:31], v[132:135], v[180:183], v[28:31]
	v_mfma_f32_16x16x32_bf16 v[24:27], v[140:143], v[180:183], v[24:27]
	v_mfma_f32_16x16x32_bf16 v[12:15], v[132:135], v[206:209], v[12:15]
	v_mfma_f32_16x16x32_bf16 v[8:11], v[140:143], v[206:209], v[8:11]
	v_mfma_f32_16x16x32_bf16 v[52:55], v[144:147], v[160:163], v[52:55]
	v_mfma_f32_16x16x32_bf16 v[48:51], v[152:155], v[160:163], v[48:51]
	v_mfma_f32_16x16x32_bf16 v[36:39], v[144:147], v[168:171], v[36:39]
	v_mfma_f32_16x16x32_bf16 v[32:35], v[152:155], v[168:171], v[32:35]
	v_mfma_f32_16x16x32_bf16 v[20:23], v[144:147], v[176:179], v[20:23]
	v_mfma_f32_16x16x32_bf16 v[16:19], v[152:155], v[176:179], v[16:19]
	v_mfma_f32_16x16x32_bf16 v[4:7], v[144:147], v[202:205], v[4:7]
	v_mfma_f32_16x16x32_bf16 v[0:3], v[152:155], v[202:205], v[0:3]
	v_mfma_f32_16x16x32_bf16 v[52:55], v[148:151], v[164:167], v[52:55]
	v_mfma_f32_16x16x32_bf16 v[48:51], v[156:159], v[164:167], v[48:51]
	v_mfma_f32_16x16x32_bf16 v[36:39], v[148:151], v[172:175], v[36:39]
	v_mfma_f32_16x16x32_bf16 v[32:35], v[156:159], v[172:175], v[32:35]
	v_mfma_f32_16x16x32_bf16 v[20:23], v[148:151], v[180:183], v[20:23]
	v_mfma_f32_16x16x32_bf16 v[16:19], v[156:159], v[180:183], v[16:19]
	v_mfma_f32_16x16x32_bf16 v[4:7], v[148:151], v[206:209], v[4:7]
	v_mfma_f32_16x16x32_bf16 v[0:3], v[156:159], v[206:209], v[0:3]
	s_barrier
; #define PG8_STAGE(bufoff, gbase, voff) do { _Pragma("unroll") for (int _i = 0; _i < 2; ++_i) \
;         __builtin_amdgcn_global_load_lds((const unsigned*)((const char*)(gbase) + (voff)[_i]), (PG8_LAS unsigned*)(lds + (bufoff) + ldsw + _i * 8192), 16, 0, 0); } while (0)
; #define PG8_LDA(dst, b, h) do { _Pragma("unroll") for (int m = 0; m < 4; ++m) _Pragma("unroll") for (int k = 0; k < 2; ++k) dst[m][k] = *(const PG8_LAS bf16x8*)(lds + PG8_SA(b, h) + aoff + m * 2048 + k * 1024); } while (0)
; #define PG8_LDB(dst, b, h) do { _Pragma("unroll") for (int n = 0; n < 2; ++n) _Pragma("unroll") for (int k = 0; k < 2; ++k) dst[n][k] = *(const PG8_LAS bf16x8*)(lds + PG8_SB(b, h) + boff + n * 2048 + k * 1024); } while (0)
; #define PG8_MMA(ai, bj, At, Bt) do { __builtin_amdgcn_s_setprio(1); _Pragma("unroll") for (int m = 0; m < 4; ++m) _Pragma("unroll") for (int n = 0; n < 2; ++n) _Pragma("unroll") for (int k = 0; k < 2; ++k) \
;         acc[ai][bj][m][n] = __builtin_amdgcn_mfma_f32_16x16x32_bf16(Bt[n][k], At[m][k], acc[ai][bj][m][n], 0, 0, 0); __builtin_amdgcn_s_setprio(0); } while (0)
; #define PG8_WAIT_V(n) asm volatile("s_waitcnt vmcnt(" #n ")" ::: "memory")
; #define PG8_WAIT_L(n) asm volatile("s_waitcnt lgkmcnt(" #n ")" ::: "memory")
; #define PG8_BAR __builtin_amdgcn_s_barrier()
; #define PG8_SCHED __builtin_amdgcn_sched_barrier(0)
; template <class Epi, class Sched, bool ALIGN_EPI = false, bool SP2 = false>
; __device__ __forceinline__ void gemm_phase(PG8_LAS unsigned char* lds, const Gemm g, const Sched& S, const Epi& E) {
;     ...
;             PG8_LDB(B0, 1, 0); PG8_LDB(B1, 1, 1); PG8_SCHED; PG8_LDA(At, 1, 0); PG8_STAGE(PG8_SA(0, 1), a2 + hstep, voffA);
;             PG8_WAIT_V(8); PG8_WAIT_L(0); PG8_BAR; PG8_MMA(0, 0, At, B0); PG8_MMA(0, 1, At, B1); PG8_BAR; PG8_SCHED;
	s_setprio 0
	s_add_i32 s73, 0, 0x18000
	s_add_i32 s74, 0, 0x1c000
	v_add_u32_e32 v140, s73, v218
	v_add_u32_e32 v156, s74, v218
	ds_read_b128 v[128:131], v140
	ds_read_b128 v[132:135], v140 offset:1024
	ds_read_b128 v[136:139], v140 offset:2048
	ds_read_b128 v[140:143], v140 offset:3072
	ds_read_b128 v[144:147], v156
	ds_read_b128 v[148:151], v156 offset:1024
	ds_read_b128 v[152:155], v156 offset:2048
	ds_read_b128 v[156:159], v156 offset:3072
	s_add_u32 s50, s50, 0x40000
	s_addc_u32 s51, s51, 0
	s_mov_b32 m0, s61
	v_lshl_add_u64 v[226:227], s[50:51], 0, v[190:191]
	ds_read_b128 v[160:163], v222 offset:32768
	ds_read_b128 v[164:167], v222 offset:33792
	ds_read_b128 v[168:171], v222 offset:34816
	ds_read_b128 v[172:175], v222 offset:35840
	ds_read_b128 v[176:179], v222 offset:36864
	ds_read_b128 v[180:183], v222 offset:37888
	ds_read_b128 v[202:205], v222 offset:38912
	ds_read_b128 v[206:209], v222 offset:39936
	global_load_lds_dwordx4 v[226:227], off
	v_lshl_add_u64 v[226:227], s[50:51], 0, v[186:187]
	s_mov_b32 m0, s62
	s_nop 0
	global_load_lds_dwordx4 v[226:227], off
	s_waitcnt vmcnt(8) lgkmcnt(0)
	s_setprio 1
	s_barrier
	v_mfma_f32_16x16x32_bf16 v[124:127], v[128:131], v[160:163], v[124:127]
	v_mfma_f32_16x16x32_bf16 v[120:123], v[136:139], v[160:163], v[120:123]
	v_mfma_f32_16x16x32_bf16 v[108:111], v[128:131], v[168:171], v[108:111]
	v_mfma_f32_16x16x32_bf16 v[104:107], v[136:139], v[168:171], v[104:107]
	v_mfma_f32_16x16x32_bf16 v[92:95], v[128:131], v[176:179], v[92:95]
	v_mfma_f32_16x16x32_bf16 v[88:91], v[136:139], v[176:179], v[88:91]
	v_mfma_f32_16x16x32_bf16 v[76:79], v[128:131], v[202:205], v[76:79]
	v_mfma_f32_16x16x32_bf16 v[72:75], v[136:139], v[202:205], v[72:75]
	v_mfma_f32_16x16x32_bf16 v[124:127], v[132:135], v[164:167], v[124:127]
	v_mfma_f32_16x16x32_bf16 v[120:123], v[140:143], v[164:167], v[120:123]
	v_mfma_f32_16x16x32_bf16 v[108:111], v[132:135], v[172:175], v[108:111]
	v_mfma_f32_16x16x32_bf16 v[104:107], v[140:143], v[172:175], v[104:107]
	v_mfma_f32_16x16x32_bf16 v[92:95], v[132:135], v[180:183], v[92:95]
	v_mfma_f32_16x16x32_bf16 v[88:91], v[140:143], v[180:183], v[88:91]
	v_mfma_f32_16x16x32_bf16 v[76:79], v[132:135], v[206:209], v[76:79]
	v_mfma_f32_16x16x32_bf16 v[72:75], v[140:143], v[206:209], v[72:75]
	v_mfma_f32_16x16x32_bf16 v[116:119], v[144:147], v[160:163], v[116:119]
	v_mfma_f32_16x16x32_bf16 v[112:115], v[152:155], v[160:163], v[112:115]
	v_mfma_f32_16x16x32_bf16 v[100:103], v[144:147], v[168:171], v[100:103]
	v_mfma_f32_16x16x32_bf16 v[96:99], v[152:155], v[168:171], v[96:99]
	v_mfma_f32_16x16x32_bf16 v[84:87], v[144:147], v[176:179], v[84:87]
	v_mfma_f32_16x16x32_bf16 v[80:83], v[152:155], v[176:179], v[80:83]
	v_mfma_f32_16x16x32_bf16 v[68:71], v[144:147], v[202:205], v[68:71]
	v_mfma_f32_16x16x32_bf16 v[64:67], v[152:155], v[202:205], v[64:67]
	v_mfma_f32_16x16x32_bf16 v[116:119], v[148:151], v[164:167], v[116:119]
	v_mfma_f32_16x16x32_bf16 v[112:115], v[156:159], v[164:167], v[112:115]
	v_mfma_f32_16x16x32_bf16 v[100:103], v[148:151], v[172:175], v[100:103]
	v_mfma_f32_16x16x32_bf16 v[96:99], v[156:159], v[172:175], v[96:99]
	v_mfma_f32_16x16x32_bf16 v[84:87], v[148:151], v[180:183], v[84:87]
	v_mfma_f32_16x16x32_bf16 v[80:83], v[156:159], v[180:183], v[80:83]
	v_mfma_f32_16x16x32_bf16 v[68:71], v[148:151], v[206:209], v[68:71]
	v_mfma_f32_16x16x32_bf16 v[64:67], v[156:159], v[206:209], v[64:67]
	s_barrier
; #define PG8_STAGE(bufoff, gbase, voff) do { _Pragma("unroll") for (int _i = 0; _i < 2; ++_i) \
;         __builtin_amdgcn_global_load_lds((const unsigned*)((const char*)(gbase) + (voff)[_i]), (PG8_LAS unsigned*)(lds + (bufoff) + ldsw + _i * 8192), 16, 0, 0); } while (0)
; #define PG8_LDA(dst, b, h) do { _Pragma("unroll") for (int m = 0; m < 4; ++m) _Pragma("unroll") for (int k = 0; k < 2; ++k) dst[m][k] = *(const PG8_LAS bf16x8*)(lds + PG8_SA(b, h) + aoff + m * 2048 + k * 1024); } while (0)
; #define PG8_MMA(ai, bj, At, Bt) do { __builtin_amdgcn_s_setprio(1); _Pragma("unroll") for (int m = 0; m < 4; ++m) _Pragma("unroll") for (int n = 0; n < 2; ++n) _Pragma("unroll") for (int k = 0; k < 2; ++k) \
;         acc[ai][bj][m][n] = __builtin_amdgcn_mfma_f32_16x16x32_bf16(Bt[n][k], At[m][k], acc[ai][bj][m][n], 0, 0, 0); __builtin_amdgcn_s_setprio(0); } while (0)
; #define PG8_WAIT_V(n) asm volatile("s_waitcnt vmcnt(" #n ")" ::: "memory")
; #define PG8_WAIT_L(n) asm volatile("s_waitcnt lgkmcnt(" #n ")" ::: "memory")
; #define PG8_BAR __builtin_amdgcn_s_barrier()
; #define PG8_SCHED __builtin_amdgcn_sched_barrier(0)
; template <class Epi, class Sched, bool ALIGN_EPI = false, bool SP2 = false>
; __device__ __forceinline__ void gemm_phase(PG8_LAS unsigned char* lds, const Gemm g, const Sched& S, const Epi& E) {
;     ...
;             PG8_LDA(At, 1, 1); PG8_STAGE(PG8_SB(1, 0), b3, voffB); PG8_STAGE(PG8_SB(1, 1), b3 + hstep, voffB); PG8_STAGE(PG8_SA(1, 0), a3, voffA);
;             PG8_WAIT_V(8); PG8_WAIT_L(0); PG8_BAR; PG8_MMA(1, 0, At, B0); PG8_MMA(1, 1, At, B1); PG8_BAR; PG8_SCHED;
;     ...
;         if constexpr (ALIGN_EPI) { if (wr == 0) PG8_BAR; }
	s_setprio 0
	s_add_i32 s50, s73, s13
	v_lshl_add_u64 v[210:211], v[210:211], 0, s[20:21]
	s_mov_b32 m0, s50
	ds_read_b128 v[160:163], v222 offset:49152
	ds_read_b128 v[164:167], v222 offset:50176
	ds_read_b128 v[168:171], v222 offset:51200
	ds_read_b128 v[172:175], v222 offset:52224
	ds_read_b128 v[176:179], v222 offset:53248
	ds_read_b128 v[180:183], v222 offset:54272
	ds_read_b128 v[202:205], v222 offset:55296
	ds_read_b128 v[206:209], v222 offset:56320
	global_load_lds_dwordx4 v[210:211], off
	s_add_i32 m0, s50, 0x2000
	s_add_u32 s44, s44, 0x40080
	v_lshl_add_u64 v[210:211], v[212:213], 0, s[20:21]
	s_addc_u32 s45, s45, 0
	s_add_i32 s50, s74, s13
	global_load_lds_dwordx4 v[210:211], off
	v_lshl_add_u64 v[210:211], s[44:45], 0, v[188:189]
	s_mov_b32 m0, s50
	s_nop 0
	global_load_lds_dwordx4 v[210:211], off
	v_lshl_add_u64 v[210:211], s[44:45], 0, v[184:185]
	s_add_i32 m0, s50, 0x2000
	s_nop 0
	global_load_lds_dwordx4 v[210:211], off
	v_lshl_add_u64 v[210:211], v[214:215], 0, s[20:21]
	s_mov_b32 m0, s64
	s_nop 0
	global_load_lds_dwordx4 v[210:211], off
	v_lshl_add_u64 v[210:211], v[224:225], 0, s[20:21]
	s_mov_b32 m0, s65
	s_nop 0
	global_load_lds_dwordx4 v[210:211], off
	s_waitcnt vmcnt(8) lgkmcnt(0)
	s_setprio 1
	s_barrier
	v_mfma_f32_16x16x32_bf16 v[60:63], v[128:131], v[160:163], v[60:63]
	v_mfma_f32_16x16x32_bf16 v[56:59], v[136:139], v[160:163], v[56:59]
	v_mfma_f32_16x16x32_bf16 v[44:47], v[128:131], v[168:171], v[44:47]
	v_mfma_f32_16x16x32_bf16 v[40:43], v[136:139], v[168:171], v[40:43]
	v_mfma_f32_16x16x32_bf16 v[28:31], v[128:131], v[176:179], v[28:31]
	v_mfma_f32_16x16x32_bf16 v[24:27], v[136:139], v[176:179], v[24:27]
	v_mfma_f32_16x16x32_bf16 v[12:15], v[128:131], v[202:205], v[12:15]
	v_mfma_f32_16x16x32_bf16 v[8:11], v[136:139], v[202:205], v[8:11]
	v_mfma_f32_16x16x32_bf16 v[60:63], v[132:135], v[164:167], v[60:63]
	v_mfma_f32_16x16x32_bf16 v[56:59], v[140:143], v[164:167], v[56:59]
	v_mfma_f32_16x16x32_bf16 v[44:47], v[132:135], v[172:175], v[44:47]
	v_mfma_f32_16x16x32_bf16 v[40:43], v[140:143], v[172:175], v[40:43]
	v_mfma_f32_16x16x32_bf16 v[28:31], v[132:135], v[180:183], v[28:31]
	v_mfma_f32_16x16x32_bf16 v[24:27], v[140:143], v[180:183], v[24:27]
	v_mfma_f32_16x16x32_bf16 v[12:15], v[132:135], v[206:209], v[12:15]
	v_mfma_f32_16x16x32_bf16 v[8:11], v[140:143], v[206:209], v[8:11]
	v_mfma_f32_16x16x32_bf16 v[52:55], v[144:147], v[160:163], v[52:55]
	v_mfma_f32_16x16x32_bf16 v[48:51], v[152:155], v[160:163], v[48:51]
	v_mfma_f32_16x16x32_bf16 v[36:39], v[144:147], v[168:171], v[36:39]
	v_mfma_f32_16x16x32_bf16 v[32:35], v[152:155], v[168:171], v[32:35]
	v_mfma_f32_16x16x32_bf16 v[20:23], v[144:147], v[176:179], v[20:23]
	v_mfma_f32_16x16x32_bf16 v[16:19], v[152:155], v[176:179], v[16:19]
	v_mfma_f32_16x16x32_bf16 v[4:7], v[144:147], v[202:205], v[4:7]
	v_mfma_f32_16x16x32_bf16 v[0:3], v[152:155], v[202:205], v[0:3]
	v_mfma_f32_16x16x32_bf16 v[52:55], v[148:151], v[164:167], v[52:55]
	v_mfma_f32_16x16x32_bf16 v[48:51], v[156:159], v[164:167], v[48:51]
	v_mfma_f32_16x16x32_bf16 v[36:39], v[148:151], v[172:175], v[36:39]
	v_mfma_f32_16x16x32_bf16 v[32:35], v[156:159], v[172:175], v[32:35]
	v_mfma_f32_16x16x32_bf16 v[20:23], v[148:151], v[180:183], v[20:23]
	v_mfma_f32_16x16x32_bf16 v[16:19], v[156:159], v[180:183], v[16:19]
	v_mfma_f32_16x16x32_bf16 v[4:7], v[148:151], v[206:209], v[4:7]
	v_mfma_f32_16x16x32_bf16 v[0:3], v[156:159], v[206:209], v[0:3]
	s_barrier
	s_setprio 0
	s_add_i32 s72, s72, 2
	s_add_u32 s36, s36, 0x100
	s_addc_u32 s37, s37, 0
	s_add_u32 s70, s70, 0x100
	s_addc_u32 s71, s71, 0
	s_cmp_gt_u32 s72, 13
	s_cbranch_scc0 .LBB0_573
	s_and_b64 vcc, exec, s[22:23]
	s_cbranch_vccz .LBB0_576
	s_barrier

; #define PG8_STAGE(bufoff, gbase, voff) do { _Pragma("unroll") for (int _i = 0; _i < 2; ++_i) \
;         __builtin_amdgcn_global_load_lds((const unsigned*)((const char*)(gbase) + (voff)[_i]), (PG8_LAS unsigned*)(lds + (bufoff) + ldsw + _i * 8192), 16, 0, 0); } while (0)
; #define PG8_LDA(dst, b, h) do { _Pragma("unroll") for (int m = 0; m < 4; ++m) _Pragma("unroll") for (int k = 0; k < 2; ++k) dst[m][k] = *(const PG8_LAS bf16x8*)(lds + PG8_SA(b, h) + aoff + m * 2048 + k * 1024); } while (0)
; #define PG8_LDB(dst, b, h) do { _Pragma("unroll") for (int n = 0; n < 2; ++n) _Pragma("unroll") for (int k = 0; k < 2; ++k) dst[n][k] = *(const PG8_LAS bf16x8*)(lds + PG8_SB(b, h) + boff + n * 2048 + k * 1024); } while (0)
; #define PG8_MMA(ai, bj, At, Bt) do { __builtin_amdgcn_s_setprio(1); _Pragma("unroll") for (int m = 0; m < 4; ++m) _Pragma("unroll") for (int n = 0; n < 2; ++n) _Pragma("unroll") for (int k = 0; k < 2; ++k) \
;         acc[ai][bj][m][n] = __builtin_amdgcn_mfma_f32_16x16x32_bf16(Bt[n][k], At[m][k], acc[ai][bj][m][n], 0, 0, 0); __builtin_amdgcn_s_setprio(0); } while (0)
; #define PG8_BAR __builtin_amdgcn_s_barrier()
; template <class Epi, class Sched, bool ALIGN_EPI = false, bool SP2 = false>
; __device__ __forceinline__ void gemm_phase(PG8_LAS unsigned char* lds, const Gemm g, const Sched& S, const Epi& E) {
;     ...
;         const bool has_next = S.next(ui + 1, nxt);
;         const char* nA = has_next ? (const char*)g.A + (size_t)nxt.pm * tstep : cA; const char* nB = has_next ? (const char*)g.Bt + (size_t)nxt.pn * tstep : cB;
;         for (int t = 0; t < nt; t += 2) {
;             const bool last = (t == nt - 2);
;             const char* a1 = cA + (size_t)(t + 1) * kstep;
;             const char* a2 = last ? nA : cA + (size_t)(t + 2) * kstep; const char* b2 = last ? nB : cB + (size_t)(t + 2) * kstep;
;             const char* a3 = a2 + kstep; const char* b3 = b2 + kstep;
;             if (last && has_next) S.a_ready(nxt);
;             if constexpr (SP2) {
;             PG8_LDB(B0, 0, 0); PG8_LDB(B1, 0, 1); PG8_SCHED; PG8_LDA(At, 0, 0); PG8_STAGE(PG8_SA(1, 1), a1 + hstep, voffA);
;             PG8_WAIT_V(8); PG8_WAIT_L(0); PG8_BAR; PG8_MMA(0, 0, At, B0); PG8_MMA(0, 1, At, B1); PG8_BAR; PG8_SCHED;
;             PG8_LDA(At, 0, 1); PG8_STAGE(PG8_SB(0, 0), b2, voffB); PG8_STAGE(PG8_SB(0, 1), b2 + hstep, voffB); PG8_STAGE(PG8_SA(0, 0), a2, voffA);
.LBB0_644:
	s_ashr_i32 s27, s26, 31
	s_lshl_b64 s[28:29], s[26:27], 20
	s_add_u32 s28, s13, s28
	s_addc_u32 s29, s47, s29
	s_and_b64 s[30:31], s[38:39], exec
	s_cselect_b32 s27, s29, s37
	s_cselect_b32 s70, s28, s36
	s_ashr_i32 s25, s24, 31
	s_lshl_b64 s[30:31], s[24:25], 20
	s_add_u32 s30, s52, s30
	s_addc_u32 s31, s53, s31
	s_and_b64 s[44:45], s[38:39], exec
	s_cselect_b32 s25, s31, s41
	s_cselect_b32 s71, s30, s40
	s_add_u32 s72, s40, 0x100
	s_addc_u32 s73, s41, 0
	s_mov_b32 s74, -2
	ds_read_b128 v[92:95], v196
	ds_read_b128 v[100:103], v196 offset:1024
	ds_read_b128 v[108:111], v196 offset:2048
	ds_read_b128 v[116:119], v196 offset:3072
	ds_read_b128 v[144:147], v197
	ds_read_b128 v[148:151], v197 offset:1024
	ds_read_b128 v[152:155], v197 offset:2048
	ds_read_b128 v[156:159], v197 offset:3072
	s_add_u32 s40, s36, 0x100
	s_addc_u32 s41, s37, 0
	s_cmp_eq_u32 s74, 28
	s_cselect_b32 s51, s27, s41
	s_cselect_b32 s50, s70, s40
	s_cselect_b32 s45, s25, s73
	s_cselect_b32 s44, s71, s72
	v_lshl_add_u64 v[212:213], s[36:37], 0, v[176:177]
	s_add_i32 m0, s55, 0xc000
	ds_read_b128 v[160:163], v198
	ds_read_b128 v[164:167], v198 offset:1024
	ds_read_b128 v[168:171], v198 offset:2048
	ds_read_b128 v[184:187], v198 offset:3072
	ds_read_b128 v[188:191], v198 offset:4096
	ds_read_b128 v[200:203], v198 offset:5120
	ds_read_b128 v[204:207], v198 offset:6144
	ds_read_b128 v[208:211], v198 offset:7168
	global_load_lds_dwordx4 v[212:213], off
	v_lshl_add_u64 v[212:213], s[36:37], 0, v[178:179]
	s_add_i32 m0, s55, 0xe000
	s_nop 0
	global_load_lds_dwordx4 v[212:213], off
	s_waitcnt vmcnt(8) lgkmcnt(0)
	s_setprio 1
	s_barrier
	v_mfma_f32_16x16x32_bf16 v[140:143], v[92:95], v[160:163], 0
	v_mfma_f32_16x16x32_bf16 v[136:139], v[108:111], v[160:163], 0
	v_mfma_f32_16x16x32_bf16 v[132:135], v[92:95], v[168:171], 0
	v_mfma_f32_16x16x32_bf16 v[120:123], v[108:111], v[168:171], 0
	v_mfma_f32_16x16x32_bf16 v[112:115], v[92:95], v[188:191], 0
	v_mfma_f32_16x16x32_bf16 v[88:91], v[108:111], v[188:191], 0
	v_mfma_f32_16x16x32_bf16 v[76:79], v[92:95], v[204:207], 0
	v_mfma_f32_16x16x32_bf16 v[72:75], v[108:111], v[204:207], 0
	v_mfma_f32_16x16x32_bf16 v[140:143], v[100:103], v[164:167], v[140:143]
	v_mfma_f32_16x16x32_bf16 v[136:139], v[116:119], v[164:167], v[136:139]
	v_mfma_f32_16x16x32_bf16 v[132:135], v[100:103], v[184:187], v[132:135]
	v_mfma_f32_16x16x32_bf16 v[120:123], v[116:119], v[184:187], v[120:123]
	v_mfma_f32_16x16x32_bf16 v[112:115], v[100:103], v[200:203], v[112:115]
	v_mfma_f32_16x16x32_bf16 v[88:91], v[116:119], v[200:203], v[88:91]
	v_mfma_f32_16x16x32_bf16 v[76:79], v[100:103], v[208:211], v[76:79]
	v_mfma_f32_16x16x32_bf16 v[72:75], v[116:119], v[208:211], v[72:75]
	v_mfma_f32_16x16x32_bf16 v[128:131], v[144:147], v[160:163], 0
	v_mfma_f32_16x16x32_bf16 v[124:127], v[152:155], v[160:163], 0
	v_mfma_f32_16x16x32_bf16 v[104:107], v[144:147], v[168:171], 0
	v_mfma_f32_16x16x32_bf16 v[96:99], v[152:155], v[168:171], 0
	v_mfma_f32_16x16x32_bf16 v[84:87], v[144:147], v[188:191], 0
	v_mfma_f32_16x16x32_bf16 v[80:83], v[152:155], v[188:191], 0
	v_mfma_f32_16x16x32_bf16 v[68:71], v[144:147], v[204:207], 0
	v_mfma_f32_16x16x32_bf16 v[64:67], v[152:155], v[204:207], 0
	v_mfma_f32_16x16x32_bf16 v[128:131], v[148:151], v[164:167], v[128:131]
	v_mfma_f32_16x16x32_bf16 v[124:127], v[156:159], v[164:167], v[124:127]
	v_mfma_f32_16x16x32_bf16 v[104:107], v[148:151], v[184:187], v[104:107]
	v_mfma_f32_16x16x32_bf16 v[96:99], v[156:159], v[184:187], v[96:99]
	v_mfma_f32_16x16x32_bf16 v[84:87], v[148:151], v[200:203], v[84:87]
	v_mfma_f32_16x16x32_bf16 v[80:83], v[156:159], v[200:203], v[80:83]
	v_mfma_f32_16x16x32_bf16 v[68:71], v[148:151], v[208:211], v[68:71]
	v_mfma_f32_16x16x32_bf16 v[64:67], v[156:159], v[208:211], v[64:67]
	s_barrier
	s_setprio 0
	s_add_i32 s36, s68, s54
	v_lshl_add_u64 v[212:213], s[44:45], 0, v[174:175]
	s_mov_b32 m0, s36
	ds_read_b128 v[160:163], v198 offset:16384
	ds_read_b128 v[164:167], v198 offset:17408
	ds_read_b128 v[168:171], v198 offset:18432
	ds_read_b128 v[184:187], v198 offset:19456
	ds_read_b128 v[188:191], v198 offset:20480
	ds_read_b128 v[200:203], v198 offset:21504
	ds_read_b128 v[204:207], v198 offset:22528
	ds_read_b128 v[208:211], v198 offset:23552
	global_load_lds_dwordx4 v[212:213], off
	s_add_i32 m0, s36, 0x2000
	s_add_u32 s36, s44, 0x80000
	v_lshl_add_u64 v[214:215], s[44:45], 0, v[172:173]
	s_addc_u32 s37, s45, 0
	s_add_i32 s75, s69, s54
	global_load_lds_dwordx4 v[214:215], off
	v_lshl_add_u64 v[218:219], s[36:37], 0, v[174:175]
	s_mov_b32 m0, s75
	v_lshl_add_u64 v[220:221], s[50:51], 0, v[172:173]
	global_load_lds_dwordx4 v[218:219], off
	v_lshl_add_u64 v[218:219], s[36:37], 0, v[172:173]
	s_add_i32 m0, s75, 0x2000
	s_nop 0
	global_load_lds_dwordx4 v[218:219], off
	v_lshl_add_u64 v[218:219], s[50:51], 0, v[174:175]
	s_mov_b32 m0, s55
	s_nop 0
	global_load_lds_dwordx4 v[218:219], off
	s_mov_b32 m0, s60
	s_nop 0
	global_load_lds_dwordx4 v[220:221], off
	s_waitcnt vmcnt(8) lgkmcnt(0)
	s_setprio 1
	s_barrier
; #define PG8_STAGE(bufoff, gbase, voff) do { _Pragma("unroll") for (int _i = 0; _i < 2; ++_i) \
;         __builtin_amdgcn_global_load_lds((const unsigned*)((const char*)(gbase) + (voff)[_i]), (PG8_LAS unsigned*)(lds + (bufoff) + ldsw + _i * 8192), 16, 0, 0); } while (0)
; #define PG8_LDA(dst, b, h) do { _Pragma("unroll") for (int m = 0; m < 4; ++m) _Pragma("unroll") for (int k = 0; k < 2; ++k) dst[m][k] = *(const PG8_LAS bf16x8*)(lds + PG8_SA(b, h) + aoff + m * 2048 + k * 1024); } while (0)
; #define PG8_LDB(dst, b, h) do { _Pragma("unroll") for (int n = 0; n < 2; ++n) _Pragma("unroll") for (int k = 0; k < 2; ++k) dst[n][k] = *(const PG8_LAS bf16x8*)(lds + PG8_SB(b, h) + boff + n * 2048 + k * 1024); } while (0)
; #define PG8_MMA(ai, bj, At, Bt) do { __builtin_amdgcn_s_setprio(1); _Pragma("unroll") for (int m = 0; m < 4; ++m) _Pragma("unroll") for (int n = 0; n < 2; ++n) _Pragma("unroll") for (int k = 0; k < 2; ++k) \
;         acc[ai][bj][m][n] = __builtin_amdgcn_mfma_f32_16x16x32_bf16(Bt[n][k], At[m][k], acc[ai][bj][m][n], 0, 0, 0); __builtin_amdgcn_s_setprio(0); } while (0)
; #define PG8_WAIT_V(n) asm volatile("s_waitcnt vmcnt(" #n ")" ::: "memory")
; #define PG8_WAIT_L(n) asm volatile("s_waitcnt lgkmcnt(" #n ")" ::: "memory")
; #define PG8_BAR __builtin_amdgcn_s_barrier()
; #define PG8_SCHED __builtin_amdgcn_sched_barrier(0)
; template <class Epi, class Sched, bool ALIGN_EPI = false, bool SP2 = false>
; __device__ __forceinline__ void gemm_phase(PG8_LAS unsigned char* lds, const Gemm g, const Sched& S, const Epi& E) {
;     ...
;             PG8_WAIT_V(8); PG8_WAIT_L(0); PG8_BAR; PG8_MMA(1, 0, At, B0); PG8_MMA(1, 1, At, B1); PG8_BAR; PG8_SCHED;
;             PG8_LDB(B0, 1, 0); PG8_LDB(B1, 1, 1); PG8_SCHED; PG8_LDA(At, 1, 0); PG8_STAGE(PG8_SA(0, 1), a2 + hstep, voffA);
;             PG8_WAIT_V(8); PG8_WAIT_L(0); PG8_BAR; PG8_MMA(0, 0, At, B0); PG8_MMA(0, 1, At, B1); PG8_BAR; PG8_SCHED;
	v_mfma_f32_16x16x32_bf16 v[60:63], v[92:95], v[160:163], 0
	v_mfma_f32_16x16x32_bf16 v[56:59], v[108:111], v[160:163], 0
	v_mfma_f32_16x16x32_bf16 v[52:55], v[92:95], v[168:171], 0
	v_mfma_f32_16x16x32_bf16 v[40:43], v[108:111], v[168:171], 0
	v_mfma_f32_16x16x32_bf16 v[36:39], v[92:95], v[188:191], 0
	v_mfma_f32_16x16x32_bf16 v[24:27], v[108:111], v[188:191], 0
	v_mfma_f32_16x16x32_bf16 v[12:15], v[92:95], v[204:207], 0
	v_mfma_f32_16x16x32_bf16 v[8:11], v[108:111], v[204:207], 0
	v_mfma_f32_16x16x32_bf16 v[60:63], v[100:103], v[164:167], v[60:63]
	v_mfma_f32_16x16x32_bf16 v[56:59], v[116:119], v[164:167], v[56:59]
	v_mfma_f32_16x16x32_bf16 v[52:55], v[100:103], v[184:187], v[52:55]
	v_mfma_f32_16x16x32_bf16 v[40:43], v[116:119], v[184:187], v[40:43]
	v_mfma_f32_16x16x32_bf16 v[36:39], v[100:103], v[200:203], v[36:39]
	v_mfma_f32_16x16x32_bf16 v[24:27], v[116:119], v[200:203], v[24:27]
	v_mfma_f32_16x16x32_bf16 v[12:15], v[100:103], v[208:211], v[12:15]
	v_mfma_f32_16x16x32_bf16 v[8:11], v[116:119], v[208:211], v[8:11]
	v_mfma_f32_16x16x32_bf16 v[48:51], v[144:147], v[160:163], 0
	v_mfma_f32_16x16x32_bf16 v[44:47], v[152:155], v[160:163], 0
	v_mfma_f32_16x16x32_bf16 v[32:35], v[144:147], v[168:171], 0
	v_mfma_f32_16x16x32_bf16 v[28:31], v[152:155], v[168:171], 0
	v_mfma_f32_16x16x32_bf16 v[20:23], v[144:147], v[188:191], 0
	v_mfma_f32_16x16x32_bf16 v[16:19], v[152:155], v[188:191], 0
	v_mfma_f32_16x16x32_bf16 v[4:7], v[144:147], v[204:207], 0
	v_mfma_f32_16x16x32_bf16 v[0:3], v[152:155], v[204:207], 0
	v_mfma_f32_16x16x32_bf16 v[48:51], v[148:151], v[164:167], v[48:51]
	v_mfma_f32_16x16x32_bf16 v[44:47], v[156:159], v[164:167], v[44:47]
	v_mfma_f32_16x16x32_bf16 v[32:35], v[148:151], v[184:187], v[32:35]
	v_mfma_f32_16x16x32_bf16 v[28:31], v[156:159], v[184:187], v[28:31]
	v_mfma_f32_16x16x32_bf16 v[20:23], v[148:151], v[200:203], v[20:23]
	v_mfma_f32_16x16x32_bf16 v[16:19], v[156:159], v[200:203], v[16:19]
	v_mfma_f32_16x16x32_bf16 v[4:7], v[148:151], v[208:211], v[4:7]
	v_mfma_f32_16x16x32_bf16 v[0:3], v[156:159], v[208:211], v[0:3]
	s_barrier
	s_setprio 0
	s_add_i32 s75, 0, 0x18000
	s_add_i32 s76, 0, 0x1c000
	v_add_u32_e32 v116, s75, v194
	v_add_u32_e32 v156, s76, v194
	ds_read_b128 v[92:95], v116
	ds_read_b128 v[100:103], v116 offset:1024
	ds_read_b128 v[108:111], v116 offset:2048
	ds_read_b128 v[116:119], v116 offset:3072
	ds_read_b128 v[144:147], v156
	ds_read_b128 v[148:151], v156 offset:1024
	ds_read_b128 v[152:155], v156 offset:2048
	ds_read_b128 v[156:159], v156 offset:3072
	s_add_u32 s36, s50, 0x80000
	s_addc_u32 s37, s51, 0
	s_mov_b32 m0, s61
	v_lshl_add_u64 v[222:223], s[36:37], 0, v[174:175]
	ds_read_b128 v[160:163], v198 offset:32768
	ds_read_b128 v[164:167], v198 offset:33792
	ds_read_b128 v[168:171], v198 offset:34816
	ds_read_b128 v[184:187], v198 offset:35840
	ds_read_b128 v[188:191], v198 offset:36864
	ds_read_b128 v[200:203], v198 offset:37888
	ds_read_b128 v[204:207], v198 offset:38912
	ds_read_b128 v[208:211], v198 offset:39936
	global_load_lds_dwordx4 v[222:223], off
	v_lshl_add_u64 v[222:223], s[36:37], 0, v[172:173]
	s_mov_b32 m0, s62
	s_nop 0
	global_load_lds_dwordx4 v[222:223], off
	s_waitcnt vmcnt(8) lgkmcnt(0)
	s_setprio 1
	s_barrier
	v_mfma_f32_16x16x32_bf16 v[140:143], v[92:95], v[160:163], v[140:143]
	v_mfma_f32_16x16x32_bf16 v[136:139], v[108:111], v[160:163], v[136:139]
	v_mfma_f32_16x16x32_bf16 v[132:135], v[92:95], v[168:171], v[132:135]
	v_mfma_f32_16x16x32_bf16 v[120:123], v[108:111], v[168:171], v[120:123]
	v_mfma_f32_16x16x32_bf16 v[112:115], v[92:95], v[188:191], v[112:115]
	v_mfma_f32_16x16x32_bf16 v[88:91], v[108:111], v[188:191], v[88:91]
	v_mfma_f32_16x16x32_bf16 v[76:79], v[92:95], v[204:207], v[76:79]
	v_mfma_f32_16x16x32_bf16 v[72:75], v[108:111], v[204:207], v[72:75]
	v_mfma_f32_16x16x32_bf16 v[140:143], v[100:103], v[164:167], v[140:143]
	v_mfma_f32_16x16x32_bf16 v[136:139], v[116:119], v[164:167], v[136:139]
	v_mfma_f32_16x16x32_bf16 v[132:135], v[100:103], v[184:187], v[132:135]
	v_mfma_f32_16x16x32_bf16 v[120:123], v[116:119], v[184:187], v[120:123]
	v_mfma_f32_16x16x32_bf16 v[112:115], v[100:103], v[200:203], v[112:115]
	v_mfma_f32_16x16x32_bf16 v[88:91], v[116:119], v[200:203], v[88:91]
	v_mfma_f32_16x16x32_bf16 v[76:79], v[100:103], v[208:211], v[76:79]
	v_mfma_f32_16x16x32_bf16 v[72:75], v[116:119], v[208:211], v[72:75]
	v_mfma_f32_16x16x32_bf16 v[128:131], v[144:147], v[160:163], v[128:131]
	v_mfma_f32_16x16x32_bf16 v[124:127], v[152:155], v[160:163], v[124:127]
	v_mfma_f32_16x16x32_bf16 v[104:107], v[144:147], v[168:171], v[104:107]
	v_mfma_f32_16x16x32_bf16 v[96:99], v[152:155], v[168:171], v[96:99]
	v_mfma_f32_16x16x32_bf16 v[84:87], v[144:147], v[188:191], v[84:87]
	v_mfma_f32_16x16x32_bf16 v[80:83], v[152:155], v[188:191], v[80:83]
	v_mfma_f32_16x16x32_bf16 v[68:71], v[144:147], v[204:207], v[68:71]
	v_mfma_f32_16x16x32_bf16 v[64:67], v[152:155], v[204:207], v[64:67]
	v_mfma_f32_16x16x32_bf16 v[128:131], v[148:151], v[164:167], v[128:131]
	v_mfma_f32_16x16x32_bf16 v[124:127], v[156:159], v[164:167], v[124:127]
	v_mfma_f32_16x16x32_bf16 v[104:107], v[148:151], v[184:187], v[104:107]
	v_mfma_f32_16x16x32_bf16 v[96:99], v[156:159], v[184:187], v[96:99]
	v_mfma_f32_16x16x32_bf16 v[84:87], v[148:151], v[200:203], v[84:87]
	v_mfma_f32_16x16x32_bf16 v[80:83], v[156:159], v[200:203], v[80:83]
	v_mfma_f32_16x16x32_bf16 v[68:71], v[148:151], v[208:211], v[68:71]
	v_mfma_f32_16x16x32_bf16 v[64:67], v[156:159], v[208:211], v[64:67]
	s_barrier
; #define PG8_STAGE(bufoff, gbase, voff) do { _Pragma("unroll") for (int _i = 0; _i < 2; ++_i) \
;         __builtin_amdgcn_global_load_lds((const unsigned*)((const char*)(gbase) + (voff)[_i]), (PG8_LAS unsigned*)(lds + (bufoff) + ldsw + _i * 8192), 16, 0, 0); } while (0)
; #define PG8_LDA(dst, b, h) do { _Pragma("unroll") for (int m = 0; m < 4; ++m) _Pragma("unroll") for (int k = 0; k < 2; ++k) dst[m][k] = *(const PG8_LAS bf16x8*)(lds + PG8_SA(b, h) + aoff + m * 2048 + k * 1024); } while (0)
; #define PG8_LDB(dst, b, h) do { _Pragma("unroll") for (int n = 0; n < 2; ++n) _Pragma("unroll") for (int k = 0; k < 2; ++k) dst[n][k] = *(const PG8_LAS bf16x8*)(lds + PG8_SB(b, h) + boff + n * 2048 + k * 1024); } while (0)
; #define PG8_MMA(ai, bj, At, Bt) do { __builtin_amdgcn_s_setprio(1); _Pragma("unroll") for (int m = 0; m < 4; ++m) _Pragma("unroll") for (int n = 0; n < 2; ++n) _Pragma("unroll") for (int k = 0; k < 2; ++k) \
;         acc[ai][bj][m][n] = __builtin_amdgcn_mfma_f32_16x16x32_bf16(Bt[n][k], At[m][k], acc[ai][bj][m][n], 0, 0, 0); __builtin_amdgcn_s_setprio(0); } while (0)
; #define PG8_WAIT_V(n) asm volatile("s_waitcnt vmcnt(" #n ")" ::: "memory")
; template <class Epi, class Sched, bool ALIGN_EPI = false, bool SP2 = false>
; __device__ __forceinline__ void gemm_phase(PG8_LAS unsigned char* lds, const Gemm g, const Sched& S, const Epi& E) {
;     ...
;             PG8_LDB(B0, 0, 0); PG8_LDB(B1, 0, 1); PG8_SCHED; PG8_LDA(At, 0, 0); PG8_STAGE(PG8_SA(1, 1), a1 + hstep, voffA);
;             PG8_WAIT_V(8); PG8_WAIT_L(0); PG8_BAR; PG8_MMA(0, 0, At, B0); PG8_MMA(0, 1, At, B1); PG8_BAR; PG8_SCHED;
;             PG8_LDA(At, 0, 1); PG8_STAGE(PG8_SB(0, 0), b2, voffB); PG8_STAGE(PG8_SB(0, 1), b2 + hstep, voffB); PG8_STAGE(PG8_SA(0, 0), a2, voffA);
;             PG8_WAIT_V(8); PG8_WAIT_L(0); PG8_BAR; PG8_MMA(1, 0, At, B0); PG8_MMA(1, 1, At, B1); PG8_BAR; PG8_SCHED;
;             PG8_LDB(B0, 1, 0); PG8_LDB(B1, 1, 1); PG8_SCHED; PG8_LDA(At, 1, 0); PG8_STAGE(PG8_SA(0, 1), a2 + hstep, voffA);
;             PG8_WAIT_V(8); PG8_WAIT_L(0); PG8_BAR; PG8_MMA(0, 0, At, B0); PG8_MMA(0, 1, At, B1); PG8_BAR; PG8_SCHED;
;             PG8_LDA(At, 1, 1); PG8_STAGE(PG8_SB(1, 0), b3, voffB); PG8_STAGE(PG8_SB(1, 1), b3 + hstep, voffB); PG8_STAGE(PG8_SA(1, 0), a3, voffA);
;             PG8_WAIT_V(8); PG8_WAIT_L(0); PG8_BAR; PG8_MMA(1, 0, At, B0); PG8_MMA(1, 1, At, B1); PG8_BAR; PG8_SCHED;
	s_setprio 0
	s_add_i32 s36, s75, s54
	v_lshl_add_u64 v[212:213], v[212:213], 0, s[20:21]
	s_mov_b32 m0, s36
	ds_read_b128 v[160:163], v198 offset:49152
	ds_read_b128 v[164:167], v198 offset:50176
	ds_read_b128 v[168:171], v198 offset:51200
	ds_read_b128 v[184:187], v198 offset:52224
	ds_read_b128 v[188:191], v198 offset:53248
	ds_read_b128 v[200:203], v198 offset:54272
	ds_read_b128 v[204:207], v198 offset:55296
	ds_read_b128 v[208:211], v198 offset:56320
	global_load_lds_dwordx4 v[212:213], off
	s_add_i32 m0, s36, 0x2000
	s_add_u32 s36, s44, 0x80080
	v_lshl_add_u64 v[212:213], v[214:215], 0, s[20:21]
	s_addc_u32 s37, s45, 0
	s_add_i32 s44, s76, s54
	global_load_lds_dwordx4 v[212:213], off
	v_lshl_add_u64 v[212:213], s[36:37], 0, v[174:175]
	s_mov_b32 m0, s44
	s_nop 0
	global_load_lds_dwordx4 v[212:213], off
	v_lshl_add_u64 v[212:213], s[36:37], 0, v[172:173]
	s_add_i32 m0, s44, 0x2000
	s_nop 0
	global_load_lds_dwordx4 v[212:213], off
	v_lshl_add_u64 v[212:213], v[218:219], 0, s[20:21]
	s_mov_b32 m0, s66
	s_nop 0
	global_load_lds_dwordx4 v[212:213], off
	v_lshl_add_u64 v[212:213], v[220:221], 0, s[20:21]
	s_mov_b32 m0, s67
	s_nop 0
	global_load_lds_dwordx4 v[212:213], off
	s_waitcnt vmcnt(8) lgkmcnt(0)
	s_setprio 1
	s_barrier
	v_mfma_f32_16x16x32_bf16 v[60:63], v[92:95], v[160:163], v[60:63]
	v_mfma_f32_16x16x32_bf16 v[56:59], v[108:111], v[160:163], v[56:59]
	v_mfma_f32_16x16x32_bf16 v[52:55], v[92:95], v[168:171], v[52:55]
	v_mfma_f32_16x16x32_bf16 v[40:43], v[108:111], v[168:171], v[40:43]
	v_mfma_f32_16x16x32_bf16 v[36:39], v[92:95], v[188:191], v[36:39]
	v_mfma_f32_16x16x32_bf16 v[24:27], v[108:111], v[188:191], v[24:27]
	v_mfma_f32_16x16x32_bf16 v[12:15], v[92:95], v[204:207], v[12:15]
	v_mfma_f32_16x16x32_bf16 v[8:11], v[108:111], v[204:207], v[8:11]
	v_mfma_f32_16x16x32_bf16 v[60:63], v[100:103], v[164:167], v[60:63]
	v_mfma_f32_16x16x32_bf16 v[56:59], v[116:119], v[164:167], v[56:59]
	v_mfma_f32_16x16x32_bf16 v[52:55], v[100:103], v[184:187], v[52:55]
	v_mfma_f32_16x16x32_bf16 v[40:43], v[116:119], v[184:187], v[40:43]
	v_mfma_f32_16x16x32_bf16 v[36:39], v[100:103], v[200:203], v[36:39]
	v_mfma_f32_16x16x32_bf16 v[24:27], v[116:119], v[200:203], v[24:27]
	v_mfma_f32_16x16x32_bf16 v[12:15], v[100:103], v[208:211], v[12:15]
	v_mfma_f32_16x16x32_bf16 v[8:11], v[116:119], v[208:211], v[8:11]
	v_mfma_f32_16x16x32_bf16 v[48:51], v[144:147], v[160:163], v[48:51]
	v_mfma_f32_16x16x32_bf16 v[44:47], v[152:155], v[160:163], v[44:47]
	v_mfma_f32_16x16x32_bf16 v[32:35], v[144:147], v[168:171], v[32:35]
	v_mfma_f32_16x16x32_bf16 v[28:31], v[152:155], v[168:171], v[28:31]
	v_mfma_f32_16x16x32_bf16 v[20:23], v[144:147], v[188:191], v[20:23]
	v_mfma_f32_16x16x32_bf16 v[16:19], v[152:155], v[188:191], v[16:19]
	v_mfma_f32_16x16x32_bf16 v[4:7], v[144:147], v[204:207], v[4:7]
	v_mfma_f32_16x16x32_bf16 v[0:3], v[152:155], v[204:207], v[0:3]
	v_mfma_f32_16x16x32_bf16 v[48:51], v[148:151], v[164:167], v[48:51]
	v_mfma_f32_16x16x32_bf16 v[44:47], v[156:159], v[164:167], v[44:47]
	v_mfma_f32_16x16x32_bf16 v[32:35], v[148:151], v[184:187], v[32:35]
	v_mfma_f32_16x16x32_bf16 v[28:31], v[156:159], v[184:187], v[28:31]
	v_mfma_f32_16x16x32_bf16 v[20:23], v[148:151], v[200:203], v[20:23]
	v_mfma_f32_16x16x32_bf16 v[16:19], v[156:159], v[200:203], v[16:19]
	v_mfma_f32_16x16x32_bf16 v[4:7], v[148:151], v[208:211], v[4:7]
	v_mfma_f32_16x16x32_bf16 v[0:3], v[156:159], v[208:211], v[0:3]
	s_barrier
	s_setprio 0
	s_add_i32 s74, s74, 2
	s_add_u32 s72, s72, 0x100
	s_addc_u32 s73, s73, 0
	s_cmp_gt_u32 s74, 29
	s_mov_b64 s[36:37], s[40:41]
.LBB0_645:
	ds_read_b128 v[92:95], v196
	ds_read_b128 v[100:103], v196 offset:1024
	ds_read_b128 v[108:111], v196 offset:2048
	ds_read_b128 v[116:119], v196 offset:3072
	ds_read_b128 v[144:147], v197
	ds_read_b128 v[148:151], v197 offset:1024
	ds_read_b128 v[152:155], v197 offset:2048
	ds_read_b128 v[156:159], v197 offset:3072
	s_add_u32 s40, s36, 0x100
	s_addc_u32 s41, s37, 0
	s_cmp_eq_u32 s74, 28
	s_cselect_b32 s51, s27, s41
	s_cselect_b32 s50, s70, s40
	s_cselect_b32 s45, s25, s73
	s_cselect_b32 s44, s71, s72
	v_lshl_add_u64 v[212:213], s[36:37], 0, v[176:177]
	s_add_i32 m0, s55, 0xc000
	ds_read_b128 v[160:163], v198
	ds_read_b128 v[164:167], v198 offset:1024
	ds_read_b128 v[168:171], v198 offset:2048
	ds_read_b128 v[184:187], v198 offset:3072
	ds_read_b128 v[188:191], v198 offset:4096
	ds_read_b128 v[200:203], v198 offset:5120
	ds_read_b128 v[204:207], v198 offset:6144
	ds_read_b128 v[208:211], v198 offset:7168
	global_load_lds_dwordx4 v[212:213], off
	v_lshl_add_u64 v[212:213], s[36:37], 0, v[178:179]
	s_add_i32 m0, s55, 0xe000
	s_nop 0
	global_load_lds_dwordx4 v[212:213], off
	s_waitcnt vmcnt(8) lgkmcnt(0)
	s_setprio 1
	s_barrier
; #define PG8_STAGE(bufoff, gbase, voff) do { _Pragma("unroll") for (int _i = 0; _i < 2; ++_i) \
;         __builtin_amdgcn_global_load_lds((const unsigned*)((const char*)(gbase) + (voff)[_i]), (PG8_LAS unsigned*)(lds + (bufoff) + ldsw + _i * 8192), 16, 0, 0); } while (0)
; #define PG8_LDA(dst, b, h) do { _Pragma("unroll") for (int m = 0; m < 4; ++m) _Pragma("unroll") for (int k = 0; k < 2; ++k) dst[m][k] = *(const PG8_LAS bf16x8*)(lds + PG8_SA(b, h) + aoff + m * 2048 + k * 1024); } while (0)
; #define PG8_MMA(ai, bj, At, Bt) do { __builtin_amdgcn_s_setprio(1); _Pragma("unroll") for (int m = 0; m < 4; ++m) _Pragma("unroll") for (int n = 0; n < 2; ++n) _Pragma("unroll") for (int k = 0; k < 2; ++k) \
;         acc[ai][bj][m][n] = __builtin_amdgcn_mfma_f32_16x16x32_bf16(Bt[n][k], At[m][k], acc[ai][bj][m][n], 0, 0, 0); __builtin_amdgcn_s_setprio(0); } while (0)
; #define PG8_WAIT_V(n) asm volatile("s_waitcnt vmcnt(" #n ")" ::: "memory")
; #define PG8_WAIT_L(n) asm volatile("s_waitcnt lgkmcnt(" #n ")" ::: "memory")
; #define PG8_BAR __builtin_amdgcn_s_barrier()
; #define PG8_SCHED __builtin_amdgcn_sched_barrier(0)
; template <class Epi, class Sched, bool ALIGN_EPI = false, bool SP2 = false>
; __device__ __forceinline__ void gemm_phase(PG8_LAS unsigned char* lds, const Gemm g, const Sched& S, const Epi& E) {
;     ...
;             PG8_WAIT_V(8); PG8_WAIT_L(0); PG8_BAR; PG8_MMA(0, 0, At, B0); PG8_MMA(0, 1, At, B1); PG8_BAR; PG8_SCHED;
;             PG8_LDA(At, 0, 1); PG8_STAGE(PG8_SB(0, 0), b2, voffB); PG8_STAGE(PG8_SB(0, 1), b2 + hstep, voffB); PG8_STAGE(PG8_SA(0, 0), a2, voffA);
;             PG8_WAIT_V(8); PG8_WAIT_L(0); PG8_BAR; PG8_MMA(1, 0, At, B0); PG8_MMA(1, 1, At, B1); PG8_BAR; PG8_SCHED;
	v_mfma_f32_16x16x32_bf16 v[140:143], v[92:95], v[160:163], v[140:143]
	v_mfma_f32_16x16x32_bf16 v[136:139], v[108:111], v[160:163], v[136:139]
	v_mfma_f32_16x16x32_bf16 v[132:135], v[92:95], v[168:171], v[132:135]
	v_mfma_f32_16x16x32_bf16 v[120:123], v[108:111], v[168:171], v[120:123]
	v_mfma_f32_16x16x32_bf16 v[112:115], v[92:95], v[188:191], v[112:115]
	v_mfma_f32_16x16x32_bf16 v[88:91], v[108:111], v[188:191], v[88:91]
	v_mfma_f32_16x16x32_bf16 v[76:79], v[92:95], v[204:207], v[76:79]
	v_mfma_f32_16x16x32_bf16 v[72:75], v[108:111], v[204:207], v[72:75]
	v_mfma_f32_16x16x32_bf16 v[140:143], v[100:103], v[164:167], v[140:143]
	v_mfma_f32_16x16x32_bf16 v[136:139], v[116:119], v[164:167], v[136:139]
	v_mfma_f32_16x16x32_bf16 v[132:135], v[100:103], v[184:187], v[132:135]
	v_mfma_f32_16x16x32_bf16 v[120:123], v[116:119], v[184:187], v[120:123]
	v_mfma_f32_16x16x32_bf16 v[112:115], v[100:103], v[200:203], v[112:115]
	v_mfma_f32_16x16x32_bf16 v[88:91], v[116:119], v[200:203], v[88:91]
	v_mfma_f32_16x16x32_bf16 v[76:79], v[100:103], v[208:211], v[76:79]
	v_mfma_f32_16x16x32_bf16 v[72:75], v[116:119], v[208:211], v[72:75]
	v_mfma_f32_16x16x32_bf16 v[128:131], v[144:147], v[160:163], v[128:131]
	v_mfma_f32_16x16x32_bf16 v[124:127], v[152:155], v[160:163], v[124:127]
	v_mfma_f32_16x16x32_bf16 v[104:107], v[144:147], v[168:171], v[104:107]
	v_mfma_f32_16x16x32_bf16 v[96:99], v[152:155], v[168:171], v[96:99]
	v_mfma_f32_16x16x32_bf16 v[84:87], v[144:147], v[188:191], v[84:87]
	v_mfma_f32_16x16x32_bf16 v[80:83], v[152:155], v[188:191], v[80:83]
	v_mfma_f32_16x16x32_bf16 v[68:71], v[144:147], v[204:207], v[68:71]
	v_mfma_f32_16x16x32_bf16 v[64:67], v[152:155], v[204:207], v[64:67]
	v_mfma_f32_16x16x32_bf16 v[128:131], v[148:151], v[164:167], v[128:131]
	v_mfma_f32_16x16x32_bf16 v[124:127], v[156:159], v[164:167], v[124:127]
	v_mfma_f32_16x16x32_bf16 v[104:107], v[148:151], v[184:187], v[104:107]
	v_mfma_f32_16x16x32_bf16 v[96:99], v[156:159], v[184:187], v[96:99]
	v_mfma_f32_16x16x32_bf16 v[84:87], v[148:151], v[200:203], v[84:87]
	v_mfma_f32_16x16x32_bf16 v[80:83], v[156:159], v[200:203], v[80:83]
	v_mfma_f32_16x16x32_bf16 v[68:71], v[148:151], v[208:211], v[68:71]
	v_mfma_f32_16x16x32_bf16 v[64:67], v[156:159], v[208:211], v[64:67]
	s_barrier
	s_setprio 0
	s_add_i32 s36, s68, s54
	v_lshl_add_u64 v[212:213], s[44:45], 0, v[174:175]
	s_mov_b32 m0, s36
	ds_read_b128 v[160:163], v198 offset:16384
	ds_read_b128 v[164:167], v198 offset:17408
	ds_read_b128 v[168:171], v198 offset:18432
	ds_read_b128 v[184:187], v198 offset:19456
	ds_read_b128 v[188:191], v198 offset:20480
	ds_read_b128 v[200:203], v198 offset:21504
	ds_read_b128 v[204:207], v198 offset:22528
	ds_read_b128 v[208:211], v198 offset:23552
	global_load_lds_dwordx4 v[212:213], off
	s_add_i32 m0, s36, 0x2000
	s_add_u32 s36, s44, 0x80000
	v_lshl_add_u64 v[214:215], s[44:45], 0, v[172:173]
	s_addc_u32 s37, s45, 0
	s_add_i32 s75, s69, s54
	global_load_lds_dwordx4 v[214:215], off
	v_lshl_add_u64 v[218:219], s[36:37], 0, v[174:175]
	s_mov_b32 m0, s75
	v_lshl_add_u64 v[220:221], s[50:51], 0, v[172:173]
	global_load_lds_dwordx4 v[218:219], off
	v_lshl_add_u64 v[218:219], s[36:37], 0, v[172:173]
	s_add_i32 m0, s75, 0x2000
	s_nop 0
	global_load_lds_dwordx4 v[218:219], off
	v_lshl_add_u64 v[218:219], s[50:51], 0, v[174:175]
	s_mov_b32 m0, s55
	s_nop 0
	global_load_lds_dwordx4 v[218:219], off
	s_mov_b32 m0, s60
	s_nop 0
	global_load_lds_dwordx4 v[220:221], off
	s_waitcnt vmcnt(8) lgkmcnt(0)
	s_setprio 1
	s_barrier
	v_mfma_f32_16x16x32_bf16 v[60:63], v[92:95], v[160:163], v[60:63]
	v_mfma_f32_16x16x32_bf16 v[56:59], v[108:111], v[160:163], v[56:59]
	v_mfma_f32_16x16x32_bf16 v[52:55], v[92:95], v[168:171], v[52:55]
	v_mfma_f32_16x16x32_bf16 v[40:43], v[108:111], v[168:171], v[40:43]
	v_mfma_f32_16x16x32_bf16 v[36:39], v[92:95], v[188:191], v[36:39]
	v_mfma_f32_16x16x32_bf16 v[24:27], v[108:111], v[188:191], v[24:27]
	v_mfma_f32_16x16x32_bf16 v[12:15], v[92:95], v[204:207], v[12:15]
	v_mfma_f32_16x16x32_bf16 v[8:11], v[108:111], v[204:207], v[8:11]
	v_mfma_f32_16x16x32_bf16 v[60:63], v[100:103], v[164:167], v[60:63]
	v_mfma_f32_16x16x32_bf16 v[56:59], v[116:119], v[164:167], v[56:59]
	v_mfma_f32_16x16x32_bf16 v[52:55], v[100:103], v[184:187], v[52:55]
	v_mfma_f32_16x16x32_bf16 v[40:43], v[116:119], v[184:187], v[40:43]
	v_mfma_f32_16x16x32_bf16 v[36:39], v[100:103], v[200:203], v[36:39]
	v_mfma_f32_16x16x32_bf16 v[24:27], v[116:119], v[200:203], v[24:27]
	v_mfma_f32_16x16x32_bf16 v[12:15], v[100:103], v[208:211], v[12:15]
	v_mfma_f32_16x16x32_bf16 v[8:11], v[116:119], v[208:211], v[8:11]
	v_mfma_f32_16x16x32_bf16 v[48:51], v[144:147], v[160:163], v[48:51]
	v_mfma_f32_16x16x32_bf16 v[44:47], v[152:155], v[160:163], v[44:47]
	v_mfma_f32_16x16x32_bf16 v[32:35], v[144:147], v[168:171], v[32:35]
	v_mfma_f32_16x16x32_bf16 v[28:31], v[152:155], v[168:171], v[28:31]
	v_mfma_f32_16x16x32_bf16 v[20:23], v[144:147], v[188:191], v[20:23]
	v_mfma_f32_16x16x32_bf16 v[16:19], v[152:155], v[188:191], v[16:19]
	v_mfma_f32_16x16x32_bf16 v[4:7], v[144:147], v[204:207], v[4:7]
	v_mfma_f32_16x16x32_bf16 v[0:3], v[152:155], v[204:207], v[0:3]
	v_mfma_f32_16x16x32_bf16 v[48:51], v[148:151], v[164:167], v[48:51]
	v_mfma_f32_16x16x32_bf16 v[44:47], v[156:159], v[164:167], v[44:47]
	v_mfma_f32_16x16x32_bf16 v[32:35], v[148:151], v[184:187], v[32:35]
	v_mfma_f32_16x16x32_bf16 v[28:31], v[156:159], v[184:187], v[28:31]
	v_mfma_f32_16x16x32_bf16 v[20:23], v[148:151], v[200:203], v[20:23]
	v_mfma_f32_16x16x32_bf16 v[16:19], v[156:159], v[200:203], v[16:19]
	v_mfma_f32_16x16x32_bf16 v[4:7], v[148:151], v[208:211], v[4:7]
	v_mfma_f32_16x16x32_bf16 v[0:3], v[156:159], v[208:211], v[0:3]
	s_barrier
; #define PG8_STAGE(bufoff, gbase, voff) do { _Pragma("unroll") for (int _i = 0; _i < 2; ++_i) \
;         __builtin_amdgcn_global_load_lds((const unsigned*)((const char*)(gbase) + (voff)[_i]), (PG8_LAS unsigned*)(lds + (bufoff) + ldsw + _i * 8192), 16, 0, 0); } while (0)
; #define PG8_LDA(dst, b, h) do { _Pragma("unroll") for (int m = 0; m < 4; ++m) _Pragma("unroll") for (int k = 0; k < 2; ++k) dst[m][k] = *(const PG8_LAS bf16x8*)(lds + PG8_SA(b, h) + aoff + m * 2048 + k * 1024); } while (0)
; #define PG8_LDB(dst, b, h) do { _Pragma("unroll") for (int n = 0; n < 2; ++n) _Pragma("unroll") for (int k = 0; k < 2; ++k) dst[n][k] = *(const PG8_LAS bf16x8*)(lds + PG8_SB(b, h) + boff + n * 2048 + k * 1024); } while (0)
; #define PG8_MMA(ai, bj, At, Bt) do { __builtin_amdgcn_s_setprio(1); _Pragma("unroll") for (int m = 0; m < 4; ++m) _Pragma("unroll") for (int n = 0; n < 2; ++n) _Pragma("unroll") for (int k = 0; k < 2; ++k) \
;         acc[ai][bj][m][n] = __builtin_amdgcn_mfma_f32_16x16x32_bf16(Bt[n][k], At[m][k], acc[ai][bj][m][n], 0, 0, 0); __builtin_amdgcn_s_setprio(0); } while (0)
; #define PG8_WAIT_V(n) asm volatile("s_waitcnt vmcnt(" #n ")" ::: "memory")
; #define PG8_WAIT_L(n) asm volatile("s_waitcnt lgkmcnt(" #n ")" ::: "memory")
; #define PG8_BAR __builtin_amdgcn_s_barrier()
; #define PG8_SCHED __builtin_amdgcn_sched_barrier(0)
; template <class Epi, class Sched, bool ALIGN_EPI = false, bool SP2 = false>
; __device__ __forceinline__ void gemm_phase(PG8_LAS unsigned char* lds, const Gemm g, const Sched& S, const Epi& E) {
;     ...
;             PG8_LDB(B0, 1, 0); PG8_LDB(B1, 1, 1); PG8_SCHED; PG8_LDA(At, 1, 0); PG8_STAGE(PG8_SA(0, 1), a2 + hstep, voffA);
;             PG8_WAIT_V(8); PG8_WAIT_L(0); PG8_BAR; PG8_MMA(0, 0, At, B0); PG8_MMA(0, 1, At, B1); PG8_BAR; PG8_SCHED;
	s_setprio 0
	s_add_i32 s75, 0, 0x18000
	s_add_i32 s76, 0, 0x1c000
	v_add_u32_e32 v116, s75, v194
	v_add_u32_e32 v156, s76, v194
	ds_read_b128 v[92:95], v116
	ds_read_b128 v[100:103], v116 offset:1024
	ds_read_b128 v[108:111], v116 offset:2048
	ds_read_b128 v[116:119], v116 offset:3072
	ds_read_b128 v[144:147], v156
	ds_read_b128 v[148:151], v156 offset:1024
	ds_read_b128 v[152:155], v156 offset:2048
	ds_read_b128 v[156:159], v156 offset:3072
	s_add_u32 s36, s50, 0x80000
	s_addc_u32 s37, s51, 0
	s_mov_b32 m0, s61
	v_lshl_add_u64 v[222:223], s[36:37], 0, v[174:175]
	ds_read_b128 v[160:163], v198 offset:32768
	ds_read_b128 v[164:167], v198 offset:33792
	ds_read_b128 v[168:171], v198 offset:34816
	ds_read_b128 v[184:187], v198 offset:35840
	ds_read_b128 v[188:191], v198 offset:36864
	ds_read_b128 v[200:203], v198 offset:37888
	ds_read_b128 v[204:207], v198 offset:38912
	ds_read_b128 v[208:211], v198 offset:39936
	global_load_lds_dwordx4 v[222:223], off
	v_lshl_add_u64 v[222:223], s[36:37], 0, v[172:173]
	s_mov_b32 m0, s62
	s_nop 0
	global_load_lds_dwordx4 v[222:223], off
	s_waitcnt vmcnt(8) lgkmcnt(0)
	s_setprio 1
	s_barrier
	v_mfma_f32_16x16x32_bf16 v[140:143], v[92:95], v[160:163], v[140:143]
	v_mfma_f32_16x16x32_bf16 v[136:139], v[108:111], v[160:163], v[136:139]
	v_mfma_f32_16x16x32_bf16 v[132:135], v[92:95], v[168:171], v[132:135]
	v_mfma_f32_16x16x32_bf16 v[120:123], v[108:111], v[168:171], v[120:123]
	v_mfma_f32_16x16x32_bf16 v[112:115], v[92:95], v[188:191], v[112:115]
	v_mfma_f32_16x16x32_bf16 v[88:91], v[108:111], v[188:191], v[88:91]
	v_mfma_f32_16x16x32_bf16 v[76:79], v[92:95], v[204:207], v[76:79]
	v_mfma_f32_16x16x32_bf16 v[72:75], v[108:111], v[204:207], v[72:75]
	v_mfma_f32_16x16x32_bf16 v[140:143], v[100:103], v[164:167], v[140:143]
	v_mfma_f32_16x16x32_bf16 v[136:139], v[116:119], v[164:167], v[136:139]
	v_mfma_f32_16x16x32_bf16 v[132:135], v[100:103], v[184:187], v[132:135]
	v_mfma_f32_16x16x32_bf16 v[120:123], v[116:119], v[184:187], v[120:123]
	v_mfma_f32_16x16x32_bf16 v[112:115], v[100:103], v[200:203], v[112:115]
	v_mfma_f32_16x16x32_bf16 v[88:91], v[116:119], v[200:203], v[88:91]
	v_mfma_f32_16x16x32_bf16 v[76:79], v[100:103], v[208:211], v[76:79]
	v_mfma_f32_16x16x32_bf16 v[72:75], v[116:119], v[208:211], v[72:75]
	v_mfma_f32_16x16x32_bf16 v[128:131], v[144:147], v[160:163], v[128:131]
	v_mfma_f32_16x16x32_bf16 v[124:127], v[152:155], v[160:163], v[124:127]
	v_mfma_f32_16x16x32_bf16 v[104:107], v[144:147], v[168:171], v[104:107]
	v_mfma_f32_16x16x32_bf16 v[96:99], v[152:155], v[168:171], v[96:99]
	v_mfma_f32_16x16x32_bf16 v[84:87], v[144:147], v[188:191], v[84:87]
	v_mfma_f32_16x16x32_bf16 v[80:83], v[152:155], v[188:191], v[80:83]
	v_mfma_f32_16x16x32_bf16 v[68:71], v[144:147], v[204:207], v[68:71]
	v_mfma_f32_16x16x32_bf16 v[64:67], v[152:155], v[204:207], v[64:67]
	v_mfma_f32_16x16x32_bf16 v[128:131], v[148:151], v[164:167], v[128:131]
	v_mfma_f32_16x16x32_bf16 v[124:127], v[156:159], v[164:167], v[124:127]
	v_mfma_f32_16x16x32_bf16 v[104:107], v[148:151], v[184:187], v[104:107]
	v_mfma_f32_16x16x32_bf16 v[96:99], v[156:159], v[184:187], v[96:99]
	v_mfma_f32_16x16x32_bf16 v[84:87], v[148:151], v[200:203], v[84:87]
	v_mfma_f32_16x16x32_bf16 v[80:83], v[156:159], v[200:203], v[80:83]
	v_mfma_f32_16x16x32_bf16 v[68:71], v[148:151], v[208:211], v[68:71]
	v_mfma_f32_16x16x32_bf16 v[64:67], v[156:159], v[208:211], v[64:67]
	s_barrier
; #define PG8_STAGE(bufoff, gbase, voff) do { _Pragma("unroll") for (int _i = 0; _i < 2; ++_i) \
;         __builtin_amdgcn_global_load_lds((const unsigned*)((const char*)(gbase) + (voff)[_i]), (PG8_LAS unsigned*)(lds + (bufoff) + ldsw + _i * 8192), 16, 0, 0); } while (0)
; #define PG8_LDA(dst, b, h) do { _Pragma("unroll") for (int m = 0; m < 4; ++m) _Pragma("unroll") for (int k = 0; k < 2; ++k) dst[m][k] = *(const PG8_LAS bf16x8*)(lds + PG8_SA(b, h) + aoff + m * 2048 + k * 1024); } while (0)
; #define PG8_MMA(ai, bj, At, Bt) do { __builtin_amdgcn_s_setprio(1); _Pragma("unroll") for (int m = 0; m < 4; ++m) _Pragma("unroll") for (int n = 0; n < 2; ++n) _Pragma("unroll") for (int k = 0; k < 2; ++k) \
;         acc[ai][bj][m][n] = __builtin_amdgcn_mfma_f32_16x16x32_bf16(Bt[n][k], At[m][k], acc[ai][bj][m][n], 0, 0, 0); __builtin_amdgcn_s_setprio(0); } while (0)
; #define PG8_WAIT_V(n) asm volatile("s_waitcnt vmcnt(" #n ")" ::: "memory")
; #define PG8_WAIT_L(n) asm volatile("s_waitcnt lgkmcnt(" #n ")" ::: "memory")
; #define PG8_BAR __builtin_amdgcn_s_barrier()
; #define PG8_SCHED __builtin_amdgcn_sched_barrier(0)
; template <class Epi, class Sched, bool ALIGN_EPI = false, bool SP2 = false>
; __device__ __forceinline__ void gemm_phase(PG8_LAS unsigned char* lds, const Gemm g, const Sched& S, const Epi& E) {
;     ...
;             PG8_LDA(At, 1, 1); PG8_STAGE(PG8_SB(1, 0), b3, voffB); PG8_STAGE(PG8_SB(1, 1), b3 + hstep, voffB); PG8_STAGE(PG8_SA(1, 0), a3, voffA);
;             PG8_WAIT_V(8); PG8_WAIT_L(0); PG8_BAR; PG8_MMA(1, 0, At, B0); PG8_MMA(1, 1, At, B1); PG8_BAR; PG8_SCHED;
;     ...
;         if constexpr (ALIGN_EPI) { if (wr == 0) PG8_BAR; }
	s_setprio 0
	s_add_i32 s36, s75, s54
	v_lshl_add_u64 v[212:213], v[212:213], 0, s[20:21]
	s_mov_b32 m0, s36
	ds_read_b128 v[160:163], v198 offset:49152
	ds_read_b128 v[164:167], v198 offset:50176
	ds_read_b128 v[168:171], v198 offset:51200
	ds_read_b128 v[184:187], v198 offset:52224
	ds_read_b128 v[188:191], v198 offset:53248
	ds_read_b128 v[200:203], v198 offset:54272
	ds_read_b128 v[204:207], v198 offset:55296
	ds_read_b128 v[208:211], v198 offset:56320
	global_load_lds_dwordx4 v[212:213], off
	s_add_i32 m0, s36, 0x2000
	s_add_u32 s36, s44, 0x80080
	v_lshl_add_u64 v[212:213], v[214:215], 0, s[20:21]
	s_addc_u32 s37, s45, 0
	s_add_i32 s44, s76, s54
	global_load_lds_dwordx4 v[212:213], off
	v_lshl_add_u64 v[212:213], s[36:37], 0, v[174:175]
	s_mov_b32 m0, s44
	s_nop 0
	global_load_lds_dwordx4 v[212:213], off
	v_lshl_add_u64 v[212:213], s[36:37], 0, v[172:173]
	s_add_i32 m0, s44, 0x2000
	s_nop 0
	global_load_lds_dwordx4 v[212:213], off
	v_lshl_add_u64 v[212:213], v[218:219], 0, s[20:21]
	s_mov_b32 m0, s66
	s_nop 0
	global_load_lds_dwordx4 v[212:213], off
	v_lshl_add_u64 v[212:213], v[220:221], 0, s[20:21]
	s_mov_b32 m0, s67
	s_nop 0
	global_load_lds_dwordx4 v[212:213], off
	s_waitcnt vmcnt(8) lgkmcnt(0)
	s_setprio 1
	s_barrier
	v_mfma_f32_16x16x32_bf16 v[60:63], v[92:95], v[160:163], v[60:63]
	v_mfma_f32_16x16x32_bf16 v[56:59], v[108:111], v[160:163], v[56:59]
	v_mfma_f32_16x16x32_bf16 v[52:55], v[92:95], v[168:171], v[52:55]
	v_mfma_f32_16x16x32_bf16 v[40:43], v[108:111], v[168:171], v[40:43]
	v_mfma_f32_16x16x32_bf16 v[36:39], v[92:95], v[188:191], v[36:39]
	v_mfma_f32_16x16x32_bf16 v[24:27], v[108:111], v[188:191], v[24:27]
	v_mfma_f32_16x16x32_bf16 v[12:15], v[92:95], v[204:207], v[12:15]
	v_mfma_f32_16x16x32_bf16 v[8:11], v[108:111], v[204:207], v[8:11]
	v_mfma_f32_16x16x32_bf16 v[60:63], v[100:103], v[164:167], v[60:63]
	v_mfma_f32_16x16x32_bf16 v[56:59], v[116:119], v[164:167], v[56:59]
	v_mfma_f32_16x16x32_bf16 v[52:55], v[100:103], v[184:187], v[52:55]
	v_mfma_f32_16x16x32_bf16 v[40:43], v[116:119], v[184:187], v[40:43]
	v_mfma_f32_16x16x32_bf16 v[36:39], v[100:103], v[200:203], v[36:39]
	v_mfma_f32_16x16x32_bf16 v[24:27], v[116:119], v[200:203], v[24:27]
	v_mfma_f32_16x16x32_bf16 v[12:15], v[100:103], v[208:211], v[12:15]
	v_mfma_f32_16x16x32_bf16 v[8:11], v[116:119], v[208:211], v[8:11]
	v_mfma_f32_16x16x32_bf16 v[48:51], v[144:147], v[160:163], v[48:51]
	v_mfma_f32_16x16x32_bf16 v[44:47], v[152:155], v[160:163], v[44:47]
	v_mfma_f32_16x16x32_bf16 v[32:35], v[144:147], v[168:171], v[32:35]
	v_mfma_f32_16x16x32_bf16 v[28:31], v[152:155], v[168:171], v[28:31]
	v_mfma_f32_16x16x32_bf16 v[20:23], v[144:147], v[188:191], v[20:23]
	v_mfma_f32_16x16x32_bf16 v[16:19], v[152:155], v[188:191], v[16:19]
	v_mfma_f32_16x16x32_bf16 v[4:7], v[144:147], v[204:207], v[4:7]
	v_mfma_f32_16x16x32_bf16 v[0:3], v[152:155], v[204:207], v[0:3]
	v_mfma_f32_16x16x32_bf16 v[48:51], v[148:151], v[164:167], v[48:51]
	v_mfma_f32_16x16x32_bf16 v[44:47], v[156:159], v[164:167], v[44:47]
	v_mfma_f32_16x16x32_bf16 v[32:35], v[148:151], v[184:187], v[32:35]
	v_mfma_f32_16x16x32_bf16 v[28:31], v[156:159], v[184:187], v[28:31]
	v_mfma_f32_16x16x32_bf16 v[20:23], v[148:151], v[200:203], v[20:23]
	v_mfma_f32_16x16x32_bf16 v[16:19], v[156:159], v[200:203], v[16:19]
	v_mfma_f32_16x16x32_bf16 v[4:7], v[148:151], v[208:211], v[4:7]
	v_mfma_f32_16x16x32_bf16 v[0:3], v[156:159], v[208:211], v[0:3]
	s_barrier
	s_setprio 0
	s_add_i32 s74, s74, 2
	s_add_u32 s72, s72, 0x100
	s_addc_u32 s73, s73, 0
	s_cmp_gt_u32 s74, 29
	s_mov_b64 s[36:37], s[40:41]
	s_cbranch_scc0 .LBB0_645
	s_and_b64 vcc, exec, s[22:23]
	s_cbranch_vccz .LBB0_648
	s_barrier

; #define PG8_STAGE(bufoff, gbase, voff) do { _Pragma("unroll") for (int _i = 0; _i < 2; ++_i) \
;         __builtin_amdgcn_global_load_lds((const unsigned*)((const char*)(gbase) + (voff)[_i]), (PG8_LAS unsigned*)(lds + (bufoff) + ldsw + _i * 8192), 16, 0, 0); } while (0)
; #define PG8_LDA(dst, b, h) do { _Pragma("unroll") for (int m = 0; m < 4; ++m) _Pragma("unroll") for (int k = 0; k < 2; ++k) dst[m][k] = *(const PG8_LAS bf16x8*)(lds + PG8_SA(b, h) + aoff + m * 2048 + k * 1024); } while (0)
; #define PG8_LDB(dst, b, h) do { _Pragma("unroll") for (int n = 0; n < 2; ++n) _Pragma("unroll") for (int k = 0; k < 2; ++k) dst[n][k] = *(const PG8_LAS bf16x8*)(lds + PG8_SB(b, h) + boff + n * 2048 + k * 1024); } while (0)
; #define PG8_MMA(ai, bj, At, Bt) do { __builtin_amdgcn_s_setprio(1); _Pragma("unroll") for (int m = 0; m < 4; ++m) _Pragma("unroll") for (int n = 0; n < 2; ++n) _Pragma("unroll") for (int k = 0; k < 2; ++k) \
;         acc[ai][bj][m][n] = __builtin_amdgcn_mfma_f32_16x16x32_bf16(Bt[n][k], At[m][k], acc[ai][bj][m][n], 0, 0, 0); __builtin_amdgcn_s_setprio(0); } while (0)
; #define PG8_BAR __builtin_amdgcn_s_barrier()
; template <class Epi, class Sched, bool ALIGN_EPI = false, bool SP2 = false>
; __device__ __forceinline__ void gemm_phase(PG8_LAS unsigned char* lds, const Gemm g, const Sched& S, const Epi& E) {
;     ...
;         const bool has_next = S.next(ui + 1, nxt);
;         const char* nA = has_next ? (const char*)g.A + (size_t)nxt.pm * tstep : cA; const char* nB = has_next ? (const char*)g.Bt + (size_t)nxt.pn * tstep : cB;
;         for (int t = 0; t < nt; t += 2) {
;             const bool last = (t == nt - 2);
;             const char* a1 = cA + (size_t)(t + 1) * kstep;
;             const char* a2 = last ? nA : cA + (size_t)(t + 2) * kstep; const char* b2 = last ? nB : cB + (size_t)(t + 2) * kstep;
;             const char* a3 = a2 + kstep; const char* b3 = b2 + kstep;
;             if (last && has_next) S.a_ready(nxt);
;             if constexpr (SP2) {
;             PG8_LDB(B0, 0, 0); PG8_LDB(B1, 0, 1); PG8_SCHED; PG8_LDA(At, 0, 0); PG8_STAGE(PG8_SA(1, 1), a1 + hstep, voffA);
;             PG8_WAIT_V(8); PG8_WAIT_L(0); PG8_BAR; PG8_MMA(0, 0, At, B0); PG8_MMA(0, 1, At, B1); PG8_BAR; PG8_SCHED;
;             PG8_LDA(At, 0, 1); PG8_STAGE(PG8_SB(0, 0), b2, voffB); PG8_STAGE(PG8_SB(0, 1), b2 + hstep, voffB); PG8_STAGE(PG8_SA(0, 0), a2, voffA);
.LBB0_774:
	s_ashr_i32 s23, s22, 31
	s_lshl_b64 s[24:25], s[22:23], 20
	s_add_u32 s24, s40, s24
	s_addc_u32 s25, s41, s25
	s_and_b64 s[26:27], s[38:39], exec
	s_cselect_b32 s23, s25, s31
	s_cselect_b32 s62, s24, s30
	s_ashr_i32 s21, s20, 31
	s_lshl_b64 s[26:27], s[20:21], 20
	s_add_u32 s26, s44, s26
	s_addc_u32 s27, s45, s27
	s_and_b64 s[36:37], s[38:39], exec
	s_cselect_b32 s21, s27, s35
	s_cselect_b32 s63, s26, s34
	s_add_u32 s30, s30, 0x80080
	s_addc_u32 s31, s31, 0
	s_add_u32 s64, s34, 0x100
	s_addc_u32 s65, s35, 0
	s_mov_b32 s66, -2
	ds_read_b128 v[152:155], v149
	ds_read_b128 v[156:159], v149 offset:1024
	ds_read_b128 v[160:163], v149 offset:2048
	ds_read_b128 v[164:167], v149 offset:3072
	ds_read_b128 v[168:171], v150
	ds_read_b128 v[172:175], v150 offset:1024
	ds_read_b128 v[176:179], v150 offset:2048
	ds_read_b128 v[180:183], v150 offset:3072
	s_add_u32 s34, s30, 0xfff80080
	s_addc_u32 s35, s31, -1
	s_cmp_eq_u32 s66, 28
	s_cselect_b32 s37, s23, s35
	s_cselect_b32 s36, s62, s34
	s_cselect_b32 s35, s21, s65
	s_cselect_b32 s34, s63, s64
	v_lshl_add_u64 v[144:145], s[30:31], 0, v[136:137]
	s_add_i32 m0, s50, 0xc000
	ds_read_b128 v[184:187], v151
	ds_read_b128 v[188:191], v151 offset:1024
	ds_read_b128 v[192:195], v151 offset:2048
	ds_read_b128 v[196:199], v151 offset:3072
	ds_read_b128 v[200:203], v151 offset:4096
	ds_read_b128 v[204:207], v151 offset:5120
	ds_read_b128 v[208:211], v151 offset:6144
	ds_read_b128 v[212:215], v151 offset:7168
	global_load_lds_dwordx4 v[144:145], off
	v_lshl_add_u64 v[144:145], s[30:31], 0, v[138:139]
	s_add_i32 m0, s50, 0xe000
	s_nop 0
	global_load_lds_dwordx4 v[144:145], off
	s_waitcnt vmcnt(8) lgkmcnt(0)
	s_setprio 1
	s_barrier
	v_mfma_f32_16x16x32_bf16 v[124:127], v[152:155], v[184:187], 0
	v_mfma_f32_16x16x32_bf16 v[120:123], v[160:163], v[184:187], 0
	v_mfma_f32_16x16x32_bf16 v[108:111], v[152:155], v[192:195], 0
	v_mfma_f32_16x16x32_bf16 v[104:107], v[160:163], v[192:195], 0
	v_mfma_f32_16x16x32_bf16 v[92:95], v[152:155], v[200:203], 0
	v_mfma_f32_16x16x32_bf16 v[88:91], v[160:163], v[200:203], 0
	v_mfma_f32_16x16x32_bf16 v[76:79], v[152:155], v[208:211], 0
	v_mfma_f32_16x16x32_bf16 v[72:75], v[160:163], v[208:211], 0
	v_mfma_f32_16x16x32_bf16 v[124:127], v[156:159], v[188:191], v[124:127]
	v_mfma_f32_16x16x32_bf16 v[120:123], v[164:167], v[188:191], v[120:123]
	v_mfma_f32_16x16x32_bf16 v[108:111], v[156:159], v[196:199], v[108:111]
	v_mfma_f32_16x16x32_bf16 v[104:107], v[164:167], v[196:199], v[104:107]
	v_mfma_f32_16x16x32_bf16 v[92:95], v[156:159], v[204:207], v[92:95]
	v_mfma_f32_16x16x32_bf16 v[88:91], v[164:167], v[204:207], v[88:91]
	v_mfma_f32_16x16x32_bf16 v[76:79], v[156:159], v[212:215], v[76:79]
	v_mfma_f32_16x16x32_bf16 v[72:75], v[164:167], v[212:215], v[72:75]
	v_mfma_f32_16x16x32_bf16 v[116:119], v[168:171], v[184:187], 0
	v_mfma_f32_16x16x32_bf16 v[112:115], v[176:179], v[184:187], 0
	v_mfma_f32_16x16x32_bf16 v[100:103], v[168:171], v[192:195], 0
	v_mfma_f32_16x16x32_bf16 v[96:99], v[176:179], v[192:195], 0
	v_mfma_f32_16x16x32_bf16 v[84:87], v[168:171], v[200:203], 0
	v_mfma_f32_16x16x32_bf16 v[80:83], v[176:179], v[200:203], 0
	v_mfma_f32_16x16x32_bf16 v[68:71], v[168:171], v[208:211], 0
	v_mfma_f32_16x16x32_bf16 v[64:67], v[176:179], v[208:211], 0
	v_mfma_f32_16x16x32_bf16 v[116:119], v[172:175], v[188:191], v[116:119]
	v_mfma_f32_16x16x32_bf16 v[112:115], v[180:183], v[188:191], v[112:115]
	v_mfma_f32_16x16x32_bf16 v[100:103], v[172:175], v[196:199], v[100:103]
	v_mfma_f32_16x16x32_bf16 v[96:99], v[180:183], v[196:199], v[96:99]
	v_mfma_f32_16x16x32_bf16 v[84:87], v[172:175], v[204:207], v[84:87]
	v_mfma_f32_16x16x32_bf16 v[80:83], v[180:183], v[204:207], v[80:83]
	v_mfma_f32_16x16x32_bf16 v[68:71], v[172:175], v[212:215], v[68:71]
	v_mfma_f32_16x16x32_bf16 v[64:67], v[180:183], v[212:215], v[64:67]
	s_barrier
	s_setprio 0
	s_add_i32 s67, s60, s47
	v_lshl_add_u64 v[144:145], s[34:35], 0, v[132:133]
	s_mov_b32 m0, s67
	ds_read_b128 v[184:187], v151 offset:16384
	ds_read_b128 v[188:191], v151 offset:17408
	ds_read_b128 v[192:195], v151 offset:18432
	ds_read_b128 v[196:199], v151 offset:19456
	ds_read_b128 v[200:203], v151 offset:20480
	ds_read_b128 v[204:207], v151 offset:21504
	ds_read_b128 v[208:211], v151 offset:22528
	ds_read_b128 v[212:215], v151 offset:23552
	global_load_lds_dwordx4 v[144:145], off
	s_add_i32 m0, s67, 0x2000
	s_add_u32 s68, s34, 0x80000
	v_lshl_add_u64 v[218:219], s[34:35], 0, v[128:129]
	s_addc_u32 s69, s35, 0
	s_add_i32 s67, s61, s47
	global_load_lds_dwordx4 v[218:219], off
	v_lshl_add_u64 v[220:221], s[68:69], 0, v[132:133]
	s_mov_b32 m0, s67
	v_lshl_add_u64 v[222:223], s[36:37], 0, v[130:131]
	global_load_lds_dwordx4 v[220:221], off
	v_lshl_add_u64 v[220:221], s[68:69], 0, v[128:129]
	s_add_i32 m0, s67, 0x2000
	s_nop 0
	global_load_lds_dwordx4 v[220:221], off
	v_lshl_add_u64 v[220:221], s[36:37], 0, v[134:135]
	s_mov_b32 m0, s50
	s_nop 0
	global_load_lds_dwordx4 v[220:221], off
	s_mov_b32 m0, s51
	s_nop 0
	global_load_lds_dwordx4 v[222:223], off
	s_waitcnt vmcnt(8) lgkmcnt(0)
	s_setprio 1
	s_barrier
; #define PG8_STAGE(bufoff, gbase, voff) do { _Pragma("unroll") for (int _i = 0; _i < 2; ++_i) \
;         __builtin_amdgcn_global_load_lds((const unsigned*)((const char*)(gbase) + (voff)[_i]), (PG8_LAS unsigned*)(lds + (bufoff) + ldsw + _i * 8192), 16, 0, 0); } while (0)
; #define PG8_LDA(dst, b, h) do { _Pragma("unroll") for (int m = 0; m < 4; ++m) _Pragma("unroll") for (int k = 0; k < 2; ++k) dst[m][k] = *(const PG8_LAS bf16x8*)(lds + PG8_SA(b, h) + aoff + m * 2048 + k * 1024); } while (0)
; #define PG8_LDB(dst, b, h) do { _Pragma("unroll") for (int n = 0; n < 2; ++n) _Pragma("unroll") for (int k = 0; k < 2; ++k) dst[n][k] = *(const PG8_LAS bf16x8*)(lds + PG8_SB(b, h) + boff + n * 2048 + k * 1024); } while (0)
; #define PG8_MMA(ai, bj, At, Bt) do { __builtin_amdgcn_s_setprio(1); _Pragma("unroll") for (int m = 0; m < 4; ++m) _Pragma("unroll") for (int n = 0; n < 2; ++n) _Pragma("unroll") for (int k = 0; k < 2; ++k) \
;         acc[ai][bj][m][n] = __builtin_amdgcn_mfma_f32_16x16x32_bf16(Bt[n][k], At[m][k], acc[ai][bj][m][n], 0, 0, 0); __builtin_amdgcn_s_setprio(0); } while (0)
; #define PG8_WAIT_V(n) asm volatile("s_waitcnt vmcnt(" #n ")" ::: "memory")
; #define PG8_WAIT_L(n) asm volatile("s_waitcnt lgkmcnt(" #n ")" ::: "memory")
; #define PG8_BAR __builtin_amdgcn_s_barrier()
; #define PG8_SCHED __builtin_amdgcn_sched_barrier(0)
; template <class Epi, class Sched, bool ALIGN_EPI = false, bool SP2 = false>
; __device__ __forceinline__ void gemm_phase(PG8_LAS unsigned char* lds, const Gemm g, const Sched& S, const Epi& E) {
;     ...
;             PG8_WAIT_V(8); PG8_WAIT_L(0); PG8_BAR; PG8_MMA(1, 0, At, B0); PG8_MMA(1, 1, At, B1); PG8_BAR; PG8_SCHED;
;             PG8_LDB(B0, 1, 0); PG8_LDB(B1, 1, 1); PG8_SCHED; PG8_LDA(At, 1, 0); PG8_STAGE(PG8_SA(0, 1), a2 + hstep, voffA);
;             PG8_WAIT_V(8); PG8_WAIT_L(0); PG8_BAR; PG8_MMA(0, 0, At, B0); PG8_MMA(0, 1, At, B1); PG8_BAR; PG8_SCHED;
	v_mfma_f32_16x16x32_bf16 v[60:63], v[152:155], v[184:187], 0
	v_mfma_f32_16x16x32_bf16 v[56:59], v[160:163], v[184:187], 0
	v_mfma_f32_16x16x32_bf16 v[44:47], v[152:155], v[192:195], 0
	v_mfma_f32_16x16x32_bf16 v[40:43], v[160:163], v[192:195], 0
	v_mfma_f32_16x16x32_bf16 v[28:31], v[152:155], v[200:203], 0
	v_mfma_f32_16x16x32_bf16 v[24:27], v[160:163], v[200:203], 0
	v_mfma_f32_16x16x32_bf16 v[12:15], v[152:155], v[208:211], 0
	v_mfma_f32_16x16x32_bf16 v[8:11], v[160:163], v[208:211], 0
	v_mfma_f32_16x16x32_bf16 v[60:63], v[156:159], v[188:191], v[60:63]
	v_mfma_f32_16x16x32_bf16 v[56:59], v[164:167], v[188:191], v[56:59]
	v_mfma_f32_16x16x32_bf16 v[44:47], v[156:159], v[196:199], v[44:47]
	v_mfma_f32_16x16x32_bf16 v[40:43], v[164:167], v[196:199], v[40:43]
	v_mfma_f32_16x16x32_bf16 v[28:31], v[156:159], v[204:207], v[28:31]
	v_mfma_f32_16x16x32_bf16 v[24:27], v[164:167], v[204:207], v[24:27]
	v_mfma_f32_16x16x32_bf16 v[12:15], v[156:159], v[212:215], v[12:15]
	v_mfma_f32_16x16x32_bf16 v[8:11], v[164:167], v[212:215], v[8:11]
	v_mfma_f32_16x16x32_bf16 v[52:55], v[168:171], v[184:187], 0
	v_mfma_f32_16x16x32_bf16 v[48:51], v[176:179], v[184:187], 0
	v_mfma_f32_16x16x32_bf16 v[36:39], v[168:171], v[192:195], 0
	v_mfma_f32_16x16x32_bf16 v[32:35], v[176:179], v[192:195], 0
	v_mfma_f32_16x16x32_bf16 v[20:23], v[168:171], v[200:203], 0
	v_mfma_f32_16x16x32_bf16 v[16:19], v[176:179], v[200:203], 0
	v_mfma_f32_16x16x32_bf16 v[4:7], v[168:171], v[208:211], 0
	v_mfma_f32_16x16x32_bf16 v[0:3], v[176:179], v[208:211], 0
	v_mfma_f32_16x16x32_bf16 v[52:55], v[172:175], v[188:191], v[52:55]
	v_mfma_f32_16x16x32_bf16 v[48:51], v[180:183], v[188:191], v[48:51]
	v_mfma_f32_16x16x32_bf16 v[36:39], v[172:175], v[196:199], v[36:39]
	v_mfma_f32_16x16x32_bf16 v[32:35], v[180:183], v[196:199], v[32:35]
	v_mfma_f32_16x16x32_bf16 v[20:23], v[172:175], v[204:207], v[20:23]
	v_mfma_f32_16x16x32_bf16 v[16:19], v[180:183], v[204:207], v[16:19]
	v_mfma_f32_16x16x32_bf16 v[4:7], v[172:175], v[212:215], v[4:7]
	v_mfma_f32_16x16x32_bf16 v[0:3], v[180:183], v[212:215], v[0:3]
	s_barrier
	s_setprio 0
	s_add_i32 s67, 0, 0x18000
	s_add_i32 s68, 0, 0x1c000
	v_add_u32_e32 v164, s67, v147
	v_add_u32_e32 v180, s68, v147
	ds_read_b128 v[152:155], v164
	ds_read_b128 v[156:159], v164 offset:1024
	ds_read_b128 v[160:163], v164 offset:2048
	ds_read_b128 v[164:167], v164 offset:3072
	ds_read_b128 v[168:171], v180
	ds_read_b128 v[172:175], v180 offset:1024
	ds_read_b128 v[176:179], v180 offset:2048
	ds_read_b128 v[180:183], v180 offset:3072
	s_add_u32 s36, s36, 0x80000
	s_addc_u32 s37, s37, 0
	s_mov_b32 m0, s52
	v_lshl_add_u64 v[224:225], s[36:37], 0, v[134:135]
	ds_read_b128 v[184:187], v151 offset:32768
	ds_read_b128 v[188:191], v151 offset:33792
	ds_read_b128 v[192:195], v151 offset:34816
	ds_read_b128 v[196:199], v151 offset:35840
	ds_read_b128 v[200:203], v151 offset:36864
	ds_read_b128 v[204:207], v151 offset:37888
	ds_read_b128 v[208:211], v151 offset:38912
	ds_read_b128 v[212:215], v151 offset:39936
	global_load_lds_dwordx4 v[224:225], off
	v_lshl_add_u64 v[224:225], s[36:37], 0, v[130:131]
	s_mov_b32 m0, s53
	s_nop 0
	global_load_lds_dwordx4 v[224:225], off
	s_waitcnt vmcnt(8) lgkmcnt(0)
	s_setprio 1
	s_barrier
	v_mfma_f32_16x16x32_bf16 v[124:127], v[152:155], v[184:187], v[124:127]
	v_mfma_f32_16x16x32_bf16 v[120:123], v[160:163], v[184:187], v[120:123]
	v_mfma_f32_16x16x32_bf16 v[108:111], v[152:155], v[192:195], v[108:111]
	v_mfma_f32_16x16x32_bf16 v[104:107], v[160:163], v[192:195], v[104:107]
	v_mfma_f32_16x16x32_bf16 v[92:95], v[152:155], v[200:203], v[92:95]
	v_mfma_f32_16x16x32_bf16 v[88:91], v[160:163], v[200:203], v[88:91]
	v_mfma_f32_16x16x32_bf16 v[76:79], v[152:155], v[208:211], v[76:79]
	v_mfma_f32_16x16x32_bf16 v[72:75], v[160:163], v[208:211], v[72:75]
	v_mfma_f32_16x16x32_bf16 v[124:127], v[156:159], v[188:191], v[124:127]
	v_mfma_f32_16x16x32_bf16 v[120:123], v[164:167], v[188:191], v[120:123]
	v_mfma_f32_16x16x32_bf16 v[108:111], v[156:159], v[196:199], v[108:111]
	v_mfma_f32_16x16x32_bf16 v[104:107], v[164:167], v[196:199], v[104:107]
	v_mfma_f32_16x16x32_bf16 v[92:95], v[156:159], v[204:207], v[92:95]
	v_mfma_f32_16x16x32_bf16 v[88:91], v[164:167], v[204:207], v[88:91]
	v_mfma_f32_16x16x32_bf16 v[76:79], v[156:159], v[212:215], v[76:79]
	v_mfma_f32_16x16x32_bf16 v[72:75], v[164:167], v[212:215], v[72:75]
	v_mfma_f32_16x16x32_bf16 v[116:119], v[168:171], v[184:187], v[116:119]
	v_mfma_f32_16x16x32_bf16 v[112:115], v[176:179], v[184:187], v[112:115]
	v_mfma_f32_16x16x32_bf16 v[100:103], v[168:171], v[192:195], v[100:103]
	v_mfma_f32_16x16x32_bf16 v[96:99], v[176:179], v[192:195], v[96:99]
	v_mfma_f32_16x16x32_bf16 v[84:87], v[168:171], v[200:203], v[84:87]
	v_mfma_f32_16x16x32_bf16 v[80:83], v[176:179], v[200:203], v[80:83]
	v_mfma_f32_16x16x32_bf16 v[68:71], v[168:171], v[208:211], v[68:71]
	v_mfma_f32_16x16x32_bf16 v[64:67], v[176:179], v[208:211], v[64:67]
	v_mfma_f32_16x16x32_bf16 v[116:119], v[172:175], v[188:191], v[116:119]
	v_mfma_f32_16x16x32_bf16 v[112:115], v[180:183], v[188:191], v[112:115]
	v_mfma_f32_16x16x32_bf16 v[100:103], v[172:175], v[196:199], v[100:103]
	v_mfma_f32_16x16x32_bf16 v[96:99], v[180:183], v[196:199], v[96:99]
	v_mfma_f32_16x16x32_bf16 v[84:87], v[172:175], v[204:207], v[84:87]
	v_mfma_f32_16x16x32_bf16 v[80:83], v[180:183], v[204:207], v[80:83]
	v_mfma_f32_16x16x32_bf16 v[68:71], v[172:175], v[212:215], v[68:71]
	v_mfma_f32_16x16x32_bf16 v[64:67], v[180:183], v[212:215], v[64:67]
	s_barrier
; #define PG8_STAGE(bufoff, gbase, voff) do { _Pragma("unroll") for (int _i = 0; _i < 2; ++_i) \
;         __builtin_amdgcn_global_load_lds((const unsigned*)((const char*)(gbase) + (voff)[_i]), (PG8_LAS unsigned*)(lds + (bufoff) + ldsw + _i * 8192), 16, 0, 0); } while (0)
; #define PG8_LDA(dst, b, h) do { _Pragma("unroll") for (int m = 0; m < 4; ++m) _Pragma("unroll") for (int k = 0; k < 2; ++k) dst[m][k] = *(const PG8_LAS bf16x8*)(lds + PG8_SA(b, h) + aoff + m * 2048 + k * 1024); } while (0)
; #define PG8_LDB(dst, b, h) do { _Pragma("unroll") for (int n = 0; n < 2; ++n) _Pragma("unroll") for (int k = 0; k < 2; ++k) dst[n][k] = *(const PG8_LAS bf16x8*)(lds + PG8_SB(b, h) + boff + n * 2048 + k * 1024); } while (0)
; #define PG8_MMA(ai, bj, At, Bt) do { __builtin_amdgcn_s_setprio(1); _Pragma("unroll") for (int m = 0; m < 4; ++m) _Pragma("unroll") for (int n = 0; n < 2; ++n) _Pragma("unroll") for (int k = 0; k < 2; ++k) \
;         acc[ai][bj][m][n] = __builtin_amdgcn_mfma_f32_16x16x32_bf16(Bt[n][k], At[m][k], acc[ai][bj][m][n], 0, 0, 0); __builtin_amdgcn_s_setprio(0); } while (0)
; #define PG8_WAIT_V(n) asm volatile("s_waitcnt vmcnt(" #n ")" ::: "memory")
; template <class Epi, class Sched, bool ALIGN_EPI = false, bool SP2 = false>
; __device__ __forceinline__ void gemm_phase(PG8_LAS unsigned char* lds, const Gemm g, const Sched& S, const Epi& E) {
;     ...
;             PG8_LDB(B0, 0, 0); PG8_LDB(B1, 0, 1); PG8_SCHED; PG8_LDA(At, 0, 0); PG8_STAGE(PG8_SA(1, 1), a1 + hstep, voffA);
;             PG8_WAIT_V(8); PG8_WAIT_L(0); PG8_BAR; PG8_MMA(0, 0, At, B0); PG8_MMA(0, 1, At, B1); PG8_BAR; PG8_SCHED;
;             PG8_LDA(At, 0, 1); PG8_STAGE(PG8_SB(0, 0), b2, voffB); PG8_STAGE(PG8_SB(0, 1), b2 + hstep, voffB); PG8_STAGE(PG8_SA(0, 0), a2, voffA);
;             PG8_WAIT_V(8); PG8_WAIT_L(0); PG8_BAR; PG8_MMA(1, 0, At, B0); PG8_MMA(1, 1, At, B1); PG8_BAR; PG8_SCHED;
;             PG8_LDB(B0, 1, 0); PG8_LDB(B1, 1, 1); PG8_SCHED; PG8_LDA(At, 1, 0); PG8_STAGE(PG8_SA(0, 1), a2 + hstep, voffA);
;             PG8_WAIT_V(8); PG8_WAIT_L(0); PG8_BAR; PG8_MMA(0, 0, At, B0); PG8_MMA(0, 1, At, B1); PG8_BAR; PG8_SCHED;
;             PG8_LDA(At, 1, 1); PG8_STAGE(PG8_SB(1, 0), b3, voffB); PG8_STAGE(PG8_SB(1, 1), b3 + hstep, voffB); PG8_STAGE(PG8_SA(1, 0), a3, voffA);
;             PG8_WAIT_V(8); PG8_WAIT_L(0); PG8_BAR; PG8_MMA(1, 0, At, B0); PG8_MMA(1, 1, At, B1); PG8_BAR; PG8_SCHED;
	s_setprio 0
	s_add_i32 s36, s67, s47
	v_lshl_add_u64 v[144:145], v[144:145], 0, s[16:17]
	s_mov_b32 m0, s36
	ds_read_b128 v[184:187], v151 offset:49152
	ds_read_b128 v[188:191], v151 offset:50176
	ds_read_b128 v[192:195], v151 offset:51200
	ds_read_b128 v[196:199], v151 offset:52224
	ds_read_b128 v[200:203], v151 offset:53248
	ds_read_b128 v[204:207], v151 offset:54272
	ds_read_b128 v[208:211], v151 offset:55296
	ds_read_b128 v[212:215], v151 offset:56320
	global_load_lds_dwordx4 v[144:145], off
	s_add_i32 m0, s36, 0x2000
	s_add_u32 s34, s34, 0x80080
	v_lshl_add_u64 v[144:145], v[218:219], 0, s[16:17]
	s_addc_u32 s35, s35, 0
	s_add_i32 s36, s68, s47
	global_load_lds_dwordx4 v[144:145], off
	v_lshl_add_u64 v[144:145], s[34:35], 0, v[132:133]
	s_mov_b32 m0, s36
	s_nop 0
	global_load_lds_dwordx4 v[144:145], off
	v_lshl_add_u64 v[144:145], s[34:35], 0, v[128:129]
	s_add_i32 m0, s36, 0x2000
	s_nop 0
	global_load_lds_dwordx4 v[144:145], off
	v_lshl_add_u64 v[144:145], v[220:221], 0, s[16:17]
	s_mov_b32 m0, s55
	s_nop 0
	global_load_lds_dwordx4 v[144:145], off
	v_lshl_add_u64 v[144:145], v[222:223], 0, s[16:17]
	s_mov_b32 m0, s59
	s_nop 0
	global_load_lds_dwordx4 v[144:145], off
	s_waitcnt vmcnt(8) lgkmcnt(0)
	s_setprio 1
	s_barrier
	v_mfma_f32_16x16x32_bf16 v[60:63], v[152:155], v[184:187], v[60:63]
	v_mfma_f32_16x16x32_bf16 v[56:59], v[160:163], v[184:187], v[56:59]
	v_mfma_f32_16x16x32_bf16 v[44:47], v[152:155], v[192:195], v[44:47]
	v_mfma_f32_16x16x32_bf16 v[40:43], v[160:163], v[192:195], v[40:43]
	v_mfma_f32_16x16x32_bf16 v[28:31], v[152:155], v[200:203], v[28:31]
	v_mfma_f32_16x16x32_bf16 v[24:27], v[160:163], v[200:203], v[24:27]
	v_mfma_f32_16x16x32_bf16 v[12:15], v[152:155], v[208:211], v[12:15]
	v_mfma_f32_16x16x32_bf16 v[8:11], v[160:163], v[208:211], v[8:11]
	v_mfma_f32_16x16x32_bf16 v[60:63], v[156:159], v[188:191], v[60:63]
	v_mfma_f32_16x16x32_bf16 v[56:59], v[164:167], v[188:191], v[56:59]
	v_mfma_f32_16x16x32_bf16 v[44:47], v[156:159], v[196:199], v[44:47]
	v_mfma_f32_16x16x32_bf16 v[40:43], v[164:167], v[196:199], v[40:43]
	v_mfma_f32_16x16x32_bf16 v[28:31], v[156:159], v[204:207], v[28:31]
	v_mfma_f32_16x16x32_bf16 v[24:27], v[164:167], v[204:207], v[24:27]
	v_mfma_f32_16x16x32_bf16 v[12:15], v[156:159], v[212:215], v[12:15]
	v_mfma_f32_16x16x32_bf16 v[8:11], v[164:167], v[212:215], v[8:11]
	v_mfma_f32_16x16x32_bf16 v[52:55], v[168:171], v[184:187], v[52:55]
	v_mfma_f32_16x16x32_bf16 v[48:51], v[176:179], v[184:187], v[48:51]
	v_mfma_f32_16x16x32_bf16 v[36:39], v[168:171], v[192:195], v[36:39]
	v_mfma_f32_16x16x32_bf16 v[32:35], v[176:179], v[192:195], v[32:35]
	v_mfma_f32_16x16x32_bf16 v[20:23], v[168:171], v[200:203], v[20:23]
	v_mfma_f32_16x16x32_bf16 v[16:19], v[176:179], v[200:203], v[16:19]
	v_mfma_f32_16x16x32_bf16 v[4:7], v[168:171], v[208:211], v[4:7]
	v_mfma_f32_16x16x32_bf16 v[0:3], v[176:179], v[208:211], v[0:3]
	v_mfma_f32_16x16x32_bf16 v[52:55], v[172:175], v[188:191], v[52:55]
	v_mfma_f32_16x16x32_bf16 v[48:51], v[180:183], v[188:191], v[48:51]
	v_mfma_f32_16x16x32_bf16 v[36:39], v[172:175], v[196:199], v[36:39]
	v_mfma_f32_16x16x32_bf16 v[32:35], v[180:183], v[196:199], v[32:35]
	v_mfma_f32_16x16x32_bf16 v[20:23], v[172:175], v[204:207], v[20:23]
	v_mfma_f32_16x16x32_bf16 v[16:19], v[180:183], v[204:207], v[16:19]
	v_mfma_f32_16x16x32_bf16 v[4:7], v[172:175], v[212:215], v[4:7]
	v_mfma_f32_16x16x32_bf16 v[0:3], v[180:183], v[212:215], v[0:3]
	s_barrier
	s_setprio 0
	s_add_i32 s66, s66, 2
	s_add_u32 s30, s30, 0x100
	s_addc_u32 s31, s31, 0
	s_add_u32 s64, s64, 0x100
	s_addc_u32 s65, s65, 0
	s_cmp_gt_u32 s66, 29
.LBB0_775:
	ds_read_b128 v[152:155], v149
	ds_read_b128 v[156:159], v149 offset:1024
	ds_read_b128 v[160:163], v149 offset:2048
	ds_read_b128 v[164:167], v149 offset:3072
	ds_read_b128 v[168:171], v150
	ds_read_b128 v[172:175], v150 offset:1024
	ds_read_b128 v[176:179], v150 offset:2048
	ds_read_b128 v[180:183], v150 offset:3072
	s_add_u32 s34, s30, 0xfff80080
	s_addc_u32 s35, s31, -1
	s_cmp_eq_u32 s66, 28
	s_cselect_b32 s37, s23, s35
	s_cselect_b32 s36, s62, s34
	s_cselect_b32 s35, s21, s65
	s_cselect_b32 s34, s63, s64
	v_lshl_add_u64 v[144:145], s[30:31], 0, v[136:137]
	s_add_i32 m0, s50, 0xc000
	ds_read_b128 v[184:187], v151
	ds_read_b128 v[188:191], v151 offset:1024
	ds_read_b128 v[192:195], v151 offset:2048
	ds_read_b128 v[196:199], v151 offset:3072
	ds_read_b128 v[200:203], v151 offset:4096
	ds_read_b128 v[204:207], v151 offset:5120
	ds_read_b128 v[208:211], v151 offset:6144
	ds_read_b128 v[212:215], v151 offset:7168
	global_load_lds_dwordx4 v[144:145], off
	v_lshl_add_u64 v[144:145], s[30:31], 0, v[138:139]
	s_add_i32 m0, s50, 0xe000
	s_nop 0
	global_load_lds_dwordx4 v[144:145], off
	s_waitcnt vmcnt(8) lgkmcnt(0)
	s_setprio 1
	s_barrier
; #define PG8_STAGE(bufoff, gbase, voff) do { _Pragma("unroll") for (int _i = 0; _i < 2; ++_i) \
;         __builtin_amdgcn_global_load_lds((const unsigned*)((const char*)(gbase) + (voff)[_i]), (PG8_LAS unsigned*)(lds + (bufoff) + ldsw + _i * 8192), 16, 0, 0); } while (0)
; #define PG8_LDA(dst, b, h) do { _Pragma("unroll") for (int m = 0; m < 4; ++m) _Pragma("unroll") for (int k = 0; k < 2; ++k) dst[m][k] = *(const PG8_LAS bf16x8*)(lds + PG8_SA(b, h) + aoff + m * 2048 + k * 1024); } while (0)
; #define PG8_LDB(dst, b, h) do { _Pragma("unroll") for (int n = 0; n < 2; ++n) _Pragma("unroll") for (int k = 0; k < 2; ++k) dst[n][k] = *(const PG8_LAS bf16x8*)(lds + PG8_SB(b, h) + boff + n * 2048 + k * 1024); } while (0)
; #define PG8_MMA(ai, bj, At, Bt) do { __builtin_amdgcn_s_setprio(1); _Pragma("unroll") for (int m = 0; m < 4; ++m) _Pragma("unroll") for (int n = 0; n < 2; ++n) _Pragma("unroll") for (int k = 0; k < 2; ++k) \
;         acc[ai][bj][m][n] = __builtin_amdgcn_mfma_f32_16x16x32_bf16(Bt[n][k], At[m][k], acc[ai][bj][m][n], 0, 0, 0); __builtin_amdgcn_s_setprio(0); } while (0)
; #define PG8_WAIT_V(n) asm volatile("s_waitcnt vmcnt(" #n ")" ::: "memory")
; template <class Epi, class Sched, bool ALIGN_EPI = false, bool SP2 = false>
; __device__ __forceinline__ void gemm_phase(PG8_LAS unsigned char* lds, const Gemm g, const Sched& S, const Epi& E) {
;     ...
;             PG8_LDB(B0, 0, 0); PG8_LDB(B1, 0, 1); PG8_SCHED; PG8_LDA(At, 0, 0); PG8_STAGE(PG8_SA(1, 1), a1 + hstep, voffA);
;             PG8_WAIT_V(8); PG8_WAIT_L(0); PG8_BAR; PG8_MMA(0, 0, At, B0); PG8_MMA(0, 1, At, B1); PG8_BAR; PG8_SCHED;
;             PG8_LDA(At, 0, 1); PG8_STAGE(PG8_SB(0, 0), b2, voffB); PG8_STAGE(PG8_SB(0, 1), b2 + hstep, voffB); PG8_STAGE(PG8_SA(0, 0), a2, voffA);
;             PG8_WAIT_V(8); PG8_WAIT_L(0); PG8_BAR; PG8_MMA(1, 0, At, B0); PG8_MMA(1, 1, At, B1); PG8_BAR; PG8_SCHED;
;             PG8_LDB(B0, 1, 0); PG8_LDB(B1, 1, 1); PG8_SCHED; PG8_LDA(At, 1, 0); PG8_STAGE(PG8_SA(0, 1), a2 + hstep, voffA);
;             PG8_WAIT_V(8); PG8_WAIT_L(0); PG8_BAR; PG8_MMA(0, 0, At, B0); PG8_MMA(0, 1, At, B1); PG8_BAR; PG8_SCHED;
;             PG8_LDA(At, 1, 1); PG8_STAGE(PG8_SB(1, 0), b3, voffB); PG8_STAGE(PG8_SB(1, 1), b3 + hstep, voffB); PG8_STAGE(PG8_SA(1, 0), a3, voffA);
;             PG8_WAIT_V(8); PG8_WAIT_L(0); PG8_BAR; PG8_MMA(1, 0, At, B0); PG8_MMA(1, 1, At, B1); PG8_BAR; PG8_SCHED;
	v_mfma_f32_16x16x32_bf16 v[124:127], v[152:155], v[184:187], v[124:127]
	v_mfma_f32_16x16x32_bf16 v[120:123], v[160:163], v[184:187], v[120:123]
	v_mfma_f32_16x16x32_bf16 v[108:111], v[152:155], v[192:195], v[108:111]
	v_mfma_f32_16x16x32_bf16 v[104:107], v[160:163], v[192:195], v[104:107]
	v_mfma_f32_16x16x32_bf16 v[92:95], v[152:155], v[200:203], v[92:95]
	v_mfma_f32_16x16x32_bf16 v[88:91], v[160:163], v[200:203], v[88:91]
	v_mfma_f32_16x16x32_bf16 v[76:79], v[152:155], v[208:211], v[76:79]
	v_mfma_f32_16x16x32_bf16 v[72:75], v[160:163], v[208:211], v[72:75]
	v_mfma_f32_16x16x32_bf16 v[124:127], v[156:159], v[188:191], v[124:127]
	v_mfma_f32_16x16x32_bf16 v[120:123], v[164:167], v[188:191], v[120:123]
	v_mfma_f32_16x16x32_bf16 v[108:111], v[156:159], v[196:199], v[108:111]
	v_mfma_f32_16x16x32_bf16 v[104:107], v[164:167], v[196:199], v[104:107]
	v_mfma_f32_16x16x32_bf16 v[92:95], v[156:159], v[204:207], v[92:95]
	v_mfma_f32_16x16x32_bf16 v[88:91], v[164:167], v[204:207], v[88:91]
	v_mfma_f32_16x16x32_bf16 v[76:79], v[156:159], v[212:215], v[76:79]
	v_mfma_f32_16x16x32_bf16 v[72:75], v[164:167], v[212:215], v[72:75]
	v_mfma_f32_16x16x32_bf16 v[116:119], v[168:171], v[184:187], v[116:119]
	v_mfma_f32_16x16x32_bf16 v[112:115], v[176:179], v[184:187], v[112:115]
	v_mfma_f32_16x16x32_bf16 v[100:103], v[168:171], v[192:195], v[100:103]
	v_mfma_f32_16x16x32_bf16 v[96:99], v[176:179], v[192:195], v[96:99]
	v_mfma_f32_16x16x32_bf16 v[84:87], v[168:171], v[200:203], v[84:87]
	v_mfma_f32_16x16x32_bf16 v[80:83], v[176:179], v[200:203], v[80:83]
	v_mfma_f32_16x16x32_bf16 v[68:71], v[168:171], v[208:211], v[68:71]
	v_mfma_f32_16x16x32_bf16 v[64:67], v[176:179], v[208:211], v[64:67]
	v_mfma_f32_16x16x32_bf16 v[116:119], v[172:175], v[188:191], v[116:119]
	v_mfma_f32_16x16x32_bf16 v[112:115], v[180:183], v[188:191], v[112:115]
	v_mfma_f32_16x16x32_bf16 v[100:103], v[172:175], v[196:199], v[100:103]
	v_mfma_f32_16x16x32_bf16 v[96:99], v[180:183], v[196:199], v[96:99]
	v_mfma_f32_16x16x32_bf16 v[84:87], v[172:175], v[204:207], v[84:87]
	v_mfma_f32_16x16x32_bf16 v[80:83], v[180:183], v[204:207], v[80:83]
	v_mfma_f32_16x16x32_bf16 v[68:71], v[172:175], v[212:215], v[68:71]
	v_mfma_f32_16x16x32_bf16 v[64:67], v[180:183], v[212:215], v[64:67]
	s_barrier
	s_setprio 0
	s_add_i32 s67, s60, s47
	v_lshl_add_u64 v[144:145], s[34:35], 0, v[132:133]
	s_mov_b32 m0, s67
	ds_read_b128 v[184:187], v151 offset:16384
	ds_read_b128 v[188:191], v151 offset:17408
	ds_read_b128 v[192:195], v151 offset:18432
	ds_read_b128 v[196:199], v151 offset:19456
	ds_read_b128 v[200:203], v151 offset:20480
	ds_read_b128 v[204:207], v151 offset:21504
	ds_read_b128 v[208:211], v151 offset:22528
	ds_read_b128 v[212:215], v151 offset:23552
	global_load_lds_dwordx4 v[144:145], off
	s_add_i32 m0, s67, 0x2000
	s_add_u32 s68, s34, 0x80000
	v_lshl_add_u64 v[218:219], s[34:35], 0, v[128:129]
	s_addc_u32 s69, s35, 0
	s_add_i32 s67, s61, s47
	global_load_lds_dwordx4 v[218:219], off
	v_lshl_add_u64 v[220:221], s[68:69], 0, v[132:133]
	s_mov_b32 m0, s67
	v_lshl_add_u64 v[222:223], s[36:37], 0, v[130:131]
	global_load_lds_dwordx4 v[220:221], off
	v_lshl_add_u64 v[220:221], s[68:69], 0, v[128:129]
	s_add_i32 m0, s67, 0x2000
	s_nop 0
	global_load_lds_dwordx4 v[220:221], off
	v_lshl_add_u64 v[220:221], s[36:37], 0, v[134:135]
	s_mov_b32 m0, s50
	s_nop 0
	global_load_lds_dwordx4 v[220:221], off
	s_mov_b32 m0, s51
	s_nop 0
	global_load_lds_dwordx4 v[222:223], off
	s_waitcnt vmcnt(8) lgkmcnt(0)
	s_setprio 1
	s_barrier
	v_mfma_f32_16x16x32_bf16 v[60:63], v[152:155], v[184:187], v[60:63]
	v_mfma_f32_16x16x32_bf16 v[56:59], v[160:163], v[184:187], v[56:59]
	v_mfma_f32_16x16x32_bf16 v[44:47], v[152:155], v[192:195], v[44:47]
	v_mfma_f32_16x16x32_bf16 v[40:43], v[160:163], v[192:195], v[40:43]
	v_mfma_f32_16x16x32_bf16 v[28:31], v[152:155], v[200:203], v[28:31]
	v_mfma_f32_16x16x32_bf16 v[24:27], v[160:163], v[200:203], v[24:27]
	v_mfma_f32_16x16x32_bf16 v[12:15], v[152:155], v[208:211], v[12:15]
	v_mfma_f32_16x16x32_bf16 v[8:11], v[160:163], v[208:211], v[8:11]
	v_mfma_f32_16x16x32_bf16 v[60:63], v[156:159], v[188:191], v[60:63]
	v_mfma_f32_16x16x32_bf16 v[56:59], v[164:167], v[188:191], v[56:59]
	v_mfma_f32_16x16x32_bf16 v[44:47], v[156:159], v[196:199], v[44:47]
	v_mfma_f32_16x16x32_bf16 v[40:43], v[164:167], v[196:199], v[40:43]
	v_mfma_f32_16x16x32_bf16 v[28:31], v[156:159], v[204:207], v[28:31]
	v_mfma_f32_16x16x32_bf16 v[24:27], v[164:167], v[204:207], v[24:27]
	v_mfma_f32_16x16x32_bf16 v[12:15], v[156:159], v[212:215], v[12:15]
	v_mfma_f32_16x16x32_bf16 v[8:11], v[164:167], v[212:215], v[8:11]
	v_mfma_f32_16x16x32_bf16 v[52:55], v[168:171], v[184:187], v[52:55]
	v_mfma_f32_16x16x32_bf16 v[48:51], v[176:179], v[184:187], v[48:51]
	v_mfma_f32_16x16x32_bf16 v[36:39], v[168:171], v[192:195], v[36:39]
	v_mfma_f32_16x16x32_bf16 v[32:35], v[176:179], v[192:195], v[32:35]
	v_mfma_f32_16x16x32_bf16 v[20:23], v[168:171], v[200:203], v[20:23]
	v_mfma_f32_16x16x32_bf16 v[16:19], v[176:179], v[200:203], v[16:19]
	v_mfma_f32_16x16x32_bf16 v[4:7], v[168:171], v[208:211], v[4:7]
	v_mfma_f32_16x16x32_bf16 v[0:3], v[176:179], v[208:211], v[0:3]
	v_mfma_f32_16x16x32_bf16 v[52:55], v[172:175], v[188:191], v[52:55]
	v_mfma_f32_16x16x32_bf16 v[48:51], v[180:183], v[188:191], v[48:51]
	v_mfma_f32_16x16x32_bf16 v[36:39], v[172:175], v[196:199], v[36:39]
	v_mfma_f32_16x16x32_bf16 v[32:35], v[180:183], v[196:199], v[32:35]
	v_mfma_f32_16x16x32_bf16 v[20:23], v[172:175], v[204:207], v[20:23]
	v_mfma_f32_16x16x32_bf16 v[16:19], v[180:183], v[204:207], v[16:19]
	v_mfma_f32_16x16x32_bf16 v[4:7], v[172:175], v[212:215], v[4:7]
	v_mfma_f32_16x16x32_bf16 v[0:3], v[180:183], v[212:215], v[0:3]
	s_barrier
; #define PG8_STAGE(bufoff, gbase, voff) do { _Pragma("unroll") for (int _i = 0; _i < 2; ++_i) \
;         __builtin_amdgcn_global_load_lds((const unsigned*)((const char*)(gbase) + (voff)[_i]), (PG8_LAS unsigned*)(lds + (bufoff) + ldsw + _i * 8192), 16, 0, 0); } while (0)
; #define PG8_LDA(dst, b, h) do { _Pragma("unroll") for (int m = 0; m < 4; ++m) _Pragma("unroll") for (int k = 0; k < 2; ++k) dst[m][k] = *(const PG8_LAS bf16x8*)(lds + PG8_SA(b, h) + aoff + m * 2048 + k * 1024); } while (0)
; #define PG8_LDB(dst, b, h) do { _Pragma("unroll") for (int n = 0; n < 2; ++n) _Pragma("unroll") for (int k = 0; k < 2; ++k) dst[n][k] = *(const PG8_LAS bf16x8*)(lds + PG8_SB(b, h) + boff + n * 2048 + k * 1024); } while (0)
; #define PG8_MMA(ai, bj, At, Bt) do { __builtin_amdgcn_s_setprio(1); _Pragma("unroll") for (int m = 0; m < 4; ++m) _Pragma("unroll") for (int n = 0; n < 2; ++n) _Pragma("unroll") for (int k = 0; k < 2; ++k) \
;         acc[ai][bj][m][n] = __builtin_amdgcn_mfma_f32_16x16x32_bf16(Bt[n][k], At[m][k], acc[ai][bj][m][n], 0, 0, 0); __builtin_amdgcn_s_setprio(0); } while (0)
; #define PG8_WAIT_V(n) asm volatile("s_waitcnt vmcnt(" #n ")" ::: "memory")
; #define PG8_WAIT_L(n) asm volatile("s_waitcnt lgkmcnt(" #n ")" ::: "memory")
; #define PG8_BAR __builtin_amdgcn_s_barrier()
; #define PG8_SCHED __builtin_amdgcn_sched_barrier(0)
; template <class Epi, class Sched, bool ALIGN_EPI = false, bool SP2 = false>
; __device__ __forceinline__ void gemm_phase(PG8_LAS unsigned char* lds, const Gemm g, const Sched& S, const Epi& E) {
;     ...
;             PG8_LDB(B0, 1, 0); PG8_LDB(B1, 1, 1); PG8_SCHED; PG8_LDA(At, 1, 0); PG8_STAGE(PG8_SA(0, 1), a2 + hstep, voffA);
;             PG8_WAIT_V(8); PG8_WAIT_L(0); PG8_BAR; PG8_MMA(0, 0, At, B0); PG8_MMA(0, 1, At, B1); PG8_BAR; PG8_SCHED;
	s_setprio 0
	s_add_i32 s67, 0, 0x18000
	s_add_i32 s68, 0, 0x1c000
	v_add_u32_e32 v164, s67, v147
	v_add_u32_e32 v180, s68, v147
	ds_read_b128 v[152:155], v164
	ds_read_b128 v[156:159], v164 offset:1024
	ds_read_b128 v[160:163], v164 offset:2048
	ds_read_b128 v[164:167], v164 offset:3072
	ds_read_b128 v[168:171], v180
	ds_read_b128 v[172:175], v180 offset:1024
	ds_read_b128 v[176:179], v180 offset:2048
	ds_read_b128 v[180:183], v180 offset:3072
	s_add_u32 s36, s36, 0x80000
	s_addc_u32 s37, s37, 0
	s_mov_b32 m0, s52
	v_lshl_add_u64 v[224:225], s[36:37], 0, v[134:135]
	ds_read_b128 v[184:187], v151 offset:32768
	ds_read_b128 v[188:191], v151 offset:33792
	ds_read_b128 v[192:195], v151 offset:34816
	ds_read_b128 v[196:199], v151 offset:35840
	ds_read_b128 v[200:203], v151 offset:36864
	ds_read_b128 v[204:207], v151 offset:37888
	ds_read_b128 v[208:211], v151 offset:38912
	ds_read_b128 v[212:215], v151 offset:39936
	global_load_lds_dwordx4 v[224:225], off
	v_lshl_add_u64 v[224:225], s[36:37], 0, v[130:131]
	s_mov_b32 m0, s53
	s_nop 0
	global_load_lds_dwordx4 v[224:225], off
	s_waitcnt vmcnt(8) lgkmcnt(0)
	s_setprio 1
	s_barrier
	v_mfma_f32_16x16x32_bf16 v[124:127], v[152:155], v[184:187], v[124:127]
	v_mfma_f32_16x16x32_bf16 v[120:123], v[160:163], v[184:187], v[120:123]
	v_mfma_f32_16x16x32_bf16 v[108:111], v[152:155], v[192:195], v[108:111]
	v_mfma_f32_16x16x32_bf16 v[104:107], v[160:163], v[192:195], v[104:107]
	v_mfma_f32_16x16x32_bf16 v[92:95], v[152:155], v[200:203], v[92:95]
	v_mfma_f32_16x16x32_bf16 v[88:91], v[160:163], v[200:203], v[88:91]
	v_mfma_f32_16x16x32_bf16 v[76:79], v[152:155], v[208:211], v[76:79]
	v_mfma_f32_16x16x32_bf16 v[72:75], v[160:163], v[208:211], v[72:75]
	v_mfma_f32_16x16x32_bf16 v[124:127], v[156:159], v[188:191], v[124:127]
	v_mfma_f32_16x16x32_bf16 v[120:123], v[164:167], v[188:191], v[120:123]
	v_mfma_f32_16x16x32_bf16 v[108:111], v[156:159], v[196:199], v[108:111]
	v_mfma_f32_16x16x32_bf16 v[104:107], v[164:167], v[196:199], v[104:107]
	v_mfma_f32_16x16x32_bf16 v[92:95], v[156:159], v[204:207], v[92:95]
	v_mfma_f32_16x16x32_bf16 v[88:91], v[164:167], v[204:207], v[88:91]
	v_mfma_f32_16x16x32_bf16 v[76:79], v[156:159], v[212:215], v[76:79]
	v_mfma_f32_16x16x32_bf16 v[72:75], v[164:167], v[212:215], v[72:75]
	v_mfma_f32_16x16x32_bf16 v[116:119], v[168:171], v[184:187], v[116:119]
	v_mfma_f32_16x16x32_bf16 v[112:115], v[176:179], v[184:187], v[112:115]
	v_mfma_f32_16x16x32_bf16 v[100:103], v[168:171], v[192:195], v[100:103]
	v_mfma_f32_16x16x32_bf16 v[96:99], v[176:179], v[192:195], v[96:99]
	v_mfma_f32_16x16x32_bf16 v[84:87], v[168:171], v[200:203], v[84:87]
	v_mfma_f32_16x16x32_bf16 v[80:83], v[176:179], v[200:203], v[80:83]
	v_mfma_f32_16x16x32_bf16 v[68:71], v[168:171], v[208:211], v[68:71]
	v_mfma_f32_16x16x32_bf16 v[64:67], v[176:179], v[208:211], v[64:67]
	v_mfma_f32_16x16x32_bf16 v[116:119], v[172:175], v[188:191], v[116:119]
	v_mfma_f32_16x16x32_bf16 v[112:115], v[180:183], v[188:191], v[112:115]
	v_mfma_f32_16x16x32_bf16 v[100:103], v[172:175], v[196:199], v[100:103]
	v_mfma_f32_16x16x32_bf16 v[96:99], v[180:183], v[196:199], v[96:99]
	v_mfma_f32_16x16x32_bf16 v[84:87], v[172:175], v[204:207], v[84:87]
	v_mfma_f32_16x16x32_bf16 v[80:83], v[180:183], v[204:207], v[80:83]
	v_mfma_f32_16x16x32_bf16 v[68:71], v[172:175], v[212:215], v[68:71]
	v_mfma_f32_16x16x32_bf16 v[64:67], v[180:183], v[212:215], v[64:67]
	s_barrier
; #define PG8_STAGE(bufoff, gbase, voff) do { _Pragma("unroll") for (int _i = 0; _i < 2; ++_i) \
;         __builtin_amdgcn_global_load_lds((const unsigned*)((const char*)(gbase) + (voff)[_i]), (PG8_LAS unsigned*)(lds + (bufoff) + ldsw + _i * 8192), 16, 0, 0); } while (0)
; #define PG8_LDA(dst, b, h) do { _Pragma("unroll") for (int m = 0; m < 4; ++m) _Pragma("unroll") for (int k = 0; k < 2; ++k) dst[m][k] = *(const PG8_LAS bf16x8*)(lds + PG8_SA(b, h) + aoff + m * 2048 + k * 1024); } while (0)
; #define PG8_LDB(dst, b, h) do { _Pragma("unroll") for (int n = 0; n < 2; ++n) _Pragma("unroll") for (int k = 0; k < 2; ++k) dst[n][k] = *(const PG8_LAS bf16x8*)(lds + PG8_SB(b, h) + boff + n * 2048 + k * 1024); } while (0)
; #define PG8_MMA(ai, bj, At, Bt) do { __builtin_amdgcn_s_setprio(1); _Pragma("unroll") for (int m = 0; m < 4; ++m) _Pragma("unroll") for (int n = 0; n < 2; ++n) _Pragma("unroll") for (int k = 0; k < 2; ++k) \
;         acc[ai][bj][m][n] = __builtin_amdgcn_mfma_f32_16x16x32_bf16(Bt[n][k], At[m][k], acc[ai][bj][m][n], 0, 0, 0); __builtin_amdgcn_s_setprio(0); } while (0)
; #define PG8_WAIT_V(n) asm volatile("s_waitcnt vmcnt(" #n ")" ::: "memory")
; #define PG8_WAIT_L(n) asm volatile("s_waitcnt lgkmcnt(" #n ")" ::: "memory")
; #define PG8_BAR __builtin_amdgcn_s_barrier()
; #define PG8_SCHED __builtin_amdgcn_sched_barrier(0)
; template <class Epi, class Sched, bool ALIGN_EPI = false, bool SP2 = false>
; __device__ __forceinline__ void gemm_phase(PG8_LAS unsigned char* lds, const Gemm g, const Sched& S, const Epi& E) {
;     ...
;             PG8_LDB(B0, 1, 0); PG8_LDB(B1, 1, 1); PG8_SCHED; PG8_LDA(At, 1, 0); PG8_STAGE(PG8_SA(0, 1), a2 + hstep, voffA);
;             PG8_WAIT_V(8); PG8_WAIT_L(0); PG8_BAR; PG8_MMA(0, 0, At, B0); PG8_MMA(0, 1, At, B1); PG8_BAR; PG8_SCHED;
;             PG8_LDA(At, 1, 1); PG8_STAGE(PG8_SB(1, 0), b3, voffB); PG8_STAGE(PG8_SB(1, 1), b3 + hstep, voffB); PG8_STAGE(PG8_SA(1, 0), a3, voffA);
;             PG8_WAIT_V(8); PG8_WAIT_L(0); PG8_BAR; PG8_MMA(1, 0, At, B0); PG8_MMA(1, 1, At, B1); PG8_BAR; PG8_SCHED;
;     ...
;         if constexpr (ALIGN_EPI) { if (wr == 0) PG8_BAR; }
	s_setprio 0
	s_add_i32 s36, s67, s47
	v_lshl_add_u64 v[144:145], v[144:145], 0, s[16:17]
	s_mov_b32 m0, s36
	ds_read_b128 v[184:187], v151 offset:49152
	ds_read_b128 v[188:191], v151 offset:50176
	ds_read_b128 v[192:195], v151 offset:51200
	ds_read_b128 v[196:199], v151 offset:52224
	ds_read_b128 v[200:203], v151 offset:53248
	ds_read_b128 v[204:207], v151 offset:54272
	ds_read_b128 v[208:211], v151 offset:55296
	ds_read_b128 v[212:215], v151 offset:56320
	global_load_lds_dwordx4 v[144:145], off
	s_add_i32 m0, s36, 0x2000
	s_add_u32 s34, s34, 0x80080
	v_lshl_add_u64 v[144:145], v[218:219], 0, s[16:17]
	s_addc_u32 s35, s35, 0
	s_add_i32 s36, s68, s47
	global_load_lds_dwordx4 v[144:145], off
	v_lshl_add_u64 v[144:145], s[34:35], 0, v[132:133]
	s_mov_b32 m0, s36
	s_nop 0
	global_load_lds_dwordx4 v[144:145], off
	v_lshl_add_u64 v[144:145], s[34:35], 0, v[128:129]
	s_add_i32 m0, s36, 0x2000
	s_nop 0
	global_load_lds_dwordx4 v[144:145], off
	v_lshl_add_u64 v[144:145], v[220:221], 0, s[16:17]
	s_mov_b32 m0, s55
	s_nop 0
	global_load_lds_dwordx4 v[144:145], off
	v_lshl_add_u64 v[144:145], v[222:223], 0, s[16:17]
	s_mov_b32 m0, s59
	s_nop 0
	global_load_lds_dwordx4 v[144:145], off
	s_waitcnt vmcnt(8) lgkmcnt(0)
	s_setprio 1
	s_barrier
	v_mfma_f32_16x16x32_bf16 v[60:63], v[152:155], v[184:187], v[60:63]
	v_mfma_f32_16x16x32_bf16 v[56:59], v[160:163], v[184:187], v[56:59]
	v_mfma_f32_16x16x32_bf16 v[44:47], v[152:155], v[192:195], v[44:47]
	v_mfma_f32_16x16x32_bf16 v[40:43], v[160:163], v[192:195], v[40:43]
	v_mfma_f32_16x16x32_bf16 v[28:31], v[152:155], v[200:203], v[28:31]
	v_mfma_f32_16x16x32_bf16 v[24:27], v[160:163], v[200:203], v[24:27]
	v_mfma_f32_16x16x32_bf16 v[12:15], v[152:155], v[208:211], v[12:15]
	v_mfma_f32_16x16x32_bf16 v[8:11], v[160:163], v[208:211], v[8:11]
	v_mfma_f32_16x16x32_bf16 v[60:63], v[156:159], v[188:191], v[60:63]
	v_mfma_f32_16x16x32_bf16 v[56:59], v[164:167], v[188:191], v[56:59]
	v_mfma_f32_16x16x32_bf16 v[44:47], v[156:159], v[196:199], v[44:47]
	v_mfma_f32_16x16x32_bf16 v[40:43], v[164:167], v[196:199], v[40:43]
	v_mfma_f32_16x16x32_bf16 v[28:31], v[156:159], v[204:207], v[28:31]
	v_mfma_f32_16x16x32_bf16 v[24:27], v[164:167], v[204:207], v[24:27]
	v_mfma_f32_16x16x32_bf16 v[12:15], v[156:159], v[212:215], v[12:15]
	v_mfma_f32_16x16x32_bf16 v[8:11], v[164:167], v[212:215], v[8:11]
	v_mfma_f32_16x16x32_bf16 v[52:55], v[168:171], v[184:187], v[52:55]
	v_mfma_f32_16x16x32_bf16 v[48:51], v[176:179], v[184:187], v[48:51]
	v_mfma_f32_16x16x32_bf16 v[36:39], v[168:171], v[192:195], v[36:39]
	v_mfma_f32_16x16x32_bf16 v[32:35], v[176:179], v[192:195], v[32:35]
	v_mfma_f32_16x16x32_bf16 v[20:23], v[168:171], v[200:203], v[20:23]
	v_mfma_f32_16x16x32_bf16 v[16:19], v[176:179], v[200:203], v[16:19]
	v_mfma_f32_16x16x32_bf16 v[4:7], v[168:171], v[208:211], v[4:7]
	v_mfma_f32_16x16x32_bf16 v[0:3], v[176:179], v[208:211], v[0:3]
	v_mfma_f32_16x16x32_bf16 v[52:55], v[172:175], v[188:191], v[52:55]
	v_mfma_f32_16x16x32_bf16 v[48:51], v[180:183], v[188:191], v[48:51]
	v_mfma_f32_16x16x32_bf16 v[36:39], v[172:175], v[196:199], v[36:39]
	v_mfma_f32_16x16x32_bf16 v[32:35], v[180:183], v[196:199], v[32:35]
	v_mfma_f32_16x16x32_bf16 v[20:23], v[172:175], v[204:207], v[20:23]
	v_mfma_f32_16x16x32_bf16 v[16:19], v[180:183], v[204:207], v[16:19]
	v_mfma_f32_16x16x32_bf16 v[4:7], v[172:175], v[212:215], v[4:7]
	v_mfma_f32_16x16x32_bf16 v[0:3], v[180:183], v[212:215], v[0:3]
	s_barrier
	s_setprio 0
	s_add_i32 s66, s66, 2
	s_add_u32 s30, s30, 0x100
	s_addc_u32 s31, s31, 0
	s_add_u32 s64, s64, 0x100
	s_addc_u32 s65, s65, 0
	s_cmp_gt_u32 s66, 29
	s_cbranch_scc0 .LBB0_775
	s_and_b64 vcc, exec, s[18:19]
	s_cbranch_vccz .LBB0_778
	s_barrier

; #define PG8_STAGE(bufoff, gbase, voff) do { _Pragma("unroll") for (int _i = 0; _i < 2; ++_i) \
;         __builtin_amdgcn_global_load_lds((const unsigned*)((const char*)(gbase) + (voff)[_i]), (PG8_LAS unsigned*)(lds + (bufoff) + ldsw + _i * 8192), 16, 0, 0); } while (0)
; #define PG8_LDA(dst, b, h) do { _Pragma("unroll") for (int m = 0; m < 4; ++m) _Pragma("unroll") for (int k = 0; k < 2; ++k) dst[m][k] = *(const PG8_LAS bf16x8*)(lds + PG8_SA(b, h) + aoff + m * 2048 + k * 1024); } while (0)
; template <class Epi, class Sched, bool ALIGN_EPI = false, bool SP2 = false>
; __device__ __forceinline__ void gemm_phase(PG8_LAS unsigned char* lds, const Gemm g, const Sched& S, const Epi& E) {
;     ...
;         const bool has_next = S.next(ui + 1, nxt);
;         const char* nA = has_next ? (const char*)g.A + (size_t)nxt.pm * tstep : cA; const char* nB = has_next ? (const char*)g.Bt + (size_t)nxt.pn * tstep : cB;
;         for (int t = 0; t < nt; t += 2) {
;             const bool last = (t == nt - 2);
;             const char* a1 = cA + (size_t)(t + 1) * kstep;
;             const char* a2 = last ? nA : cA + (size_t)(t + 2) * kstep; const char* b2 = last ? nB : cB + (size_t)(t + 2) * kstep;
;             const char* a3 = a2 + kstep; const char* b3 = b2 + kstep;
;             if (last && has_next) S.a_ready(nxt);
;             if constexpr (SP2) {
;             PG8_LDB(B0, 0, 0); PG8_LDB(B1, 0, 1); PG8_SCHED; PG8_LDA(At, 0, 0); PG8_STAGE(PG8_SA(1, 1), a1 + hstep, voffA);
;             PG8_WAIT_V(8); PG8_WAIT_L(0); PG8_BAR; PG8_MMA(0, 0, At, B0); PG8_MMA(0, 1, At, B1); PG8_BAR; PG8_SCHED;
;             PG8_LDA(At, 0, 1); PG8_STAGE(PG8_SB(0, 0), b2, voffB); PG8_STAGE(PG8_SB(0, 1), b2 + hstep, voffB); PG8_STAGE(PG8_SA(0, 0), a2, voffA);
;             PG8_WAIT_V(8); PG8_WAIT_L(0); PG8_BAR; PG8_MMA(1, 0, At, B0); PG8_MMA(1, 1, At, B1); PG8_BAR; PG8_SCHED;
;             PG8_LDB(B0, 1, 0); PG8_LDB(B1, 1, 1); PG8_SCHED; PG8_LDA(At, 1, 0); PG8_STAGE(PG8_SA(0, 1), a2 + hstep, voffA);
;             PG8_WAIT_V(8); PG8_WAIT_L(0); PG8_BAR; PG8_MMA(0, 0, At, B0); PG8_MMA(0, 1, At, B1); PG8_BAR; PG8_SCHED;
;             PG8_LDA(At, 1, 1); PG8_STAGE(PG8_SB(1, 0), b3, voffB); PG8_STAGE(PG8_SB(1, 1), b3 + hstep, voffB); PG8_STAGE(PG8_SA(1, 0), a3, voffA);
;             PG8_WAIT_V(8); PG8_WAIT_L(0); PG8_BAR; PG8_MMA(1, 0, At, B0); PG8_MMA(1, 1, At, B1); PG8_BAR; PG8_SCHED;
.LBB0_846:
	s_ashr_i32 s23, s22, 31
	s_lshl_b64 s[24:25], s[22:23], 22
	s_add_u32 s24, s40, s24
	s_addc_u32 s25, s41, s25
	s_and_b64 s[26:27], s[0:1], exec
	s_cselect_b32 s23, s25, s31
	s_cselect_b32 s57, s24, s30
	s_ashr_i32 s21, s20, 31
	s_lshl_b64 s[26:27], s[20:21], 22
	s_add_u32 s26, s44, s26
	s_addc_u32 s27, s45, s27
	s_and_b64 s[36:37], s[0:1], exec
	s_cselect_b32 s21, s27, s35
	s_cselect_b32 s58, s26, s34
	s_add_u32 s59, s34, 0x100
	s_addc_u32 s60, s35, 0
	s_mov_b32 s61, -2
	ds_read_b128 v[72:75], v165
	ds_read_b128 v[84:87], v165 offset:1024
	ds_read_b128 v[92:95], v165 offset:2048
	ds_read_b128 v[108:111], v165 offset:3072
	ds_read_b128 v[156:159], v166
	ds_read_b128 v[168:171], v166 offset:1024
	ds_read_b128 v[172:175], v166 offset:2048
	ds_read_b128 v[176:179], v166 offset:3072
	s_add_u32 s34, s30, 0x100
	s_addc_u32 s35, s31, 0
	s_cmpk_eq_i32 s61, 0x7c
	s_cselect_b32 s39, s23, s35
	s_cselect_b32 s38, s57, s34
	s_cselect_b32 s37, s21, s60
	s_cselect_b32 s36, s58, s59
	v_lshl_add_u64 v[160:161], s[30:31], 0, v[148:149]
	s_add_i32 m0, s42, 0xc000
	ds_read_b128 v[180:183], v167
	ds_read_b128 v[184:187], v167 offset:1024
	ds_read_b128 v[188:191], v167 offset:2048
	ds_read_b128 v[192:195], v167 offset:3072
	ds_read_b128 v[196:199], v167 offset:4096
	ds_read_b128 v[200:203], v167 offset:5120
	ds_read_b128 v[204:207], v167 offset:6144
	ds_read_b128 v[208:211], v167 offset:7168
	global_load_lds_dwordx4 v[160:161], off
	v_lshl_add_u64 v[160:161], s[30:31], 0, v[150:151]
	s_add_i32 m0, s42, 0xe000
	s_nop 0
	global_load_lds_dwordx4 v[160:161], off
	s_waitcnt vmcnt(8) lgkmcnt(0)
	s_setprio 1
	s_barrier
	v_mfma_f32_16x16x32_bf16 v[140:143], v[72:75], v[180:183], 0
	v_mfma_f32_16x16x32_bf16 v[136:139], v[92:95], v[180:183], 0
	v_mfma_f32_16x16x32_bf16 v[132:135], v[72:75], v[188:191], 0
	v_mfma_f32_16x16x32_bf16 v[128:131], v[92:95], v[188:191], 0
	v_mfma_f32_16x16x32_bf16 v[120:123], v[72:75], v[196:199], 0
	v_mfma_f32_16x16x32_bf16 v[112:115], v[92:95], v[196:199], 0
	v_mfma_f32_16x16x32_bf16 v[100:103], v[72:75], v[204:207], 0
	v_mfma_f32_16x16x32_bf16 v[88:91], v[92:95], v[204:207], 0
	v_mfma_f32_16x16x32_bf16 v[140:143], v[84:87], v[184:187], v[140:143]
	v_mfma_f32_16x16x32_bf16 v[136:139], v[108:111], v[184:187], v[136:139]
	v_mfma_f32_16x16x32_bf16 v[132:135], v[84:87], v[192:195], v[132:135]
	v_mfma_f32_16x16x32_bf16 v[128:131], v[108:111], v[192:195], v[128:131]
	v_mfma_f32_16x16x32_bf16 v[120:123], v[84:87], v[200:203], v[120:123]
	v_mfma_f32_16x16x32_bf16 v[112:115], v[108:111], v[200:203], v[112:115]
	v_mfma_f32_16x16x32_bf16 v[100:103], v[84:87], v[208:211], v[100:103]
	v_mfma_f32_16x16x32_bf16 v[88:91], v[108:111], v[208:211], v[88:91]
	v_mfma_f32_16x16x32_bf16 v[124:127], v[156:159], v[180:183], 0
	v_mfma_f32_16x16x32_bf16 v[116:119], v[172:175], v[180:183], 0
	v_mfma_f32_16x16x32_bf16 v[104:107], v[156:159], v[188:191], 0
	v_mfma_f32_16x16x32_bf16 v[96:99], v[172:175], v[188:191], 0
	v_mfma_f32_16x16x32_bf16 v[80:83], v[156:159], v[196:199], 0
	v_mfma_f32_16x16x32_bf16 v[76:79], v[172:175], v[196:199], 0
	v_mfma_f32_16x16x32_bf16 v[68:71], v[156:159], v[204:207], 0
	v_mfma_f32_16x16x32_bf16 v[64:67], v[172:175], v[204:207], 0
	v_mfma_f32_16x16x32_bf16 v[124:127], v[168:171], v[184:187], v[124:127]
	v_mfma_f32_16x16x32_bf16 v[116:119], v[176:179], v[184:187], v[116:119]
	v_mfma_f32_16x16x32_bf16 v[104:107], v[168:171], v[192:195], v[104:107]
	v_mfma_f32_16x16x32_bf16 v[96:99], v[176:179], v[192:195], v[96:99]
	v_mfma_f32_16x16x32_bf16 v[80:83], v[168:171], v[200:203], v[80:83]
	v_mfma_f32_16x16x32_bf16 v[76:79], v[176:179], v[200:203], v[76:79]
	v_mfma_f32_16x16x32_bf16 v[68:71], v[168:171], v[208:211], v[68:71]
	v_mfma_f32_16x16x32_bf16 v[64:67], v[176:179], v[208:211], v[64:67]
	s_barrier
	s_setprio 0
	s_add_i32 s30, s55, s47
	v_lshl_add_u64 v[160:161], s[36:37], 0, v[146:147]
	s_mov_b32 m0, s30
	ds_read_b128 v[180:183], v167 offset:16384
	ds_read_b128 v[184:187], v167 offset:17408
	ds_read_b128 v[188:191], v167 offset:18432
	ds_read_b128 v[192:195], v167 offset:19456
	ds_read_b128 v[196:199], v167 offset:20480
	ds_read_b128 v[200:203], v167 offset:21504
	ds_read_b128 v[204:207], v167 offset:22528
	ds_read_b128 v[208:211], v167 offset:23552
	global_load_lds_dwordx4 v[160:161], off
	s_add_i32 m0, s30, 0x2000
	s_add_u32 s30, s36, 0x200000
	v_lshl_add_u64 v[212:213], s[36:37], 0, v[144:145]
	s_addc_u32 s31, s37, 0
	s_add_i32 s62, s56, s47
	global_load_lds_dwordx4 v[212:213], off
	v_lshl_add_u64 v[214:215], s[30:31], 0, v[146:147]
	s_mov_b32 m0, s62
	v_lshl_add_u64 v[216:217], s[38:39], 0, v[144:145]
	global_load_lds_dwordx4 v[214:215], off
	v_lshl_add_u64 v[214:215], s[30:31], 0, v[144:145]
	s_add_i32 m0, s62, 0x2000
	s_nop 0
	global_load_lds_dwordx4 v[214:215], off
	v_lshl_add_u64 v[214:215], s[38:39], 0, v[146:147]
	s_mov_b32 m0, s42
	s_nop 0
	global_load_lds_dwordx4 v[214:215], off
	s_mov_b32 m0, s43
	s_nop 0
	global_load_lds_dwordx4 v[216:217], off
	s_waitcnt vmcnt(8) lgkmcnt(0)
	s_setprio 1
	s_barrier
; #define PG8_STAGE(bufoff, gbase, voff) do { _Pragma("unroll") for (int _i = 0; _i < 2; ++_i) \
;         __builtin_amdgcn_global_load_lds((const unsigned*)((const char*)(gbase) + (voff)[_i]), (PG8_LAS unsigned*)(lds + (bufoff) + ldsw + _i * 8192), 16, 0, 0); } while (0)
; #define PG8_LDA(dst, b, h) do { _Pragma("unroll") for (int m = 0; m < 4; ++m) _Pragma("unroll") for (int k = 0; k < 2; ++k) dst[m][k] = *(const PG8_LAS bf16x8*)(lds + PG8_SA(b, h) + aoff + m * 2048 + k * 1024); } while (0)
; #define PG8_LDB(dst, b, h) do { _Pragma("unroll") for (int n = 0; n < 2; ++n) _Pragma("unroll") for (int k = 0; k < 2; ++k) dst[n][k] = *(const PG8_LAS bf16x8*)(lds + PG8_SB(b, h) + boff + n * 2048 + k * 1024); } while (0)
; #define PG8_MMA(ai, bj, At, Bt) do { __builtin_amdgcn_s_setprio(1); _Pragma("unroll") for (int m = 0; m < 4; ++m) _Pragma("unroll") for (int n = 0; n < 2; ++n) _Pragma("unroll") for (int k = 0; k < 2; ++k) \
;         acc[ai][bj][m][n] = __builtin_amdgcn_mfma_f32_16x16x32_bf16(Bt[n][k], At[m][k], acc[ai][bj][m][n], 0, 0, 0); __builtin_amdgcn_s_setprio(0); } while (0)
; #define PG8_WAIT_V(n) asm volatile("s_waitcnt vmcnt(" #n ")" ::: "memory")
; #define PG8_WAIT_L(n) asm volatile("s_waitcnt lgkmcnt(" #n ")" ::: "memory")
; #define PG8_BAR __builtin_amdgcn_s_barrier()
; #define PG8_SCHED __builtin_amdgcn_sched_barrier(0)
; template <class Epi, class Sched, bool ALIGN_EPI = false, bool SP2 = false>
; __device__ __forceinline__ void gemm_phase(PG8_LAS unsigned char* lds, const Gemm g, const Sched& S, const Epi& E) {
;     ...
;             PG8_LDB(B0, 0, 0); PG8_LDB(B1, 0, 1); PG8_SCHED; PG8_LDA(At, 0, 0); PG8_STAGE(PG8_SA(1, 1), a1 + hstep, voffA);
;             PG8_WAIT_V(8); PG8_WAIT_L(0); PG8_BAR; PG8_MMA(0, 0, At, B0); PG8_MMA(0, 1, At, B1); PG8_BAR; PG8_SCHED;
;             PG8_LDA(At, 0, 1); PG8_STAGE(PG8_SB(0, 0), b2, voffB); PG8_STAGE(PG8_SB(0, 1), b2 + hstep, voffB); PG8_STAGE(PG8_SA(0, 0), a2, voffA);
;             PG8_WAIT_V(8); PG8_WAIT_L(0); PG8_BAR; PG8_MMA(1, 0, At, B0); PG8_MMA(1, 1, At, B1); PG8_BAR; PG8_SCHED;
;             PG8_LDB(B0, 1, 0); PG8_LDB(B1, 1, 1); PG8_SCHED; PG8_LDA(At, 1, 0); PG8_STAGE(PG8_SA(0, 1), a2 + hstep, voffA);
;             PG8_WAIT_V(8); PG8_WAIT_L(0); PG8_BAR; PG8_MMA(0, 0, At, B0); PG8_MMA(0, 1, At, B1); PG8_BAR; PG8_SCHED;
	v_mfma_f32_16x16x32_bf16 v[60:63], v[72:75], v[180:183], 0
	v_mfma_f32_16x16x32_bf16 v[56:59], v[92:95], v[180:183], 0
	v_mfma_f32_16x16x32_bf16 v[52:55], v[72:75], v[188:191], 0
	v_mfma_f32_16x16x32_bf16 v[44:47], v[92:95], v[188:191], 0
	v_mfma_f32_16x16x32_bf16 v[36:39], v[72:75], v[196:199], 0
	v_mfma_f32_16x16x32_bf16 v[28:31], v[92:95], v[196:199], 0
	v_mfma_f32_16x16x32_bf16 v[20:23], v[72:75], v[204:207], 0
	v_mfma_f32_16x16x32_bf16 v[12:15], v[92:95], v[204:207], 0
	v_mfma_f32_16x16x32_bf16 v[60:63], v[84:87], v[184:187], v[60:63]
	v_mfma_f32_16x16x32_bf16 v[56:59], v[108:111], v[184:187], v[56:59]
	v_mfma_f32_16x16x32_bf16 v[52:55], v[84:87], v[192:195], v[52:55]
	v_mfma_f32_16x16x32_bf16 v[44:47], v[108:111], v[192:195], v[44:47]
	v_mfma_f32_16x16x32_bf16 v[36:39], v[84:87], v[200:203], v[36:39]
	v_mfma_f32_16x16x32_bf16 v[28:31], v[108:111], v[200:203], v[28:31]
	v_mfma_f32_16x16x32_bf16 v[20:23], v[84:87], v[208:211], v[20:23]
	v_mfma_f32_16x16x32_bf16 v[12:15], v[108:111], v[208:211], v[12:15]
	v_mfma_f32_16x16x32_bf16 v[48:51], v[156:159], v[180:183], 0
	v_mfma_f32_16x16x32_bf16 v[40:43], v[172:175], v[180:183], 0
	v_mfma_f32_16x16x32_bf16 v[32:35], v[156:159], v[188:191], 0
	v_mfma_f32_16x16x32_bf16 v[24:27], v[172:175], v[188:191], 0
	v_mfma_f32_16x16x32_bf16 v[16:19], v[156:159], v[196:199], 0
	v_mfma_f32_16x16x32_bf16 v[8:11], v[172:175], v[196:199], 0
	v_mfma_f32_16x16x32_bf16 v[4:7], v[156:159], v[204:207], 0
	v_mfma_f32_16x16x32_bf16 v[0:3], v[172:175], v[204:207], 0
	v_mfma_f32_16x16x32_bf16 v[48:51], v[168:171], v[184:187], v[48:51]
	v_mfma_f32_16x16x32_bf16 v[40:43], v[176:179], v[184:187], v[40:43]
	v_mfma_f32_16x16x32_bf16 v[32:35], v[168:171], v[192:195], v[32:35]
	v_mfma_f32_16x16x32_bf16 v[24:27], v[176:179], v[192:195], v[24:27]
	v_mfma_f32_16x16x32_bf16 v[16:19], v[168:171], v[200:203], v[16:19]
	v_mfma_f32_16x16x32_bf16 v[8:11], v[176:179], v[200:203], v[8:11]
	v_mfma_f32_16x16x32_bf16 v[4:7], v[168:171], v[208:211], v[4:7]
	v_mfma_f32_16x16x32_bf16 v[0:3], v[176:179], v[208:211], v[0:3]
	s_barrier
	s_setprio 0
	s_add_i32 s62, 0, 0x18000
	s_add_i32 s63, 0, 0x1c000
	v_add_u32_e32 v108, s62, v163
	v_add_u32_e32 v176, s63, v163
	ds_read_b128 v[72:75], v108
	ds_read_b128 v[84:87], v108 offset:1024
	ds_read_b128 v[92:95], v108 offset:2048
	ds_read_b128 v[108:111], v108 offset:3072
	ds_read_b128 v[156:159], v176
	ds_read_b128 v[168:171], v176 offset:1024
	ds_read_b128 v[172:175], v176 offset:2048
	ds_read_b128 v[176:179], v176 offset:3072
	s_add_u32 s30, s38, 0x200000
	s_addc_u32 s31, s39, 0
	s_mov_b32 m0, s48
	v_lshl_add_u64 v[218:219], s[30:31], 0, v[146:147]
	ds_read_b128 v[180:183], v167 offset:32768
	ds_read_b128 v[184:187], v167 offset:33792
	ds_read_b128 v[188:191], v167 offset:34816
	ds_read_b128 v[192:195], v167 offset:35840
	ds_read_b128 v[196:199], v167 offset:36864
	ds_read_b128 v[200:203], v167 offset:37888
	ds_read_b128 v[204:207], v167 offset:38912
	ds_read_b128 v[208:211], v167 offset:39936
	global_load_lds_dwordx4 v[218:219], off
	v_lshl_add_u64 v[218:219], s[30:31], 0, v[144:145]
	s_mov_b32 m0, s49
	s_nop 0
	global_load_lds_dwordx4 v[218:219], off
	s_waitcnt vmcnt(8) lgkmcnt(0)
	s_setprio 1
	s_barrier
	v_mfma_f32_16x16x32_bf16 v[140:143], v[72:75], v[180:183], v[140:143]
	v_mfma_f32_16x16x32_bf16 v[136:139], v[92:95], v[180:183], v[136:139]
	v_mfma_f32_16x16x32_bf16 v[132:135], v[72:75], v[188:191], v[132:135]
	v_mfma_f32_16x16x32_bf16 v[128:131], v[92:95], v[188:191], v[128:131]
	v_mfma_f32_16x16x32_bf16 v[120:123], v[72:75], v[196:199], v[120:123]
	v_mfma_f32_16x16x32_bf16 v[112:115], v[92:95], v[196:199], v[112:115]
	v_mfma_f32_16x16x32_bf16 v[100:103], v[72:75], v[204:207], v[100:103]
	v_mfma_f32_16x16x32_bf16 v[88:91], v[92:95], v[204:207], v[88:91]
	v_mfma_f32_16x16x32_bf16 v[140:143], v[84:87], v[184:187], v[140:143]
	v_mfma_f32_16x16x32_bf16 v[136:139], v[108:111], v[184:187], v[136:139]
	v_mfma_f32_16x16x32_bf16 v[132:135], v[84:87], v[192:195], v[132:135]
	v_mfma_f32_16x16x32_bf16 v[128:131], v[108:111], v[192:195], v[128:131]
	v_mfma_f32_16x16x32_bf16 v[120:123], v[84:87], v[200:203], v[120:123]
	v_mfma_f32_16x16x32_bf16 v[112:115], v[108:111], v[200:203], v[112:115]
	v_mfma_f32_16x16x32_bf16 v[100:103], v[84:87], v[208:211], v[100:103]
	v_mfma_f32_16x16x32_bf16 v[88:91], v[108:111], v[208:211], v[88:91]
	v_mfma_f32_16x16x32_bf16 v[124:127], v[156:159], v[180:183], v[124:127]
	v_mfma_f32_16x16x32_bf16 v[116:119], v[172:175], v[180:183], v[116:119]
	v_mfma_f32_16x16x32_bf16 v[104:107], v[156:159], v[188:191], v[104:107]
	v_mfma_f32_16x16x32_bf16 v[96:99], v[172:175], v[188:191], v[96:99]
	v_mfma_f32_16x16x32_bf16 v[80:83], v[156:159], v[196:199], v[80:83]
	v_mfma_f32_16x16x32_bf16 v[76:79], v[172:175], v[196:199], v[76:79]
	v_mfma_f32_16x16x32_bf16 v[68:71], v[156:159], v[204:207], v[68:71]
	v_mfma_f32_16x16x32_bf16 v[64:67], v[172:175], v[204:207], v[64:67]
	v_mfma_f32_16x16x32_bf16 v[124:127], v[168:171], v[184:187], v[124:127]
	v_mfma_f32_16x16x32_bf16 v[116:119], v[176:179], v[184:187], v[116:119]
	v_mfma_f32_16x16x32_bf16 v[104:107], v[168:171], v[192:195], v[104:107]
	v_mfma_f32_16x16x32_bf16 v[96:99], v[176:179], v[192:195], v[96:99]
	v_mfma_f32_16x16x32_bf16 v[80:83], v[168:171], v[200:203], v[80:83]
	v_mfma_f32_16x16x32_bf16 v[76:79], v[176:179], v[200:203], v[76:79]
	v_mfma_f32_16x16x32_bf16 v[68:71], v[168:171], v[208:211], v[68:71]
	v_mfma_f32_16x16x32_bf16 v[64:67], v[176:179], v[208:211], v[64:67]
	s_barrier
; #define PG8_STAGE(bufoff, gbase, voff) do { _Pragma("unroll") for (int _i = 0; _i < 2; ++_i) \
;         __builtin_amdgcn_global_load_lds((const unsigned*)((const char*)(gbase) + (voff)[_i]), (PG8_LAS unsigned*)(lds + (bufoff) + ldsw + _i * 8192), 16, 0, 0); } while (0)
; #define PG8_LDA(dst, b, h) do { _Pragma("unroll") for (int m = 0; m < 4; ++m) _Pragma("unroll") for (int k = 0; k < 2; ++k) dst[m][k] = *(const PG8_LAS bf16x8*)(lds + PG8_SA(b, h) + aoff + m * 2048 + k * 1024); } while (0)
; #define PG8_WAIT_V(n) asm volatile("s_waitcnt vmcnt(" #n ")" ::: "memory")
; #define PG8_BAR __builtin_amdgcn_s_barrier()
; template <class Epi, class Sched, bool ALIGN_EPI = false, bool SP2 = false>
; __device__ __forceinline__ void gemm_phase(PG8_LAS unsigned char* lds, const Gemm g, const Sched& S, const Epi& E) {
;     ...
;         const bool has_next = S.next(ui + 1, nxt);
;         const char* nA = has_next ? (const char*)g.A + (size_t)nxt.pm * tstep : cA; const char* nB = has_next ? (const char*)g.Bt + (size_t)nxt.pn * tstep : cB;
;         for (int t = 0; t < nt; t += 2) {
;             const bool last = (t == nt - 2);
;             const char* a1 = cA + (size_t)(t + 1) * kstep;
;             const char* a2 = last ? nA : cA + (size_t)(t + 2) * kstep; const char* b2 = last ? nB : cB + (size_t)(t + 2) * kstep;
;             const char* a3 = a2 + kstep; const char* b3 = b2 + kstep;
;             if (last && has_next) S.a_ready(nxt);
;             if constexpr (SP2) {
;             PG8_LDB(B0, 0, 0); PG8_LDB(B1, 0, 1); PG8_SCHED; PG8_LDA(At, 0, 0); PG8_STAGE(PG8_SA(1, 1), a1 + hstep, voffA);
;             PG8_WAIT_V(8); PG8_WAIT_L(0); PG8_BAR; PG8_MMA(0, 0, At, B0); PG8_MMA(0, 1, At, B1); PG8_BAR; PG8_SCHED;
;             PG8_LDA(At, 0, 1); PG8_STAGE(PG8_SB(0, 0), b2, voffB); PG8_STAGE(PG8_SB(0, 1), b2 + hstep, voffB); PG8_STAGE(PG8_SA(0, 0), a2, voffA);
;     ...
;             PG8_LDB(B0, 1, 0); PG8_LDB(B1, 1, 1); PG8_SCHED; PG8_LDA(At, 1, 0); PG8_STAGE(PG8_SA(0, 1), a2 + hstep, voffA);
;             PG8_WAIT_V(8); PG8_WAIT_L(0); PG8_BAR; PG8_MMA(0, 0, At, B0); PG8_MMA(0, 1, At, B1); PG8_BAR; PG8_SCHED;
;             PG8_LDA(At, 1, 1); PG8_STAGE(PG8_SB(1, 0), b3, voffB); PG8_STAGE(PG8_SB(1, 1), b3 + hstep, voffB); PG8_STAGE(PG8_SA(1, 0), a3, voffA);
;             PG8_WAIT_V(8); PG8_WAIT_L(0); PG8_BAR; PG8_MMA(1, 0, At, B0); PG8_MMA(1, 1, At, B1); PG8_BAR; PG8_SCHED;
	s_setprio 0
	s_add_i32 s30, s62, s47
	v_lshl_add_u64 v[160:161], v[160:161], 0, s[8:9]
	s_mov_b32 m0, s30
	ds_read_b128 v[180:183], v167 offset:49152
	ds_read_b128 v[184:187], v167 offset:50176
	ds_read_b128 v[188:191], v167 offset:51200
	ds_read_b128 v[192:195], v167 offset:52224
	ds_read_b128 v[196:199], v167 offset:53248
	ds_read_b128 v[200:203], v167 offset:54272
	ds_read_b128 v[204:207], v167 offset:55296
	ds_read_b128 v[208:211], v167 offset:56320
	global_load_lds_dwordx4 v[160:161], off
	s_add_i32 m0, s30, 0x2000
	s_add_u32 s30, s36, 0x200080
	v_lshl_add_u64 v[160:161], v[212:213], 0, s[8:9]
	s_addc_u32 s31, s37, 0
	s_add_i32 s36, s63, s47
	global_load_lds_dwordx4 v[160:161], off
	v_lshl_add_u64 v[160:161], s[30:31], 0, v[146:147]
	s_mov_b32 m0, s36
	s_nop 0
	global_load_lds_dwordx4 v[160:161], off
	v_lshl_add_u64 v[160:161], s[30:31], 0, v[144:145]
	s_add_i32 m0, s36, 0x2000
	s_nop 0
	global_load_lds_dwordx4 v[160:161], off
	v_lshl_add_u64 v[160:161], v[214:215], 0, s[8:9]
	s_mov_b32 m0, s53
	s_nop 0
	global_load_lds_dwordx4 v[160:161], off
	v_lshl_add_u64 v[160:161], v[216:217], 0, s[8:9]
	s_mov_b32 m0, s54
	s_nop 0
	global_load_lds_dwordx4 v[160:161], off
	s_waitcnt vmcnt(8) lgkmcnt(0)
	s_setprio 1
	s_barrier
	v_mfma_f32_16x16x32_bf16 v[60:63], v[72:75], v[180:183], v[60:63]
	v_mfma_f32_16x16x32_bf16 v[56:59], v[92:95], v[180:183], v[56:59]
	v_mfma_f32_16x16x32_bf16 v[52:55], v[72:75], v[188:191], v[52:55]
	v_mfma_f32_16x16x32_bf16 v[44:47], v[92:95], v[188:191], v[44:47]
	v_mfma_f32_16x16x32_bf16 v[36:39], v[72:75], v[196:199], v[36:39]
	v_mfma_f32_16x16x32_bf16 v[28:31], v[92:95], v[196:199], v[28:31]
	v_mfma_f32_16x16x32_bf16 v[20:23], v[72:75], v[204:207], v[20:23]
	v_mfma_f32_16x16x32_bf16 v[12:15], v[92:95], v[204:207], v[12:15]
	v_mfma_f32_16x16x32_bf16 v[60:63], v[84:87], v[184:187], v[60:63]
	v_mfma_f32_16x16x32_bf16 v[56:59], v[108:111], v[184:187], v[56:59]
	v_mfma_f32_16x16x32_bf16 v[52:55], v[84:87], v[192:195], v[52:55]
	v_mfma_f32_16x16x32_bf16 v[44:47], v[108:111], v[192:195], v[44:47]
	v_mfma_f32_16x16x32_bf16 v[36:39], v[84:87], v[200:203], v[36:39]
	v_mfma_f32_16x16x32_bf16 v[28:31], v[108:111], v[200:203], v[28:31]
	v_mfma_f32_16x16x32_bf16 v[20:23], v[84:87], v[208:211], v[20:23]
	v_mfma_f32_16x16x32_bf16 v[12:15], v[108:111], v[208:211], v[12:15]
	v_mfma_f32_16x16x32_bf16 v[48:51], v[156:159], v[180:183], v[48:51]
	v_mfma_f32_16x16x32_bf16 v[40:43], v[172:175], v[180:183], v[40:43]
	v_mfma_f32_16x16x32_bf16 v[32:35], v[156:159], v[188:191], v[32:35]
	v_mfma_f32_16x16x32_bf16 v[24:27], v[172:175], v[188:191], v[24:27]
	v_mfma_f32_16x16x32_bf16 v[16:19], v[156:159], v[196:199], v[16:19]
	v_mfma_f32_16x16x32_bf16 v[8:11], v[172:175], v[196:199], v[8:11]
	v_mfma_f32_16x16x32_bf16 v[4:7], v[156:159], v[204:207], v[4:7]
	v_mfma_f32_16x16x32_bf16 v[0:3], v[172:175], v[204:207], v[0:3]
	v_mfma_f32_16x16x32_bf16 v[48:51], v[168:171], v[184:187], v[48:51]
	v_mfma_f32_16x16x32_bf16 v[40:43], v[176:179], v[184:187], v[40:43]
	v_mfma_f32_16x16x32_bf16 v[32:35], v[168:171], v[192:195], v[32:35]
	v_mfma_f32_16x16x32_bf16 v[24:27], v[176:179], v[192:195], v[24:27]
	v_mfma_f32_16x16x32_bf16 v[16:19], v[168:171], v[200:203], v[16:19]
	v_mfma_f32_16x16x32_bf16 v[8:11], v[176:179], v[200:203], v[8:11]
	v_mfma_f32_16x16x32_bf16 v[4:7], v[168:171], v[208:211], v[4:7]
	v_mfma_f32_16x16x32_bf16 v[0:3], v[176:179], v[208:211], v[0:3]
	s_barrier
	s_setprio 0
	s_add_i32 s61, s61, 2
	s_add_u32 s59, s59, 0x100
	s_addc_u32 s60, s60, 0
	s_cmpk_gt_u32 s61, 0x7d
	s_mov_b64 s[30:31], s[34:35]
.LBB0_847:
	ds_read_b128 v[72:75], v165
	ds_read_b128 v[84:87], v165 offset:1024
	ds_read_b128 v[92:95], v165 offset:2048
	ds_read_b128 v[108:111], v165 offset:3072
	ds_read_b128 v[156:159], v166
	ds_read_b128 v[168:171], v166 offset:1024
	ds_read_b128 v[172:175], v166 offset:2048
	ds_read_b128 v[176:179], v166 offset:3072
	s_add_u32 s34, s30, 0x100
	s_addc_u32 s35, s31, 0
	s_cmpk_eq_i32 s61, 0x7c
	s_cselect_b32 s39, s23, s35
	s_cselect_b32 s38, s57, s34
	s_cselect_b32 s37, s21, s60
	s_cselect_b32 s36, s58, s59
	v_lshl_add_u64 v[160:161], s[30:31], 0, v[148:149]
	s_add_i32 m0, s42, 0xc000
	ds_read_b128 v[180:183], v167
	ds_read_b128 v[184:187], v167 offset:1024
	ds_read_b128 v[188:191], v167 offset:2048
	ds_read_b128 v[192:195], v167 offset:3072
	ds_read_b128 v[196:199], v167 offset:4096
	ds_read_b128 v[200:203], v167 offset:5120
	ds_read_b128 v[204:207], v167 offset:6144
	ds_read_b128 v[208:211], v167 offset:7168
	global_load_lds_dwordx4 v[160:161], off
	v_lshl_add_u64 v[160:161], s[30:31], 0, v[150:151]
	s_add_i32 m0, s42, 0xe000
	s_nop 0
	global_load_lds_dwordx4 v[160:161], off
	s_waitcnt vmcnt(8) lgkmcnt(0)
	s_setprio 1
	s_barrier
; #define PG8_STAGE(bufoff, gbase, voff) do { _Pragma("unroll") for (int _i = 0; _i < 2; ++_i) \
;         __builtin_amdgcn_global_load_lds((const unsigned*)((const char*)(gbase) + (voff)[_i]), (PG8_LAS unsigned*)(lds + (bufoff) + ldsw + _i * 8192), 16, 0, 0); } while (0)
; #define PG8_LDA(dst, b, h) do { _Pragma("unroll") for (int m = 0; m < 4; ++m) _Pragma("unroll") for (int k = 0; k < 2; ++k) dst[m][k] = *(const PG8_LAS bf16x8*)(lds + PG8_SA(b, h) + aoff + m * 2048 + k * 1024); } while (0)
; #define PG8_LDB(dst, b, h) do { _Pragma("unroll") for (int n = 0; n < 2; ++n) _Pragma("unroll") for (int k = 0; k < 2; ++k) dst[n][k] = *(const PG8_LAS bf16x8*)(lds + PG8_SB(b, h) + boff + n * 2048 + k * 1024); } while (0)
; #define PG8_MMA(ai, bj, At, Bt) do { __builtin_amdgcn_s_setprio(1); _Pragma("unroll") for (int m = 0; m < 4; ++m) _Pragma("unroll") for (int n = 0; n < 2; ++n) _Pragma("unroll") for (int k = 0; k < 2; ++k) \
;         acc[ai][bj][m][n] = __builtin_amdgcn_mfma_f32_16x16x32_bf16(Bt[n][k], At[m][k], acc[ai][bj][m][n], 0, 0, 0); __builtin_amdgcn_s_setprio(0); } while (0)
; #define PG8_WAIT_V(n) asm volatile("s_waitcnt vmcnt(" #n ")" ::: "memory")
; #define PG8_WAIT_L(n) asm volatile("s_waitcnt lgkmcnt(" #n ")" ::: "memory")
; #define PG8_BAR __builtin_amdgcn_s_barrier()
; #define PG8_SCHED __builtin_amdgcn_sched_barrier(0)
; template <class Epi, class Sched, bool ALIGN_EPI = false, bool SP2 = false>
; __device__ __forceinline__ void gemm_phase(PG8_LAS unsigned char* lds, const Gemm g, const Sched& S, const Epi& E) {
;     ...
;             PG8_LDB(B0, 0, 0); PG8_LDB(B1, 0, 1); PG8_SCHED; PG8_LDA(At, 0, 0); PG8_STAGE(PG8_SA(1, 1), a1 + hstep, voffA);
;             PG8_WAIT_V(8); PG8_WAIT_L(0); PG8_BAR; PG8_MMA(0, 0, At, B0); PG8_MMA(0, 1, At, B1); PG8_BAR; PG8_SCHED;
;             PG8_LDA(At, 0, 1); PG8_STAGE(PG8_SB(0, 0), b2, voffB); PG8_STAGE(PG8_SB(0, 1), b2 + hstep, voffB); PG8_STAGE(PG8_SA(0, 0), a2, voffA);
;             PG8_WAIT_V(8); PG8_WAIT_L(0); PG8_BAR; PG8_MMA(1, 0, At, B0); PG8_MMA(1, 1, At, B1); PG8_BAR; PG8_SCHED;
	v_mfma_f32_16x16x32_bf16 v[140:143], v[72:75], v[180:183], v[140:143]
	v_mfma_f32_16x16x32_bf16 v[136:139], v[92:95], v[180:183], v[136:139]
	v_mfma_f32_16x16x32_bf16 v[132:135], v[72:75], v[188:191], v[132:135]
	v_mfma_f32_16x16x32_bf16 v[128:131], v[92:95], v[188:191], v[128:131]
	v_mfma_f32_16x16x32_bf16 v[120:123], v[72:75], v[196:199], v[120:123]
	v_mfma_f32_16x16x32_bf16 v[112:115], v[92:95], v[196:199], v[112:115]
	v_mfma_f32_16x16x32_bf16 v[100:103], v[72:75], v[204:207], v[100:103]
	v_mfma_f32_16x16x32_bf16 v[88:91], v[92:95], v[204:207], v[88:91]
	v_mfma_f32_16x16x32_bf16 v[140:143], v[84:87], v[184:187], v[140:143]
	v_mfma_f32_16x16x32_bf16 v[136:139], v[108:111], v[184:187], v[136:139]
	v_mfma_f32_16x16x32_bf16 v[132:135], v[84:87], v[192:195], v[132:135]
	v_mfma_f32_16x16x32_bf16 v[128:131], v[108:111], v[192:195], v[128:131]
	v_mfma_f32_16x16x32_bf16 v[120:123], v[84:87], v[200:203], v[120:123]
	v_mfma_f32_16x16x32_bf16 v[112:115], v[108:111], v[200:203], v[112:115]
	v_mfma_f32_16x16x32_bf16 v[100:103], v[84:87], v[208:211], v[100:103]
	v_mfma_f32_16x16x32_bf16 v[88:91], v[108:111], v[208:211], v[88:91]
	v_mfma_f32_16x16x32_bf16 v[124:127], v[156:159], v[180:183], v[124:127]
	v_mfma_f32_16x16x32_bf16 v[116:119], v[172:175], v[180:183], v[116:119]
	v_mfma_f32_16x16x32_bf16 v[104:107], v[156:159], v[188:191], v[104:107]
	v_mfma_f32_16x16x32_bf16 v[96:99], v[172:175], v[188:191], v[96:99]
	v_mfma_f32_16x16x32_bf16 v[80:83], v[156:159], v[196:199], v[80:83]
	v_mfma_f32_16x16x32_bf16 v[76:79], v[172:175], v[196:199], v[76:79]
	v_mfma_f32_16x16x32_bf16 v[68:71], v[156:159], v[204:207], v[68:71]
	v_mfma_f32_16x16x32_bf16 v[64:67], v[172:175], v[204:207], v[64:67]
	v_mfma_f32_16x16x32_bf16 v[124:127], v[168:171], v[184:187], v[124:127]
	v_mfma_f32_16x16x32_bf16 v[116:119], v[176:179], v[184:187], v[116:119]
	v_mfma_f32_16x16x32_bf16 v[104:107], v[168:171], v[192:195], v[104:107]
	v_mfma_f32_16x16x32_bf16 v[96:99], v[176:179], v[192:195], v[96:99]
	v_mfma_f32_16x16x32_bf16 v[80:83], v[168:171], v[200:203], v[80:83]
	v_mfma_f32_16x16x32_bf16 v[76:79], v[176:179], v[200:203], v[76:79]
	v_mfma_f32_16x16x32_bf16 v[68:71], v[168:171], v[208:211], v[68:71]
	v_mfma_f32_16x16x32_bf16 v[64:67], v[176:179], v[208:211], v[64:67]
	s_barrier
	s_setprio 0
	s_add_i32 s30, s55, s47
	v_lshl_add_u64 v[160:161], s[36:37], 0, v[146:147]
	s_mov_b32 m0, s30
	ds_read_b128 v[180:183], v167 offset:16384
	ds_read_b128 v[184:187], v167 offset:17408
	ds_read_b128 v[188:191], v167 offset:18432
	ds_read_b128 v[192:195], v167 offset:19456
	ds_read_b128 v[196:199], v167 offset:20480
	ds_read_b128 v[200:203], v167 offset:21504
	ds_read_b128 v[204:207], v167 offset:22528
	ds_read_b128 v[208:211], v167 offset:23552
	global_load_lds_dwordx4 v[160:161], off
	s_add_i32 m0, s30, 0x2000
	s_add_u32 s30, s36, 0x200000
	v_lshl_add_u64 v[212:213], s[36:37], 0, v[144:145]
	s_addc_u32 s31, s37, 0
	s_add_i32 s62, s56, s47
	global_load_lds_dwordx4 v[212:213], off
	v_lshl_add_u64 v[214:215], s[30:31], 0, v[146:147]
	s_mov_b32 m0, s62
	v_lshl_add_u64 v[216:217], s[38:39], 0, v[144:145]
	global_load_lds_dwordx4 v[214:215], off
	v_lshl_add_u64 v[214:215], s[30:31], 0, v[144:145]
	s_add_i32 m0, s62, 0x2000
	s_nop 0
	global_load_lds_dwordx4 v[214:215], off
	v_lshl_add_u64 v[214:215], s[38:39], 0, v[146:147]
	s_mov_b32 m0, s42
	s_nop 0
	global_load_lds_dwordx4 v[214:215], off
	s_mov_b32 m0, s43
	s_nop 0
	global_load_lds_dwordx4 v[216:217], off
	s_waitcnt vmcnt(8) lgkmcnt(0)
	s_setprio 1
	s_barrier
	v_mfma_f32_16x16x32_bf16 v[60:63], v[72:75], v[180:183], v[60:63]
	v_mfma_f32_16x16x32_bf16 v[56:59], v[92:95], v[180:183], v[56:59]
	v_mfma_f32_16x16x32_bf16 v[52:55], v[72:75], v[188:191], v[52:55]
	v_mfma_f32_16x16x32_bf16 v[44:47], v[92:95], v[188:191], v[44:47]
	v_mfma_f32_16x16x32_bf16 v[36:39], v[72:75], v[196:199], v[36:39]
	v_mfma_f32_16x16x32_bf16 v[28:31], v[92:95], v[196:199], v[28:31]
	v_mfma_f32_16x16x32_bf16 v[20:23], v[72:75], v[204:207], v[20:23]
	v_mfma_f32_16x16x32_bf16 v[12:15], v[92:95], v[204:207], v[12:15]
	v_mfma_f32_16x16x32_bf16 v[60:63], v[84:87], v[184:187], v[60:63]
	v_mfma_f32_16x16x32_bf16 v[56:59], v[108:111], v[184:187], v[56:59]
	v_mfma_f32_16x16x32_bf16 v[52:55], v[84:87], v[192:195], v[52:55]
	v_mfma_f32_16x16x32_bf16 v[44:47], v[108:111], v[192:195], v[44:47]
	v_mfma_f32_16x16x32_bf16 v[36:39], v[84:87], v[200:203], v[36:39]
	v_mfma_f32_16x16x32_bf16 v[28:31], v[108:111], v[200:203], v[28:31]
	v_mfma_f32_16x16x32_bf16 v[20:23], v[84:87], v[208:211], v[20:23]
	v_mfma_f32_16x16x32_bf16 v[12:15], v[108:111], v[208:211], v[12:15]
	v_mfma_f32_16x16x32_bf16 v[48:51], v[156:159], v[180:183], v[48:51]
	v_mfma_f32_16x16x32_bf16 v[40:43], v[172:175], v[180:183], v[40:43]
	v_mfma_f32_16x16x32_bf16 v[32:35], v[156:159], v[188:191], v[32:35]
	v_mfma_f32_16x16x32_bf16 v[24:27], v[172:175], v[188:191], v[24:27]
	v_mfma_f32_16x16x32_bf16 v[16:19], v[156:159], v[196:199], v[16:19]
	v_mfma_f32_16x16x32_bf16 v[8:11], v[172:175], v[196:199], v[8:11]
	v_mfma_f32_16x16x32_bf16 v[4:7], v[156:159], v[204:207], v[4:7]
	v_mfma_f32_16x16x32_bf16 v[0:3], v[172:175], v[204:207], v[0:3]
	v_mfma_f32_16x16x32_bf16 v[48:51], v[168:171], v[184:187], v[48:51]
	v_mfma_f32_16x16x32_bf16 v[40:43], v[176:179], v[184:187], v[40:43]
	v_mfma_f32_16x16x32_bf16 v[32:35], v[168:171], v[192:195], v[32:35]
	v_mfma_f32_16x16x32_bf16 v[24:27], v[176:179], v[192:195], v[24:27]
	v_mfma_f32_16x16x32_bf16 v[16:19], v[168:171], v[200:203], v[16:19]
	v_mfma_f32_16x16x32_bf16 v[8:11], v[176:179], v[200:203], v[8:11]
	v_mfma_f32_16x16x32_bf16 v[4:7], v[168:171], v[208:211], v[4:7]
	v_mfma_f32_16x16x32_bf16 v[0:3], v[176:179], v[208:211], v[0:3]
	s_barrier
; #define PG8_STAGE(bufoff, gbase, voff) do { _Pragma("unroll") for (int _i = 0; _i < 2; ++_i) \
;         __builtin_amdgcn_global_load_lds((const unsigned*)((const char*)(gbase) + (voff)[_i]), (PG8_LAS unsigned*)(lds + (bufoff) + ldsw + _i * 8192), 16, 0, 0); } while (0)
; #define PG8_LDA(dst, b, h) do { _Pragma("unroll") for (int m = 0; m < 4; ++m) _Pragma("unroll") for (int k = 0; k < 2; ++k) dst[m][k] = *(const PG8_LAS bf16x8*)(lds + PG8_SA(b, h) + aoff + m * 2048 + k * 1024); } while (0)
; #define PG8_LDB(dst, b, h) do { _Pragma("unroll") for (int n = 0; n < 2; ++n) _Pragma("unroll") for (int k = 0; k < 2; ++k) dst[n][k] = *(const PG8_LAS bf16x8*)(lds + PG8_SB(b, h) + boff + n * 2048 + k * 1024); } while (0)
; #define PG8_MMA(ai, bj, At, Bt) do { __builtin_amdgcn_s_setprio(1); _Pragma("unroll") for (int m = 0; m < 4; ++m) _Pragma("unroll") for (int n = 0; n < 2; ++n) _Pragma("unroll") for (int k = 0; k < 2; ++k) \
;         acc[ai][bj][m][n] = __builtin_amdgcn_mfma_f32_16x16x32_bf16(Bt[n][k], At[m][k], acc[ai][bj][m][n], 0, 0, 0); __builtin_amdgcn_s_setprio(0); } while (0)
; #define PG8_WAIT_V(n) asm volatile("s_waitcnt vmcnt(" #n ")" ::: "memory")
; #define PG8_WAIT_L(n) asm volatile("s_waitcnt lgkmcnt(" #n ")" ::: "memory")
; #define PG8_BAR __builtin_amdgcn_s_barrier()
; #define PG8_SCHED __builtin_amdgcn_sched_barrier(0)
; template <class Epi, class Sched, bool ALIGN_EPI = false, bool SP2 = false>
; __device__ __forceinline__ void gemm_phase(PG8_LAS unsigned char* lds, const Gemm g, const Sched& S, const Epi& E) {
;     ...
;             PG8_LDB(B0, 1, 0); PG8_LDB(B1, 1, 1); PG8_SCHED; PG8_LDA(At, 1, 0); PG8_STAGE(PG8_SA(0, 1), a2 + hstep, voffA);
;             PG8_WAIT_V(8); PG8_WAIT_L(0); PG8_BAR; PG8_MMA(0, 0, At, B0); PG8_MMA(0, 1, At, B1); PG8_BAR; PG8_SCHED;
	s_setprio 0
	s_add_i32 s62, 0, 0x18000
	s_add_i32 s63, 0, 0x1c000
	v_add_u32_e32 v108, s62, v163
	v_add_u32_e32 v176, s63, v163
	ds_read_b128 v[72:75], v108
	ds_read_b128 v[84:87], v108 offset:1024
	ds_read_b128 v[92:95], v108 offset:2048
	ds_read_b128 v[108:111], v108 offset:3072
	ds_read_b128 v[156:159], v176
	ds_read_b128 v[168:171], v176 offset:1024
	ds_read_b128 v[172:175], v176 offset:2048
	ds_read_b128 v[176:179], v176 offset:3072
	s_add_u32 s30, s38, 0x200000
	s_addc_u32 s31, s39, 0
	s_mov_b32 m0, s48
	v_lshl_add_u64 v[218:219], s[30:31], 0, v[146:147]
	ds_read_b128 v[180:183], v167 offset:32768
	ds_read_b128 v[184:187], v167 offset:33792
	ds_read_b128 v[188:191], v167 offset:34816
	ds_read_b128 v[192:195], v167 offset:35840
	ds_read_b128 v[196:199], v167 offset:36864
	ds_read_b128 v[200:203], v167 offset:37888
	ds_read_b128 v[204:207], v167 offset:38912
	ds_read_b128 v[208:211], v167 offset:39936
	global_load_lds_dwordx4 v[218:219], off
	v_lshl_add_u64 v[218:219], s[30:31], 0, v[144:145]
	s_mov_b32 m0, s49
	s_nop 0
	global_load_lds_dwordx4 v[218:219], off
	s_waitcnt vmcnt(8) lgkmcnt(0)
	s_setprio 1
	s_barrier
	v_mfma_f32_16x16x32_bf16 v[140:143], v[72:75], v[180:183], v[140:143]
	v_mfma_f32_16x16x32_bf16 v[136:139], v[92:95], v[180:183], v[136:139]
	v_mfma_f32_16x16x32_bf16 v[132:135], v[72:75], v[188:191], v[132:135]
	v_mfma_f32_16x16x32_bf16 v[128:131], v[92:95], v[188:191], v[128:131]
	v_mfma_f32_16x16x32_bf16 v[120:123], v[72:75], v[196:199], v[120:123]
	v_mfma_f32_16x16x32_bf16 v[112:115], v[92:95], v[196:199], v[112:115]
	v_mfma_f32_16x16x32_bf16 v[100:103], v[72:75], v[204:207], v[100:103]
	v_mfma_f32_16x16x32_bf16 v[88:91], v[92:95], v[204:207], v[88:91]
	v_mfma_f32_16x16x32_bf16 v[140:143], v[84:87], v[184:187], v[140:143]
	v_mfma_f32_16x16x32_bf16 v[136:139], v[108:111], v[184:187], v[136:139]
	v_mfma_f32_16x16x32_bf16 v[132:135], v[84:87], v[192:195], v[132:135]
	v_mfma_f32_16x16x32_bf16 v[128:131], v[108:111], v[192:195], v[128:131]
	v_mfma_f32_16x16x32_bf16 v[120:123], v[84:87], v[200:203], v[120:123]
	v_mfma_f32_16x16x32_bf16 v[112:115], v[108:111], v[200:203], v[112:115]
	v_mfma_f32_16x16x32_bf16 v[100:103], v[84:87], v[208:211], v[100:103]
	v_mfma_f32_16x16x32_bf16 v[88:91], v[108:111], v[208:211], v[88:91]
	v_mfma_f32_16x16x32_bf16 v[124:127], v[156:159], v[180:183], v[124:127]
	v_mfma_f32_16x16x32_bf16 v[116:119], v[172:175], v[180:183], v[116:119]
	v_mfma_f32_16x16x32_bf16 v[104:107], v[156:159], v[188:191], v[104:107]
	v_mfma_f32_16x16x32_bf16 v[96:99], v[172:175], v[188:191], v[96:99]
	v_mfma_f32_16x16x32_bf16 v[80:83], v[156:159], v[196:199], v[80:83]
	v_mfma_f32_16x16x32_bf16 v[76:79], v[172:175], v[196:199], v[76:79]
	v_mfma_f32_16x16x32_bf16 v[68:71], v[156:159], v[204:207], v[68:71]
	v_mfma_f32_16x16x32_bf16 v[64:67], v[172:175], v[204:207], v[64:67]
	v_mfma_f32_16x16x32_bf16 v[124:127], v[168:171], v[184:187], v[124:127]
	v_mfma_f32_16x16x32_bf16 v[116:119], v[176:179], v[184:187], v[116:119]
	v_mfma_f32_16x16x32_bf16 v[104:107], v[168:171], v[192:195], v[104:107]
	v_mfma_f32_16x16x32_bf16 v[96:99], v[176:179], v[192:195], v[96:99]
	v_mfma_f32_16x16x32_bf16 v[80:83], v[168:171], v[200:203], v[80:83]
	v_mfma_f32_16x16x32_bf16 v[76:79], v[176:179], v[200:203], v[76:79]
	v_mfma_f32_16x16x32_bf16 v[68:71], v[168:171], v[208:211], v[68:71]
	v_mfma_f32_16x16x32_bf16 v[64:67], v[176:179], v[208:211], v[64:67]
	s_barrier
; #define PG8_STAGE(bufoff, gbase, voff) do { _Pragma("unroll") for (int _i = 0; _i < 2; ++_i) \
;         __builtin_amdgcn_global_load_lds((const unsigned*)((const char*)(gbase) + (voff)[_i]), (PG8_LAS unsigned*)(lds + (bufoff) + ldsw + _i * 8192), 16, 0, 0); } while (0)
; #define PG8_LDA(dst, b, h) do { _Pragma("unroll") for (int m = 0; m < 4; ++m) _Pragma("unroll") for (int k = 0; k < 2; ++k) dst[m][k] = *(const PG8_LAS bf16x8*)(lds + PG8_SA(b, h) + aoff + m * 2048 + k * 1024); } while (0)
; #define PG8_LDB(dst, b, h) do { _Pragma("unroll") for (int n = 0; n < 2; ++n) _Pragma("unroll") for (int k = 0; k < 2; ++k) dst[n][k] = *(const PG8_LAS bf16x8*)(lds + PG8_SB(b, h) + boff + n * 2048 + k * 1024); } while (0)
; #define PG8_MMA(ai, bj, At, Bt) do { __builtin_amdgcn_s_setprio(1); _Pragma("unroll") for (int m = 0; m < 4; ++m) _Pragma("unroll") for (int n = 0; n < 2; ++n) _Pragma("unroll") for (int k = 0; k < 2; ++k) \
;         acc[ai][bj][m][n] = __builtin_amdgcn_mfma_f32_16x16x32_bf16(Bt[n][k], At[m][k], acc[ai][bj][m][n], 0, 0, 0); __builtin_amdgcn_s_setprio(0); } while (0)
; #define PG8_WAIT_V(n) asm volatile("s_waitcnt vmcnt(" #n ")" ::: "memory")
; #define PG8_WAIT_L(n) asm volatile("s_waitcnt lgkmcnt(" #n ")" ::: "memory")
; #define PG8_BAR __builtin_amdgcn_s_barrier()
; #define PG8_SCHED __builtin_amdgcn_sched_barrier(0)
; template <class Epi, class Sched, bool ALIGN_EPI = false, bool SP2 = false>
; __device__ __forceinline__ void gemm_phase(PG8_LAS unsigned char* lds, const Gemm g, const Sched& S, const Epi& E) {
;     ...
;             PG8_LDB(B0, 1, 0); PG8_LDB(B1, 1, 1); PG8_SCHED; PG8_LDA(At, 1, 0); PG8_STAGE(PG8_SA(0, 1), a2 + hstep, voffA);
;             PG8_WAIT_V(8); PG8_WAIT_L(0); PG8_BAR; PG8_MMA(0, 0, At, B0); PG8_MMA(0, 1, At, B1); PG8_BAR; PG8_SCHED;
;             PG8_LDA(At, 1, 1); PG8_STAGE(PG8_SB(1, 0), b3, voffB); PG8_STAGE(PG8_SB(1, 1), b3 + hstep, voffB); PG8_STAGE(PG8_SA(1, 0), a3, voffA);
;             PG8_WAIT_V(8); PG8_WAIT_L(0); PG8_BAR; PG8_MMA(1, 0, At, B0); PG8_MMA(1, 1, At, B1); PG8_BAR; PG8_SCHED;
;     ...
;         if constexpr (ALIGN_EPI) { if (wr == 0) PG8_BAR; }
	s_setprio 0
	s_add_i32 s30, s62, s47
	v_lshl_add_u64 v[160:161], v[160:161], 0, s[8:9]
	s_mov_b32 m0, s30
	ds_read_b128 v[180:183], v167 offset:49152
	ds_read_b128 v[184:187], v167 offset:50176
	ds_read_b128 v[188:191], v167 offset:51200
	ds_read_b128 v[192:195], v167 offset:52224
	ds_read_b128 v[196:199], v167 offset:53248
	ds_read_b128 v[200:203], v167 offset:54272
	ds_read_b128 v[204:207], v167 offset:55296
	ds_read_b128 v[208:211], v167 offset:56320
	global_load_lds_dwordx4 v[160:161], off
	s_add_i32 m0, s30, 0x2000
	s_add_u32 s30, s36, 0x200080
	v_lshl_add_u64 v[160:161], v[212:213], 0, s[8:9]
	s_addc_u32 s31, s37, 0
	s_add_i32 s36, s63, s47
	global_load_lds_dwordx4 v[160:161], off
	v_lshl_add_u64 v[160:161], s[30:31], 0, v[146:147]
	s_mov_b32 m0, s36
	s_nop 0
	global_load_lds_dwordx4 v[160:161], off
	v_lshl_add_u64 v[160:161], s[30:31], 0, v[144:145]
	s_add_i32 m0, s36, 0x2000
	s_nop 0
	global_load_lds_dwordx4 v[160:161], off
	v_lshl_add_u64 v[160:161], v[214:215], 0, s[8:9]
	s_mov_b32 m0, s53
	s_nop 0
	global_load_lds_dwordx4 v[160:161], off
	v_lshl_add_u64 v[160:161], v[216:217], 0, s[8:9]
	s_mov_b32 m0, s54
	s_nop 0
	global_load_lds_dwordx4 v[160:161], off
	s_waitcnt vmcnt(8) lgkmcnt(0)
	s_setprio 1
	s_barrier
	v_mfma_f32_16x16x32_bf16 v[60:63], v[72:75], v[180:183], v[60:63]
	v_mfma_f32_16x16x32_bf16 v[56:59], v[92:95], v[180:183], v[56:59]
	v_mfma_f32_16x16x32_bf16 v[52:55], v[72:75], v[188:191], v[52:55]
	v_mfma_f32_16x16x32_bf16 v[44:47], v[92:95], v[188:191], v[44:47]
	v_mfma_f32_16x16x32_bf16 v[36:39], v[72:75], v[196:199], v[36:39]
	v_mfma_f32_16x16x32_bf16 v[28:31], v[92:95], v[196:199], v[28:31]
	v_mfma_f32_16x16x32_bf16 v[20:23], v[72:75], v[204:207], v[20:23]
	v_mfma_f32_16x16x32_bf16 v[12:15], v[92:95], v[204:207], v[12:15]
	v_mfma_f32_16x16x32_bf16 v[60:63], v[84:87], v[184:187], v[60:63]
	v_mfma_f32_16x16x32_bf16 v[56:59], v[108:111], v[184:187], v[56:59]
	v_mfma_f32_16x16x32_bf16 v[52:55], v[84:87], v[192:195], v[52:55]
	v_mfma_f32_16x16x32_bf16 v[44:47], v[108:111], v[192:195], v[44:47]
	v_mfma_f32_16x16x32_bf16 v[36:39], v[84:87], v[200:203], v[36:39]
	v_mfma_f32_16x16x32_bf16 v[28:31], v[108:111], v[200:203], v[28:31]
	v_mfma_f32_16x16x32_bf16 v[20:23], v[84:87], v[208:211], v[20:23]
	v_mfma_f32_16x16x32_bf16 v[12:15], v[108:111], v[208:211], v[12:15]
	v_mfma_f32_16x16x32_bf16 v[48:51], v[156:159], v[180:183], v[48:51]
	v_mfma_f32_16x16x32_bf16 v[40:43], v[172:175], v[180:183], v[40:43]
	v_mfma_f32_16x16x32_bf16 v[32:35], v[156:159], v[188:191], v[32:35]
	v_mfma_f32_16x16x32_bf16 v[24:27], v[172:175], v[188:191], v[24:27]
	v_mfma_f32_16x16x32_bf16 v[16:19], v[156:159], v[196:199], v[16:19]
	v_mfma_f32_16x16x32_bf16 v[8:11], v[172:175], v[196:199], v[8:11]
	v_mfma_f32_16x16x32_bf16 v[4:7], v[156:159], v[204:207], v[4:7]
	v_mfma_f32_16x16x32_bf16 v[0:3], v[172:175], v[204:207], v[0:3]
	v_mfma_f32_16x16x32_bf16 v[48:51], v[168:171], v[184:187], v[48:51]
	v_mfma_f32_16x16x32_bf16 v[40:43], v[176:179], v[184:187], v[40:43]
	v_mfma_f32_16x16x32_bf16 v[32:35], v[168:171], v[192:195], v[32:35]
	v_mfma_f32_16x16x32_bf16 v[24:27], v[176:179], v[192:195], v[24:27]
	v_mfma_f32_16x16x32_bf16 v[16:19], v[168:171], v[200:203], v[16:19]
	v_mfma_f32_16x16x32_bf16 v[8:11], v[176:179], v[200:203], v[8:11]
	v_mfma_f32_16x16x32_bf16 v[4:7], v[168:171], v[208:211], v[4:7]
	v_mfma_f32_16x16x32_bf16 v[0:3], v[176:179], v[208:211], v[0:3]
	s_barrier
	s_setprio 0
	s_add_i32 s61, s61, 2
	s_add_u32 s59, s59, 0x100
	s_addc_u32 s60, s60, 0
	s_cmpk_gt_u32 s61, 0x7d
	s_mov_b64 s[30:31], s[34:35]
	s_cbranch_scc0 .LBB0_847
	s_and_b64 vcc, exec, s[10:11]
	s_cbranch_vccz .LBB0_850
	s_barrier
